# speedup vs baseline: 1.0133x; 1.0031x over previous
; #define STAGE(P, BASE, br, kt) do { const char* _gb = (const char*)((BASE) + ((long)(br) * K + (long)(kt) * BK)); \
;     __builtin_amdgcn_global_load_lds((const unsigned*)(_gb + (size_t)so0), (unsigned*)((char*)(P) + wv1k), 16, 0, 0); \
;     __builtin_amdgcn_global_load_lds((const unsigned*)(_gb + (size_t)so1), (unsigned*)((char*)(P) + wv1k + 8192), 16, 0, 0); } while (0)
; #define WAIT_V(n) asm volatile("s_waitcnt vmcnt(" #n ")" ::: "memory")
; #define BAR __builtin_amdgcn_s_barrier()
; template <class Epi> ...
;     ...
;   const int wid = cx.tid >> 6, lane = cx.tid & 63, wr = wid >> 2, wc = wid & 3, fr = lane & 15, fq = lane >> 4;
;   const int wv1k = __builtin_amdgcn_readfirstlane(cx.tid >> 6) * 1024;
;   unsigned so0, so1;
;   { int r, c; stage_rc(cx.tid * 16, r, c); so0 = (unsigned)(r * K + c) * 2u; stage_rc(cx.tid * 16 + 8192, r, c); so1 = (unsigned)(r * K + c) * 2u; }
;   if (zinit) {
;     _Pragma("unroll") for (int ai = 0; ai < 2; ++ai) _Pragma("unroll") for (int bj = 0; bj < 2; ++bj) _Pragma("unroll") for (int m = 0; m < 4; ++m) _Pragma("unroll") for (int n = 0; n < 2; ++n) acc[ai][bj][m][n] = f32x4{0.f, 0.f, 0.f, 0.f};
;   }
;   bf16x8 At[4][2], B0[2][2], B1[2][2];
;   const int nt = K / BK;
;   if (!(OVERLAP && pre)) {
;     STAGE(SB(0, 0), Bt, bcol, 0); STAGE(SA(0, 0), A, brow, 0);
;     STAGE(SB(0, 1), Bt, bcol + HALF, 0); STAGE(SA(0, 1), A, brow + HALF, 0);
;   }
;   if (wr == 1) BAR;
;   if (OVERLAP && pre) WAIT_V(0); else WAIT_V(4);
;   BAR;
; DEVINL bool run_phase(int ph, int rep) {
;     ...
;       for (int t = cx.bid; t < nwg; t += cx.nb) {
;         int pm, pn; tile_coords(t, nM, nN, pm, pn);
;         const int grow = pm * BM;
;         const float* res = fx ? x_row(p, grow) - (size_t)grow * DM : p.out;
;         EpiRes e{res, p.out, p.mod + (size_t)seq_of_row(grow) * (2 * MODW) + l * MODW + (f2 ? 8 : 2) * DM, 0.5f};
;         Acc acc; e.init(acc, grow, pn * BM);
;         gemm_tile_acc(acc, false, cx, p.act, W, DFF, grow, pn * BM, e, false, nullptr, nullptr, 0, -1, 0);
.LBB0_74:
	v_readfirstlane_b32 s100, v234
	s_nop 3
	s_lshr_b32 s100, s100, 6
	s_cmp_ge_u32 s100, 4
	s_cbranch_scc0 .Lprio_74_done
	s_setprio 1

; #define STAGE(P, BASE, br, kt) do { const char* _gb = (const char*)((BASE) + ((long)(br) * K + (long)(kt) * BK)); \
;     __builtin_amdgcn_global_load_lds((const unsigned*)(_gb + (size_t)so0), (unsigned*)((char*)(P) + wv1k), 16, 0, 0); \
;     __builtin_amdgcn_global_load_lds((const unsigned*)(_gb + (size_t)so1), (unsigned*)((char*)(P) + wv1k + 8192), 16, 0, 0); } while (0)
; #define LDA(dst, b, h) _Pragma("unroll") for (int m = 0; m < 4; ++m) _Pragma("unroll") for (int k = 0; k < 2; ++k) \
;     dst[m][k] = *reinterpret_cast<const bf16x8*>((char*)SA(b, h) + lds_byte(wr * 64 + m * 16 + fr, k * 32 + fq * 8))
; #define LDB(dst, b, h) _Pragma("unroll") for (int n = 0; n < 2; ++n) _Pragma("unroll") for (int k = 0; k < 2; ++k) \
;     dst[n][k] = *reinterpret_cast<const bf16x8*>((char*)SB(b, h) + lds_byte(wc * 32 + n * 16 + fr, k * 32 + fq * 8))
; #define MMA(ai, bj, At_, Bt_) do { __builtin_amdgcn_s_setprio(1); \
;     _Pragma("unroll") for (int m = 0; m < 4; ++m) _Pragma("unroll") for (int n = 0; n < 2; ++n) _Pragma("unroll") for (int k = 0; k < 2; ++k) \
;       acc[ai][bj][m][n] = __builtin_amdgcn_mfma_f32_16x16x32_bf16(At_[m][k], Bt_[n][k], acc[ai][bj][m][n], 0, 0, 0); \
;     __builtin_amdgcn_s_setprio(0); } while (0)
; #define WAIT_V(n) asm volatile("s_waitcnt vmcnt(" #n ")" ::: "memory")
; #define WAIT_L(n) asm volatile("s_waitcnt lgkmcnt(" #n ")" ::: "memory")
; #define BAR __builtin_amdgcn_s_barrier()
; #define SCHED __builtin_amdgcn_sched_barrier(0)
; template <class Epi> ...
;     ...
;   for (int t = 0; t < nt - 2; t += 2) {
;     LDB(B0, 0, 0); SCHED; LDA(At, 0, 0); STAGE(SA(1, 1), A, brow + HALF, t + 1);
;     WAIT_L(8); BAR; WAIT_L(0); MMA(0, 0, At, B0); BAR; SCHED;
;     LDB(B1, 0, 1); STAGE(SB(0, 0), Bt, bcol, t + 2);
;     BAR; WAIT_L(0); MMA(0, 1, At, B1); BAR;
;     LDA(At, 0, 1); STAGE(SA(0, 0), A, brow, t + 2);
;     BAR; WAIT_L(0); MMA(1, 0, At, B0); BAR; SCHED;
;     STAGE(SB(0, 1), Bt, bcol + HALF, t + 2);
;     WAIT_V(6); BAR; MMA(1, 1, At, B1); BAR;
.LBB0_82:
	ds_read_b128 v[106:109], v235
	ds_read_b128 v[110:113], v235 offset:1024
	ds_read_b128 v[162:165], v235 offset:2048
	ds_read_b128 v[166:169], v235 offset:3072
	v_lshl_add_u64 v[210:211], v[96:97], 0, s[24:25]
	s_add_i32 s28, s42, 0xc000
	v_lshl_add_u64 v[202:203], v[210:211], 0, s[54:55]
	s_mov_b32 m0, s28
	v_lshl_add_u64 v[212:213], v[90:91], 0, s[24:25]
	s_add_i32 s27, s42, 0xe000
	ds_read_b128 v[170:173], v236
	ds_read_b128 v[174:177], v236 offset:1024
	ds_read_b128 v[178:181], v237
	ds_read_b128 v[182:185], v237 offset:1024
	ds_read_b128 v[186:189], v238
	ds_read_b128 v[190:193], v238 offset:1024
	ds_read_b128 v[194:197], v239
	ds_read_b128 v[198:201], v239 offset:1024
	global_load_lds_dwordx4 v[202:203], off
	v_lshl_add_u64 v[202:203], v[212:213], 0, s[54:55]
	s_mov_b32 m0, s27
	s_nop 0
	global_load_lds_dwordx4 v[202:203], off
	s_waitcnt lgkmcnt(8)
	s_barrier
	s_waitcnt lgkmcnt(0)
	s_waitcnt lgkmcnt(0)
	v_mfma_f32_16x16x32_bf16 v[2:5], v[170:173], v[106:109], v[2:5]
	v_mfma_f32_16x16x32_bf16 v[10:13], v[170:173], v[162:165], v[10:13]
	v_mfma_f32_16x16x32_bf16 v[22:25], v[178:181], v[106:109], v[22:25]
	v_mfma_f32_16x16x32_bf16 v[30:33], v[178:181], v[162:165], v[30:33]
	v_mfma_f32_16x16x32_bf16 v[62:65], v[186:189], v[106:109], v[62:65]
	v_mfma_f32_16x16x32_bf16 v[86:89], v[186:189], v[162:165], v[86:89]
	v_mfma_f32_16x16x32_bf16 v[118:121], v[194:197], v[106:109], v[118:121]
	v_mfma_f32_16x16x32_bf16 v[130:133], v[194:197], v[162:165], v[130:133]
	v_mfma_f32_16x16x32_bf16 v[2:5], v[174:177], v[110:113], v[2:5]
	v_mfma_f32_16x16x32_bf16 v[10:13], v[174:177], v[166:169], v[10:13]
	v_mfma_f32_16x16x32_bf16 v[22:25], v[182:185], v[110:113], v[22:25]
	v_mfma_f32_16x16x32_bf16 v[30:33], v[182:185], v[166:169], v[30:33]
	v_mfma_f32_16x16x32_bf16 v[62:65], v[190:193], v[110:113], v[62:65]
	v_mfma_f32_16x16x32_bf16 v[86:89], v[190:193], v[166:169], v[86:89]
	v_mfma_f32_16x16x32_bf16 v[118:121], v[198:201], v[110:113], v[118:121]
	v_mfma_f32_16x16x32_bf16 v[130:133], v[198:201], v[166:169], v[130:133]
	s_barrier
	v_lshl_add_u64 v[214:215], v[48:49], 0, s[24:25]
	s_mov_b32 m0, s43
	v_lshl_add_u64 v[216:217], v[214:215], 0, s[0:1]
	ds_read_b128 v[202:205], v240
	ds_read_b128 v[206:209], v240 offset:1024
	ds_read_b128 v[222:225], v240 offset:2048
	ds_read_b128 v[226:229], v240 offset:3072
	global_load_lds_dwordx4 v[216:217], off
	v_lshl_add_u64 v[216:217], v[34:35], 0, s[24:25]
	v_lshl_add_u64 v[218:219], v[216:217], 0, s[0:1]
	s_mov_b32 m0, s44
	s_nop 0
	global_load_lds_dwordx4 v[218:219], off
	s_barrier
	s_waitcnt lgkmcnt(0)
	s_waitcnt lgkmcnt(0)
	v_mfma_f32_16x16x32_bf16 v[6:9], v[170:173], v[202:205], v[6:9]
	v_mfma_f32_16x16x32_bf16 v[14:17], v[170:173], v[222:225], v[14:17]
	v_mfma_f32_16x16x32_bf16 v[18:21], v[178:181], v[202:205], v[18:21]
	v_mfma_f32_16x16x32_bf16 v[26:29], v[178:181], v[222:225], v[26:29]
	v_mfma_f32_16x16x32_bf16 v[58:61], v[186:189], v[202:205], v[58:61]
	v_mfma_f32_16x16x32_bf16 v[82:85], v[186:189], v[222:225], v[82:85]
	v_mfma_f32_16x16x32_bf16 v[114:117], v[194:197], v[202:205], v[114:117]
	v_mfma_f32_16x16x32_bf16 v[126:129], v[194:197], v[222:225], v[126:129]
	v_mfma_f32_16x16x32_bf16 v[6:9], v[174:177], v[206:209], v[6:9]
	v_mfma_f32_16x16x32_bf16 v[14:17], v[174:177], v[226:229], v[14:17]
	v_mfma_f32_16x16x32_bf16 v[18:21], v[182:185], v[206:209], v[18:21]
	v_mfma_f32_16x16x32_bf16 v[26:29], v[182:185], v[226:229], v[26:29]
	v_mfma_f32_16x16x32_bf16 v[58:61], v[190:193], v[206:209], v[58:61]
	v_mfma_f32_16x16x32_bf16 v[82:85], v[190:193], v[226:229], v[82:85]
	v_mfma_f32_16x16x32_bf16 v[114:117], v[198:201], v[206:209], v[114:117]
	v_mfma_f32_16x16x32_bf16 v[126:129], v[198:201], v[226:229], v[126:129]
	v_lshl_add_u64 v[218:219], v[72:73], 0, s[24:25]
	s_mov_b32 m0, s42
	v_lshl_add_u64 v[220:221], v[218:219], 0, s[0:1]
	s_barrier
	ds_read_b128 v[170:173], v236 offset:16384
	ds_read_b128 v[174:177], v236 offset:17408
	ds_read_b128 v[178:181], v237 offset:16384
	ds_read_b128 v[182:185], v237 offset:17408
	ds_read_b128 v[186:189], v238 offset:16384
	ds_read_b128 v[190:193], v238 offset:17408
	ds_read_b128 v[194:197], v239 offset:16384
	ds_read_b128 v[198:201], v239 offset:17408
	global_load_lds_dwordx4 v[220:221], off
	v_lshl_add_u64 v[220:221], v[66:67], 0, s[24:25]
	v_lshl_add_u64 v[230:231], v[220:221], 0, s[0:1]
	s_mov_b32 m0, s19
	s_nop 0
	global_load_lds_dwordx4 v[230:231], off
	s_barrier
	s_waitcnt lgkmcnt(0)
	s_waitcnt lgkmcnt(0)
	v_mfma_f32_16x16x32_bf16 v[122:125], v[170:173], v[106:109], v[122:125]
	v_mfma_f32_16x16x32_bf16 v[138:141], v[170:173], v[162:165], v[138:141]
	v_mfma_f32_16x16x32_bf16 v[50:53], v[178:181], v[106:109], v[50:53]
	v_mfma_f32_16x16x32_bf16 v[54:57], v[178:181], v[162:165], v[54:57]
	v_mfma_f32_16x16x32_bf16 v[78:81], v[186:189], v[106:109], v[78:81]
	v_mfma_f32_16x16x32_bf16 v[142:145], v[186:189], v[162:165], v[142:145]
	v_mfma_f32_16x16x32_bf16 v[102:105], v[194:197], v[106:109], v[102:105]
	v_mfma_f32_16x16x32_bf16 v[122:125], v[174:177], v[110:113], v[122:125]
	v_mfma_f32_16x16x32_bf16 v[138:141], v[174:177], v[166:169], v[138:141]
	v_mfma_f32_16x16x32_bf16 v[50:53], v[182:185], v[110:113], v[50:53]
	v_mfma_f32_16x16x32_bf16 v[54:57], v[182:185], v[166:169], v[54:57]
	v_mfma_f32_16x16x32_bf16 v[78:81], v[190:193], v[110:113], v[78:81]
	v_mfma_f32_16x16x32_bf16 v[142:145], v[190:193], v[166:169], v[142:145]
	v_mfma_f32_16x16x32_bf16 v[102:105], v[198:201], v[110:113], v[102:105]
	v_mfma_f32_16x16x32_bf16 v[106:109], v[194:197], v[162:165], v[146:149]
	v_mfma_f32_16x16x32_bf16 v[106:109], v[198:201], v[166:169], v[106:109]
	s_barrier
; #define STAGE(P, BASE, br, kt) do { const char* _gb = (const char*)((BASE) + ((long)(br) * K + (long)(kt) * BK)); \
;     __builtin_amdgcn_global_load_lds((const unsigned*)(_gb + (size_t)so0), (unsigned*)((char*)(P) + wv1k), 16, 0, 0); \
;     __builtin_amdgcn_global_load_lds((const unsigned*)(_gb + (size_t)so1), (unsigned*)((char*)(P) + wv1k + 8192), 16, 0, 0); } while (0)
; #define LDA(dst, b, h) _Pragma("unroll") for (int m = 0; m < 4; ++m) _Pragma("unroll") for (int k = 0; k < 2; ++k) \
;     dst[m][k] = *reinterpret_cast<const bf16x8*>((char*)SA(b, h) + lds_byte(wr * 64 + m * 16 + fr, k * 32 + fq * 8))
; #define LDB(dst, b, h) _Pragma("unroll") for (int n = 0; n < 2; ++n) _Pragma("unroll") for (int k = 0; k < 2; ++k) \
;     dst[n][k] = *reinterpret_cast<const bf16x8*>((char*)SB(b, h) + lds_byte(wc * 32 + n * 16 + fr, k * 32 + fq * 8))
; #define MMA(ai, bj, At_, Bt_) do { __builtin_amdgcn_s_setprio(1); \
;     _Pragma("unroll") for (int m = 0; m < 4; ++m) _Pragma("unroll") for (int n = 0; n < 2; ++n) _Pragma("unroll") for (int k = 0; k < 2; ++k) \
;       acc[ai][bj][m][n] = __builtin_amdgcn_mfma_f32_16x16x32_bf16(At_[m][k], Bt_[n][k], acc[ai][bj][m][n], 0, 0, 0); \
;     __builtin_amdgcn_s_setprio(0); } while (0)
; #define WAIT_V(n) asm volatile("s_waitcnt vmcnt(" #n ")" ::: "memory")
; #define WAIT_L(n) asm volatile("s_waitcnt lgkmcnt(" #n ")" ::: "memory")
; #define BAR __builtin_amdgcn_s_barrier()
; #define SCHED __builtin_amdgcn_sched_barrier(0)
; template <class Epi> ...
;     ...
;     WAIT_V(6); BAR; MMA(1, 1, At, B1); BAR;
;     LDB(B0, 1, 0); SCHED; LDA(At, 1, 0); STAGE(SA(0, 1), A, brow + HALF, t + 2);
;     WAIT_L(8); BAR; WAIT_L(0); MMA(0, 0, At, B0); BAR; SCHED;
;     LDB(B1, 1, 1); STAGE(SB(1, 0), Bt, bcol, t + 3);
;     BAR; WAIT_L(0); MMA(0, 1, At, B1); BAR;
;     LDA(At, 1, 1); STAGE(SA(1, 0), A, brow, t + 3);
;     BAR; WAIT_L(0); MMA(1, 0, At, B0); BAR; SCHED;
	s_mov_b32 m0, s45
	v_lshl_add_u64 v[110:111], v[214:215], 0, s[2:3]
	global_load_lds_dwordx4 v[110:111], off
	v_lshl_add_u64 v[110:111], v[216:217], 0, s[2:3]
	s_mov_b32 m0, s46
	s_nop 0
	global_load_lds_dwordx4 v[110:111], off
	s_waitcnt vmcnt(6)
	s_barrier
	v_mfma_f32_16x16x32_bf16 v[36:39], v[170:173], v[222:225], v[36:39]
	v_mfma_f32_16x16x32_bf16 v[40:43], v[178:181], v[202:205], v[40:43]
	v_mfma_f32_16x16x32_bf16 v[44:47], v[178:181], v[222:225], v[44:47]
	v_mfma_f32_16x16x32_bf16 v[74:77], v[186:189], v[202:205], v[74:77]
	v_mfma_f32_16x16x32_bf16 v[68:71], v[186:189], v[222:225], v[68:71]
	v_mfma_f32_16x16x32_bf16 v[98:101], v[194:197], v[202:205], v[98:101]
	v_mfma_f32_16x16x32_bf16 v[92:95], v[194:197], v[222:225], v[92:95]
	v_mfma_f32_16x16x32_bf16 v[110:113], v[170:173], v[202:205], v[134:137]
	v_mfma_f32_16x16x32_bf16 v[36:39], v[174:177], v[226:229], v[36:39]
	v_mfma_f32_16x16x32_bf16 v[40:43], v[182:185], v[206:209], v[40:43]
	v_mfma_f32_16x16x32_bf16 v[44:47], v[182:185], v[226:229], v[44:47]
	v_mfma_f32_16x16x32_bf16 v[74:77], v[190:193], v[206:209], v[74:77]
	v_mfma_f32_16x16x32_bf16 v[68:71], v[190:193], v[226:229], v[68:71]
	v_mfma_f32_16x16x32_bf16 v[98:101], v[198:201], v[206:209], v[98:101]
	v_mfma_f32_16x16x32_bf16 v[92:95], v[198:201], v[226:229], v[92:95]
	v_mfma_f32_16x16x32_bf16 v[110:113], v[174:177], v[206:209], v[110:113]
	s_barrier
	ds_read_b128 v[134:137], v241
	ds_read_b128 v[146:149], v241 offset:1024
	ds_read_b128 v[162:165], v241 offset:2048
	ds_read_b128 v[166:169], v241 offset:3072
	s_mov_b32 m0, s47
	v_lshl_add_u64 v[202:203], v[210:211], 0, s[2:3]
	ds_read_b128 v[170:173], v236 offset:32768
	ds_read_b128 v[174:177], v236 offset:33792
	ds_read_b128 v[178:181], v237 offset:32768
	ds_read_b128 v[182:185], v237 offset:33792
	ds_read_b128 v[186:189], v238 offset:32768
	ds_read_b128 v[190:193], v238 offset:33792
	ds_read_b128 v[194:197], v239 offset:32768
	ds_read_b128 v[198:201], v239 offset:33792
	global_load_lds_dwordx4 v[202:203], off
	v_lshl_add_u64 v[202:203], v[212:213], 0, s[2:3]
	s_mov_b32 m0, s50
	s_nop 0
	global_load_lds_dwordx4 v[202:203], off
	s_waitcnt lgkmcnt(8)
	s_barrier
	s_waitcnt lgkmcnt(0)
	s_waitcnt lgkmcnt(0)
	v_mfma_f32_16x16x32_bf16 v[2:5], v[170:173], v[134:137], v[2:5]
	v_mfma_f32_16x16x32_bf16 v[10:13], v[170:173], v[162:165], v[10:13]
	v_mfma_f32_16x16x32_bf16 v[22:25], v[178:181], v[134:137], v[22:25]
	v_mfma_f32_16x16x32_bf16 v[30:33], v[178:181], v[162:165], v[30:33]
	v_mfma_f32_16x16x32_bf16 v[62:65], v[186:189], v[134:137], v[62:65]
	v_mfma_f32_16x16x32_bf16 v[86:89], v[186:189], v[162:165], v[86:89]
	v_mfma_f32_16x16x32_bf16 v[118:121], v[194:197], v[134:137], v[118:121]
	v_mfma_f32_16x16x32_bf16 v[130:133], v[194:197], v[162:165], v[130:133]
	v_mfma_f32_16x16x32_bf16 v[2:5], v[174:177], v[146:149], v[2:5]
	v_mfma_f32_16x16x32_bf16 v[10:13], v[174:177], v[166:169], v[10:13]
	v_mfma_f32_16x16x32_bf16 v[22:25], v[182:185], v[146:149], v[22:25]
	v_mfma_f32_16x16x32_bf16 v[30:33], v[182:185], v[166:169], v[30:33]
	v_mfma_f32_16x16x32_bf16 v[62:65], v[190:193], v[146:149], v[62:65]
	v_mfma_f32_16x16x32_bf16 v[86:89], v[190:193], v[166:169], v[86:89]
	v_mfma_f32_16x16x32_bf16 v[118:121], v[198:201], v[146:149], v[118:121]
	v_mfma_f32_16x16x32_bf16 v[130:133], v[198:201], v[166:169], v[130:133]
	s_barrier
	s_mov_b32 m0, s34
	v_lshl_add_u64 v[210:211], v[214:215], 0, s[90:91]
	ds_read_b128 v[202:205], v242
	ds_read_b128 v[206:209], v242 offset:1024
	ds_read_b128 v[222:225], v242 offset:2048
	ds_read_b128 v[226:229], v242 offset:3072
	global_load_lds_dwordx4 v[210:211], off
	v_lshl_add_u64 v[210:211], v[216:217], 0, s[90:91]
	s_mov_b32 m0, s35
	s_nop 0
	global_load_lds_dwordx4 v[210:211], off
	s_barrier
	s_waitcnt lgkmcnt(0)
	s_waitcnt lgkmcnt(0)
	v_mfma_f32_16x16x32_bf16 v[6:9], v[170:173], v[202:205], v[6:9]
	v_mfma_f32_16x16x32_bf16 v[14:17], v[170:173], v[222:225], v[14:17]
	v_mfma_f32_16x16x32_bf16 v[18:21], v[178:181], v[202:205], v[18:21]
	v_mfma_f32_16x16x32_bf16 v[26:29], v[178:181], v[222:225], v[26:29]
	v_mfma_f32_16x16x32_bf16 v[58:61], v[186:189], v[202:205], v[58:61]
	v_mfma_f32_16x16x32_bf16 v[82:85], v[186:189], v[222:225], v[82:85]
	v_mfma_f32_16x16x32_bf16 v[114:117], v[194:197], v[202:205], v[114:117]
	v_mfma_f32_16x16x32_bf16 v[126:129], v[194:197], v[222:225], v[126:129]
	v_mfma_f32_16x16x32_bf16 v[6:9], v[174:177], v[206:209], v[6:9]
	v_mfma_f32_16x16x32_bf16 v[14:17], v[174:177], v[226:229], v[14:17]
	v_mfma_f32_16x16x32_bf16 v[18:21], v[182:185], v[206:209], v[18:21]
	v_mfma_f32_16x16x32_bf16 v[26:29], v[182:185], v[226:229], v[26:29]
	v_mfma_f32_16x16x32_bf16 v[58:61], v[190:193], v[206:209], v[58:61]
	v_mfma_f32_16x16x32_bf16 v[82:85], v[190:193], v[226:229], v[82:85]
	v_mfma_f32_16x16x32_bf16 v[114:117], v[198:201], v[206:209], v[114:117]
	v_mfma_f32_16x16x32_bf16 v[126:129], v[198:201], v[226:229], v[126:129]
	s_mov_b32 m0, s51
	v_lshl_add_u64 v[210:211], v[218:219], 0, s[90:91]
	s_barrier
	ds_read_b128 v[170:173], v236 offset:49152
	ds_read_b128 v[174:177], v236 offset:50176
	ds_read_b128 v[178:181], v237 offset:49152
	ds_read_b128 v[182:185], v237 offset:50176
	ds_read_b128 v[186:189], v238 offset:49152
	ds_read_b128 v[190:193], v238 offset:50176
	ds_read_b128 v[194:197], v239 offset:49152
	ds_read_b128 v[198:201], v239 offset:50176
	global_load_lds_dwordx4 v[210:211], off
	v_lshl_add_u64 v[210:211], v[220:221], 0, s[90:91]
	s_mov_b32 m0, s52
	s_nop 0
	global_load_lds_dwordx4 v[210:211], off
	s_barrier
; #define STAGE(P, BASE, br, kt) do { const char* _gb = (const char*)((BASE) + ((long)(br) * K + (long)(kt) * BK)); \
;     __builtin_amdgcn_global_load_lds((const unsigned*)(_gb + (size_t)so0), (unsigned*)((char*)(P) + wv1k), 16, 0, 0); \
;     __builtin_amdgcn_global_load_lds((const unsigned*)(_gb + (size_t)so1), (unsigned*)((char*)(P) + wv1k + 8192), 16, 0, 0); } while (0)
; #define LDA(dst, b, h) _Pragma("unroll") for (int m = 0; m < 4; ++m) _Pragma("unroll") for (int k = 0; k < 2; ++k) \
;     dst[m][k] = *reinterpret_cast<const bf16x8*>((char*)SA(b, h) + lds_byte(wr * 64 + m * 16 + fr, k * 32 + fq * 8))
; #define LDB(dst, b, h) _Pragma("unroll") for (int n = 0; n < 2; ++n) _Pragma("unroll") for (int k = 0; k < 2; ++k) \
;     dst[n][k] = *reinterpret_cast<const bf16x8*>((char*)SB(b, h) + lds_byte(wc * 32 + n * 16 + fr, k * 32 + fq * 8))
; #define MMA(ai, bj, At_, Bt_) do { __builtin_amdgcn_s_setprio(1); \
;     _Pragma("unroll") for (int m = 0; m < 4; ++m) _Pragma("unroll") for (int n = 0; n < 2; ++n) _Pragma("unroll") for (int k = 0; k < 2; ++k) \
;       acc[ai][bj][m][n] = __builtin_amdgcn_mfma_f32_16x16x32_bf16(At_[m][k], Bt_[n][k], acc[ai][bj][m][n], 0, 0, 0); \
;     __builtin_amdgcn_s_setprio(0); } while (0)
; #define WAIT_V(n) asm volatile("s_waitcnt vmcnt(" #n ")" ::: "memory")
; #define WAIT_L(n) asm volatile("s_waitcnt lgkmcnt(" #n ")" ::: "memory")
; #define BAR __builtin_amdgcn_s_barrier()
; #define SCHED __builtin_amdgcn_sched_barrier(0)
; template <class Epi> ...
;     ...
;     BAR; WAIT_L(0); MMA(1, 0, At, B0); BAR; SCHED;
;     STAGE(SB(1, 1), Bt, bcol + HALF, t + 3);
;     WAIT_V(6); BAR; MMA(1, 1, At, B1); BAR;
;   }
;   { LDB(B0, 0, 0); LDA(At, 0, 0); STAGE(SA(1, 1), A, brow + HALF, nt - 1);
;     BAR; WAIT_L(0); MMA(0, 0, At, B0); BAR;
;     LDB(B1, 0, 1); BAR; WAIT_L(0); MMA(0, 1, At, B1); BAR;
;     LDA(At, 0, 1); WAIT_V(4); BAR; WAIT_L(0); MMA(1, 0, At, B0); MMA(1, 1, At, B1); BAR; }
	s_waitcnt lgkmcnt(0)
	s_waitcnt lgkmcnt(0)
	v_mfma_f32_16x16x32_bf16 v[122:125], v[170:173], v[134:137], v[122:125]
	v_mfma_f32_16x16x32_bf16 v[138:141], v[170:173], v[162:165], v[138:141]
	v_mfma_f32_16x16x32_bf16 v[50:53], v[178:181], v[134:137], v[50:53]
	v_mfma_f32_16x16x32_bf16 v[54:57], v[178:181], v[162:165], v[54:57]
	v_mfma_f32_16x16x32_bf16 v[78:81], v[186:189], v[134:137], v[78:81]
	v_mfma_f32_16x16x32_bf16 v[142:145], v[186:189], v[162:165], v[142:145]
	v_mfma_f32_16x16x32_bf16 v[102:105], v[194:197], v[134:137], v[102:105]
	v_mfma_f32_16x16x32_bf16 v[106:109], v[194:197], v[162:165], v[106:109]
	v_mfma_f32_16x16x32_bf16 v[122:125], v[174:177], v[146:149], v[122:125]
	v_mfma_f32_16x16x32_bf16 v[138:141], v[174:177], v[166:169], v[138:141]
	v_mfma_f32_16x16x32_bf16 v[50:53], v[182:185], v[146:149], v[50:53]
	v_mfma_f32_16x16x32_bf16 v[54:57], v[182:185], v[166:169], v[54:57]
	v_mfma_f32_16x16x32_bf16 v[78:81], v[190:193], v[146:149], v[78:81]
	v_mfma_f32_16x16x32_bf16 v[142:145], v[190:193], v[166:169], v[142:145]
	v_mfma_f32_16x16x32_bf16 v[102:105], v[198:201], v[146:149], v[102:105]
	v_mfma_f32_16x16x32_bf16 v[146:149], v[198:201], v[166:169], v[106:109]
	s_barrier
	s_mov_b32 m0, s30
	v_lshl_add_u64 v[106:107], v[214:215], 0, s[60:61]
	global_load_lds_dwordx4 v[106:107], off
	v_lshl_add_u64 v[106:107], v[216:217], 0, s[60:61]
	s_mov_b32 m0, s31
	s_nop 0
	global_load_lds_dwordx4 v[106:107], off
	s_waitcnt vmcnt(6)
	s_barrier
	v_mfma_f32_16x16x32_bf16 v[106:109], v[170:173], v[202:205], v[110:113]
	v_mfma_f32_16x16x32_bf16 v[36:39], v[170:173], v[222:225], v[36:39]
	v_mfma_f32_16x16x32_bf16 v[40:43], v[178:181], v[202:205], v[40:43]
	v_mfma_f32_16x16x32_bf16 v[44:47], v[178:181], v[222:225], v[44:47]
	v_mfma_f32_16x16x32_bf16 v[74:77], v[186:189], v[202:205], v[74:77]
	v_mfma_f32_16x16x32_bf16 v[68:71], v[186:189], v[222:225], v[68:71]
	v_mfma_f32_16x16x32_bf16 v[98:101], v[194:197], v[202:205], v[98:101]
	v_mfma_f32_16x16x32_bf16 v[92:95], v[194:197], v[222:225], v[92:95]
	v_mfma_f32_16x16x32_bf16 v[134:137], v[174:177], v[206:209], v[106:109]
	v_mfma_f32_16x16x32_bf16 v[36:39], v[174:177], v[226:229], v[36:39]
	v_mfma_f32_16x16x32_bf16 v[40:43], v[182:185], v[206:209], v[40:43]
	v_mfma_f32_16x16x32_bf16 v[44:47], v[182:185], v[226:229], v[44:47]
	v_mfma_f32_16x16x32_bf16 v[74:77], v[190:193], v[206:209], v[74:77]
	v_mfma_f32_16x16x32_bf16 v[68:71], v[190:193], v[226:229], v[68:71]
	v_mfma_f32_16x16x32_bf16 v[98:101], v[198:201], v[206:209], v[98:101]
	v_mfma_f32_16x16x32_bf16 v[92:95], v[198:201], v[226:229], v[92:95]
	s_add_i32 s26, s26, 2
	s_add_u32 s24, s24, 0x100
	s_addc_u32 s25, s25, 0
	s_cmp_lt_u32 s26, 40
	s_barrier
	s_cbranch_scc1 .LBB0_82
	s_add_u32 s22, s22, 0x1580
	s_addc_u32 s23, s23, 0
	s_mov_b32 m0, s28
	v_lshl_add_u64 v[34:35], s[22:23], 0, v[0:1]
	ds_read_b128 v[106:109], v235
	ds_read_b128 v[110:113], v235 offset:1024
	ds_read_b128 v[162:165], v235 offset:2048
	ds_read_b128 v[166:169], v235 offset:3072
	ds_read_b128 v[170:173], v236
	ds_read_b128 v[174:177], v236 offset:1024
	ds_read_b128 v[178:181], v237
	ds_read_b128 v[182:185], v237 offset:1024
	ds_read_b128 v[186:189], v238
	ds_read_b128 v[190:193], v238 offset:1024
	ds_read_b128 v[194:197], v239
	ds_read_b128 v[198:201], v239 offset:1024
	global_load_lds_dwordx4 v[34:35], off
	v_lshl_add_u64 v[34:35], s[22:23], 0, v[152:153]
	s_mov_b32 m0, s27
	s_nop 0
	global_load_lds_dwordx4 v[34:35], off
	s_barrier
	s_waitcnt lgkmcnt(0)
	s_waitcnt lgkmcnt(0)
	v_mfma_f32_16x16x32_bf16 v[2:5], v[170:173], v[106:109], v[2:5]
	v_mfma_f32_16x16x32_bf16 v[10:13], v[170:173], v[162:165], v[10:13]
	v_mfma_f32_16x16x32_bf16 v[22:25], v[178:181], v[106:109], v[22:25]
	v_mfma_f32_16x16x32_bf16 v[30:33], v[178:181], v[162:165], v[30:33]
	v_mfma_f32_16x16x32_bf16 v[62:65], v[186:189], v[106:109], v[62:65]
	v_mfma_f32_16x16x32_bf16 v[86:89], v[186:189], v[162:165], v[86:89]
	v_mfma_f32_16x16x32_bf16 v[118:121], v[194:197], v[106:109], v[118:121]
	v_mfma_f32_16x16x32_bf16 v[2:5], v[174:177], v[110:113], v[2:5]
	v_mfma_f32_16x16x32_bf16 v[10:13], v[174:177], v[166:169], v[10:13]
	v_mfma_f32_16x16x32_bf16 v[22:25], v[182:185], v[110:113], v[22:25]
	v_mfma_f32_16x16x32_bf16 v[30:33], v[182:185], v[166:169], v[30:33]
	v_mfma_f32_16x16x32_bf16 v[62:65], v[190:193], v[110:113], v[62:65]
	v_mfma_f32_16x16x32_bf16 v[86:89], v[190:193], v[166:169], v[86:89]
	v_mfma_f32_16x16x32_bf16 v[202:205], v[198:201], v[110:113], v[118:121]
	v_mfma_f32_16x16x32_bf16 v[118:121], v[194:197], v[162:165], v[130:133]
	v_mfma_f32_16x16x32_bf16 v[130:133], v[198:201], v[166:169], v[118:121]
	s_barrier
	s_nop 4
	ds_read_b128 v[118:121], v240
	ds_read_b128 v[206:209], v240 offset:1024
	ds_read_b128 v[222:225], v240 offset:2048
	ds_read_b128 v[226:229], v240 offset:3072
	s_barrier
	s_waitcnt lgkmcnt(0)
	s_waitcnt lgkmcnt(0)
	v_mfma_f32_16x16x32_bf16 v[58:61], v[186:189], v[118:121], v[58:61]
	v_mfma_f32_16x16x32_bf16 v[6:9], v[170:173], v[118:121], v[6:9]
	v_mfma_f32_16x16x32_bf16 v[14:17], v[170:173], v[222:225], v[14:17]
	v_mfma_f32_16x16x32_bf16 v[170:173], v[190:193], v[206:209], v[58:61]
	v_mfma_f32_16x16x32_bf16 v[58:61], v[186:189], v[222:225], v[82:85]
	v_mfma_f32_16x16x32_bf16 v[6:9], v[174:177], v[206:209], v[6:9]
	v_mfma_f32_16x16x32_bf16 v[14:17], v[174:177], v[226:229], v[14:17]
	v_mfma_f32_16x16x32_bf16 v[18:21], v[178:181], v[118:121], v[18:21]
	v_mfma_f32_16x16x32_bf16 v[26:29], v[178:181], v[222:225], v[26:29]
	v_mfma_f32_16x16x32_bf16 v[174:177], v[190:193], v[226:229], v[58:61]
	v_mfma_f32_16x16x32_bf16 v[58:61], v[194:197], v[118:121], v[114:117]
	v_mfma_f32_16x16x32_bf16 v[18:21], v[182:185], v[206:209], v[18:21]
	v_mfma_f32_16x16x32_bf16 v[26:29], v[182:185], v[226:229], v[26:29]
	v_mfma_f32_16x16x32_bf16 v[178:181], v[198:201], v[206:209], v[58:61]
	v_mfma_f32_16x16x32_bf16 v[58:61], v[194:197], v[222:225], v[126:129]
	v_mfma_f32_16x16x32_bf16 v[182:185], v[198:201], v[226:229], v[58:61]
	s_barrier
; #define LDA(dst, b, h) _Pragma("unroll") for (int m = 0; m < 4; ++m) _Pragma("unroll") for (int k = 0; k < 2; ++k) \
;     dst[m][k] = *reinterpret_cast<const bf16x8*>((char*)SA(b, h) + lds_byte(wr * 64 + m * 16 + fr, k * 32 + fq * 8))
; #define LDB(dst, b, h) _Pragma("unroll") for (int n = 0; n < 2; ++n) _Pragma("unroll") for (int k = 0; k < 2; ++k) \
;     dst[n][k] = *reinterpret_cast<const bf16x8*>((char*)SB(b, h) + lds_byte(wc * 32 + n * 16 + fr, k * 32 + fq * 8))
; #define MMA(ai, bj, At_, Bt_) do { __builtin_amdgcn_s_setprio(1); \
;     _Pragma("unroll") for (int m = 0; m < 4; ++m) _Pragma("unroll") for (int n = 0; n < 2; ++n) _Pragma("unroll") for (int k = 0; k < 2; ++k) \
;       acc[ai][bj][m][n] = __builtin_amdgcn_mfma_f32_16x16x32_bf16(At_[m][k], Bt_[n][k], acc[ai][bj][m][n], 0, 0, 0); \
;     __builtin_amdgcn_s_setprio(0); } while (0)
; #define WAIT_V(n) asm volatile("s_waitcnt vmcnt(" #n ")" ::: "memory")
; #define WAIT_L(n) asm volatile("s_waitcnt lgkmcnt(" #n ")" ::: "memory")
; #define BAR __builtin_amdgcn_s_barrier()
; template <class Epi> ...
;     ...
;     LDA(At, 0, 1); WAIT_V(4); BAR; WAIT_L(0); MMA(1, 0, At, B0); MMA(1, 1, At, B1); BAR; }
;   { LDB(B0, 1, 0); LDA(At, 1, 0); WAIT_V(2); BAR; WAIT_L(0); MMA(0, 0, At, B0); BAR;
	s_nop 4
	ds_read_b128 v[58:61], v236 offset:16384
	ds_read_b128 v[82:85], v236 offset:17408
	ds_read_b128 v[114:117], v237 offset:16384
	ds_read_b128 v[126:129], v237 offset:17408
	ds_read_b128 v[186:189], v238 offset:16384
	ds_read_b128 v[190:193], v238 offset:17408
	ds_read_b128 v[194:197], v239 offset:16384
	ds_read_b128 v[198:201], v239 offset:17408
	s_waitcnt vmcnt(4)
	s_barrier
	s_waitcnt lgkmcnt(0)
	s_waitcnt lgkmcnt(0)
	v_mfma_f32_16x16x32_bf16 v[48:51], v[114:117], v[106:109], v[50:53]
	v_mfma_f32_16x16x32_bf16 v[244:247], v[126:129], v[110:113], v[48:51]
	v_mfma_f32_16x16x32_bf16 v[48:51], v[114:117], v[162:165], v[54:57]
	v_mfma_f32_16x16x32_bf16 v[248:251], v[126:129], v[166:169], v[48:51]
	v_mfma_f32_16x16x32_bf16 v[48:51], v[186:189], v[106:109], v[78:81]
	v_mfma_f32_16x16x32_bf16 v[214:217], v[190:193], v[110:113], v[48:51]
	v_mfma_f32_16x16x32_bf16 v[48:51], v[186:189], v[162:165], v[142:145]
	v_mfma_f32_16x16x32_bf16 v[122:125], v[58:61], v[106:109], v[122:125]
	v_mfma_f32_16x16x32_bf16 v[142:145], v[190:193], v[166:169], v[48:51]
	v_mfma_f32_16x16x32_bf16 v[48:51], v[194:197], v[106:109], v[102:105]
	v_mfma_f32_16x16x32_bf16 v[230:233], v[82:85], v[110:113], v[122:125]
	v_mfma_f32_16x16x32_bf16 v[122:125], v[58:61], v[162:165], v[138:141]
	v_mfma_f32_16x16x32_bf16 v[210:213], v[198:201], v[110:113], v[48:51]
	v_mfma_f32_16x16x32_bf16 v[48:51], v[194:197], v[162:165], v[146:149]
	v_mfma_f32_16x16x32_bf16 v[138:141], v[82:85], v[166:169], v[122:125]
	v_mfma_f32_16x16x32_bf16 v[146:149], v[198:201], v[166:169], v[48:51]
	v_mfma_f32_16x16x32_bf16 v[34:37], v[58:61], v[222:225], v[36:39]
	v_mfma_f32_16x16x32_bf16 v[162:165], v[82:85], v[226:229], v[34:37]
	v_mfma_f32_16x16x32_bf16 v[34:37], v[114:117], v[118:121], v[40:43]
	v_mfma_f32_16x16x32_bf16 v[48:51], v[58:61], v[118:121], v[134:137]
	v_mfma_f32_16x16x32_bf16 v[166:169], v[126:129], v[206:209], v[34:37]
	v_mfma_f32_16x16x32_bf16 v[34:37], v[114:117], v[222:225], v[44:47]
	v_mfma_f32_16x16x32_bf16 v[134:137], v[82:85], v[206:209], v[48:51]
	v_mfma_f32_16x16x32_bf16 v[46:49], v[126:129], v[226:229], v[34:37]
	v_mfma_f32_16x16x32_bf16 v[34:37], v[186:189], v[118:121], v[74:77]
	v_mfma_f32_16x16x32_bf16 v[218:221], v[190:193], v[206:209], v[34:37]
	v_mfma_f32_16x16x32_bf16 v[34:37], v[186:189], v[222:225], v[68:71]
	v_mfma_f32_16x16x32_bf16 v[186:189], v[190:193], v[226:229], v[34:37]
	v_mfma_f32_16x16x32_bf16 v[34:37], v[194:197], v[118:121], v[98:101]
	v_mfma_f32_16x16x32_bf16 v[190:193], v[198:201], v[206:209], v[34:37]
	v_mfma_f32_16x16x32_bf16 v[34:37], v[194:197], v[222:225], v[92:95]
	v_mfma_f32_16x16x32_bf16 v[194:197], v[198:201], v[226:229], v[34:37]
	s_barrier
	ds_read_b128 v[42:45], v241
	ds_read_b128 v[66:69], v241 offset:1024
	ds_read_b128 v[70:73], v241 offset:2048
	ds_read_b128 v[198:201], v241 offset:3072
	s_nop 0
	ds_read_b128 v[34:37], v236 offset:32768
	ds_read_b128 v[38:41], v236 offset:33792
	ds_read_b128 v[50:53], v237 offset:32768
	ds_read_b128 v[54:57], v237 offset:33792
	ds_read_b128 v[74:77], v238 offset:32768
	ds_read_b128 v[78:81], v238 offset:33792
	ds_read_b128 v[206:209], v239 offset:32768
	ds_read_b128 v[222:225], v239 offset:33792
	s_waitcnt vmcnt(2)
	s_barrier
	s_waitcnt lgkmcnt(0)
	s_waitcnt lgkmcnt(0)
	v_mfma_f32_16x16x32_bf16 v[2:5], v[34:37], v[42:45], v[2:5]
	v_mfma_f32_16x16x32_bf16 v[114:117], v[38:41], v[66:69], v[2:5]
	v_mfma_f32_16x16x32_bf16 v[2:5], v[34:37], v[70:73], v[10:13]
	v_mfma_f32_16x16x32_bf16 v[118:121], v[38:41], v[198:201], v[2:5]
	v_mfma_f32_16x16x32_bf16 v[2:5], v[50:53], v[42:45], v[22:25]
	v_mfma_f32_16x16x32_bf16 v[98:101], v[54:57], v[66:69], v[2:5]
	v_mfma_f32_16x16x32_bf16 v[2:5], v[50:53], v[70:73], v[30:33]
	v_mfma_f32_16x16x32_bf16 v[102:105], v[54:57], v[198:201], v[2:5]
	v_mfma_f32_16x16x32_bf16 v[2:5], v[74:77], v[42:45], v[62:65]
	v_mfma_f32_16x16x32_bf16 v[82:85], v[78:81], v[66:69], v[2:5]
	v_mfma_f32_16x16x32_bf16 v[2:5], v[74:77], v[70:73], v[86:89]
	v_mfma_f32_16x16x32_bf16 v[86:89], v[78:81], v[198:201], v[2:5]
	v_mfma_f32_16x16x32_bf16 v[2:5], v[206:209], v[42:45], v[202:205]
	v_mfma_f32_16x16x32_bf16 v[58:61], v[222:225], v[66:69], v[2:5]
	v_mfma_f32_16x16x32_bf16 v[2:5], v[206:209], v[70:73], v[130:133]
	v_mfma_f32_16x16x32_bf16 v[62:65], v[222:225], v[198:201], v[2:5]
	s_barrier
; #define LDA(dst, b, h) _Pragma("unroll") for (int m = 0; m < 4; ++m) _Pragma("unroll") for (int k = 0; k < 2; ++k) \
;     dst[m][k] = *reinterpret_cast<const bf16x8*>((char*)SA(b, h) + lds_byte(wr * 64 + m * 16 + fr, k * 32 + fq * 8))
; #define LDB(dst, b, h) _Pragma("unroll") for (int n = 0; n < 2; ++n) _Pragma("unroll") for (int k = 0; k < 2; ++k) \
;     dst[n][k] = *reinterpret_cast<const bf16x8*>((char*)SB(b, h) + lds_byte(wc * 32 + n * 16 + fr, k * 32 + fq * 8))
; #define MMA(ai, bj, At_, Bt_) do { __builtin_amdgcn_s_setprio(1); \
;     _Pragma("unroll") for (int m = 0; m < 4; ++m) _Pragma("unroll") for (int n = 0; n < 2; ++n) _Pragma("unroll") for (int k = 0; k < 2; ++k) \
;       acc[ai][bj][m][n] = __builtin_amdgcn_mfma_f32_16x16x32_bf16(At_[m][k], Bt_[n][k], acc[ai][bj][m][n], 0, 0, 0); \
;     __builtin_amdgcn_s_setprio(0); } while (0)
; #define WAIT_V(n) asm volatile("s_waitcnt vmcnt(" #n ")" ::: "memory")
; #define WAIT_L(n) asm volatile("s_waitcnt lgkmcnt(" #n ")" ::: "memory")
; #define BAR __builtin_amdgcn_s_barrier()
; template <class Epi> ...
;     ...
;   { LDB(B0, 1, 0); LDA(At, 1, 0); WAIT_V(2); BAR; WAIT_L(0); MMA(0, 0, At, B0); BAR;
;     LDB(B1, 1, 1); WAIT_V(0); BAR; WAIT_L(0); MMA(0, 1, At, B1); BAR;
;     LDA(At, 1, 1); BAR; WAIT_L(0); MMA(1, 0, At, B0); MMA(1, 1, At, B1); BAR; }
;   if (wr == 0) BAR;
	ds_read_b128 v[10:13], v242
	ds_read_b128 v[130:133], v242 offset:1024
	ds_read_b128 v[202:205], v242 offset:2048
	ds_read_b128 v[226:229], v242 offset:3072
	s_waitcnt vmcnt(0)
	s_barrier
	s_waitcnt lgkmcnt(0)
	s_waitcnt lgkmcnt(0)
	v_mfma_f32_16x16x32_bf16 v[2:5], v[34:37], v[10:13], v[6:9]
	v_mfma_f32_16x16x32_bf16 v[122:125], v[38:41], v[130:133], v[2:5]
	v_mfma_f32_16x16x32_bf16 v[2:5], v[34:37], v[202:205], v[14:17]
	v_mfma_f32_16x16x32_bf16 v[126:129], v[38:41], v[226:229], v[2:5]
	v_mfma_f32_16x16x32_bf16 v[2:5], v[50:53], v[10:13], v[18:21]
	v_mfma_f32_16x16x32_bf16 v[106:109], v[54:57], v[130:133], v[2:5]
	v_mfma_f32_16x16x32_bf16 v[2:5], v[50:53], v[202:205], v[26:29]
	v_mfma_f32_16x16x32_bf16 v[110:113], v[54:57], v[226:229], v[2:5]
	v_mfma_f32_16x16x32_bf16 v[2:5], v[74:77], v[10:13], v[170:173]
	v_mfma_f32_16x16x32_bf16 v[90:93], v[78:81], v[130:133], v[2:5]
	v_mfma_f32_16x16x32_bf16 v[2:5], v[74:77], v[202:205], v[174:177]
	v_mfma_f32_16x16x32_bf16 v[94:97], v[78:81], v[226:229], v[2:5]
	v_mfma_f32_16x16x32_bf16 v[2:5], v[206:209], v[10:13], v[178:181]
	v_mfma_f32_16x16x32_bf16 v[74:77], v[222:225], v[130:133], v[2:5]
	v_mfma_f32_16x16x32_bf16 v[2:5], v[206:209], v[202:205], v[182:185]
	v_mfma_f32_16x16x32_bf16 v[78:81], v[222:225], v[226:229], v[2:5]
	s_barrier
	ds_read_b128 v[14:17], v236 offset:49152
	ds_read_b128 v[26:29], v236 offset:50176
	ds_read_b128 v[30:33], v237 offset:49152
	ds_read_b128 v[170:173], v237 offset:50176
	ds_read_b128 v[174:177], v238 offset:49152
	ds_read_b128 v[178:181], v238 offset:50176
	ds_read_b128 v[182:185], v239 offset:49152
	ds_read_b128 v[206:209], v239 offset:50176
	s_barrier
	s_waitcnt lgkmcnt(0)
	s_waitcnt lgkmcnt(0)
	v_mfma_f32_16x16x32_bf16 v[2:5], v[14:17], v[42:45], v[230:233]
	v_mfma_f32_16x16x32_bf16 v[50:53], v[26:29], v[66:69], v[2:5]
	v_mfma_f32_16x16x32_bf16 v[2:5], v[14:17], v[70:73], v[138:141]
	v_mfma_f32_16x16x32_bf16 v[54:57], v[26:29], v[198:201], v[2:5]
	v_mfma_f32_16x16x32_bf16 v[2:5], v[30:33], v[42:45], v[244:247]
	v_mfma_f32_16x16x32_bf16 v[34:37], v[170:173], v[66:69], v[2:5]
	v_mfma_f32_16x16x32_bf16 v[2:5], v[30:33], v[70:73], v[248:251]
	v_mfma_f32_16x16x32_bf16 v[38:41], v[170:173], v[198:201], v[2:5]
	v_mfma_f32_16x16x32_bf16 v[2:5], v[174:177], v[42:45], v[214:217]
	v_mfma_f32_16x16x32_bf16 v[18:21], v[178:181], v[66:69], v[2:5]
	v_mfma_f32_16x16x32_bf16 v[2:5], v[174:177], v[70:73], v[142:145]
	v_mfma_f32_16x16x32_bf16 v[22:25], v[178:181], v[198:201], v[2:5]
	v_mfma_f32_16x16x32_bf16 v[2:5], v[182:185], v[42:45], v[210:213]
	v_mfma_f32_16x16x32_bf16 v[6:9], v[182:185], v[70:73], v[146:149]
	v_mfma_f32_16x16x32_bf16 v[2:5], v[206:209], v[66:69], v[2:5]
	v_mfma_f32_16x16x32_bf16 v[6:9], v[206:209], v[198:201], v[6:9]
	v_mfma_f32_16x16x32_bf16 v[42:45], v[14:17], v[10:13], v[134:137]
	v_mfma_f32_16x16x32_bf16 v[14:17], v[14:17], v[202:205], v[162:165]
	v_mfma_f32_16x16x32_bf16 v[70:73], v[26:29], v[226:229], v[14:17]
	v_mfma_f32_16x16x32_bf16 v[14:17], v[30:33], v[10:13], v[166:169]
	v_mfma_f32_16x16x32_bf16 v[66:69], v[26:29], v[130:133], v[42:45]
	v_mfma_f32_16x16x32_bf16 v[42:45], v[170:173], v[130:133], v[14:17]
	v_mfma_f32_16x16x32_bf16 v[14:17], v[30:33], v[202:205], v[46:49]
	v_mfma_f32_16x16x32_bf16 v[46:49], v[170:173], v[226:229], v[14:17]
	v_mfma_f32_16x16x32_bf16 v[14:17], v[174:177], v[10:13], v[218:221]
	v_mfma_f32_16x16x32_bf16 v[26:29], v[178:181], v[130:133], v[14:17]
	v_mfma_f32_16x16x32_bf16 v[14:17], v[174:177], v[202:205], v[186:189]
	v_mfma_f32_16x16x32_bf16 v[30:33], v[178:181], v[226:229], v[14:17]
	v_mfma_f32_16x16x32_bf16 v[10:13], v[182:185], v[10:13], v[190:193]
	v_mfma_f32_16x16x32_bf16 v[14:17], v[182:185], v[202:205], v[194:197]
	v_mfma_f32_16x16x32_bf16 v[10:13], v[206:209], v[130:133], v[10:13]
	v_mfma_f32_16x16x32_bf16 v[14:17], v[206:209], v[226:229], v[14:17]
	s_barrier
	s_and_saveexec_b64 s[22:23], s[6:7]
	s_cbranch_execz .LBB0_73
	s_barrier
	s_branch .LBB0_73

; #define STAGE(P, BASE, br, kt) do { const char* _gb = (const char*)((BASE) + ((long)(br) * K + (long)(kt) * BK)); \
;     __builtin_amdgcn_global_load_lds((const unsigned*)(_gb + (size_t)so0), (unsigned*)((char*)(P) + wv1k), 16, 0, 0); \
;     __builtin_amdgcn_global_load_lds((const unsigned*)(_gb + (size_t)so1), (unsigned*)((char*)(P) + wv1k + 8192), 16, 0, 0); } while (0)
; #define LDA(dst, b, h) _Pragma("unroll") for (int m = 0; m < 4; ++m) _Pragma("unroll") for (int k = 0; k < 2; ++k) \
;     dst[m][k] = *reinterpret_cast<const bf16x8*>((char*)SA(b, h) + lds_byte(wr * 64 + m * 16 + fr, k * 32 + fq * 8))
; #define LDB(dst, b, h) _Pragma("unroll") for (int n = 0; n < 2; ++n) _Pragma("unroll") for (int k = 0; k < 2; ++k) \
;     dst[n][k] = *reinterpret_cast<const bf16x8*>((char*)SB(b, h) + lds_byte(wc * 32 + n * 16 + fr, k * 32 + fq * 8))
; #define MMA(ai, bj, At_, Bt_) do { __builtin_amdgcn_s_setprio(1); \
;     _Pragma("unroll") for (int m = 0; m < 4; ++m) _Pragma("unroll") for (int n = 0; n < 2; ++n) _Pragma("unroll") for (int k = 0; k < 2; ++k) \
;       acc[ai][bj][m][n] = __builtin_amdgcn_mfma_f32_16x16x32_bf16(At_[m][k], Bt_[n][k], acc[ai][bj][m][n], 0, 0, 0); \
;     __builtin_amdgcn_s_setprio(0); } while (0)
; #define WAIT_V(n) asm volatile("s_waitcnt vmcnt(" #n ")" ::: "memory")
; #define WAIT_L(n) asm volatile("s_waitcnt lgkmcnt(" #n ")" ::: "memory")
; #define BAR __builtin_amdgcn_s_barrier()
; #define SCHED __builtin_amdgcn_sched_barrier(0)
; template <class Epi> ...
;     ...
;   for (int t = 0; t < nt - 2; t += 2) {
;     LDB(B0, 0, 0); SCHED; LDA(At, 0, 0); STAGE(SA(1, 1), A, brow + HALF, t + 1);
;     WAIT_L(8); BAR; WAIT_L(0); MMA(0, 0, At, B0); BAR; SCHED;
;     LDB(B1, 0, 1); STAGE(SB(0, 0), Bt, bcol, t + 2);
;     BAR; WAIT_L(0); MMA(0, 1, At, B1); BAR;
;     LDA(At, 0, 1); STAGE(SA(0, 0), A, brow, t + 2);
;     BAR; WAIT_L(0); MMA(1, 0, At, B0); BAR; SCHED;
;     STAGE(SB(0, 1), Bt, bcol + HALF, t + 2);
;     WAIT_V(6); BAR; MMA(1, 1, At, B1); BAR;
.LBB0_115:
	ds_read_b128 v[106:109], v208
	ds_read_b128 v[110:113], v208 offset:1024
	ds_read_b128 v[162:165], v208 offset:2048
	ds_read_b128 v[166:169], v208 offset:3072
	v_lshl_add_u64 v[206:207], v[72:73], 0, s[22:23]
	s_add_i32 s26, s21, 0xc000
	v_lshl_add_u64 v[90:91], v[206:207], 0, s[28:29]
	s_mov_b32 m0, s26
	v_lshl_add_u64 v[224:225], v[66:67], 0, s[22:23]
	s_add_i32 s25, s21, 0xe000
	ds_read_b128 v[170:173], v209
	ds_read_b128 v[174:177], v209 offset:1024
	ds_read_b128 v[178:181], v210
	ds_read_b128 v[182:185], v210 offset:1024
	ds_read_b128 v[186:189], v211
	ds_read_b128 v[190:193], v211 offset:1024
	ds_read_b128 v[194:197], v235
	ds_read_b128 v[198:201], v235 offset:1024
	global_load_lds_dwordx4 v[90:91], off
	v_lshl_add_u64 v[90:91], v[224:225], 0, s[28:29]
	s_mov_b32 m0, s25
	s_nop 0
	global_load_lds_dwordx4 v[90:91], off
	s_waitcnt lgkmcnt(8)
	s_barrier
	s_waitcnt lgkmcnt(0)
	s_waitcnt lgkmcnt(0)
	v_mfma_f32_16x16x32_bf16 v[2:5], v[170:173], v[106:109], v[2:5]
	v_mfma_f32_16x16x32_bf16 v[10:13], v[170:173], v[162:165], v[10:13]
	v_mfma_f32_16x16x32_bf16 v[22:25], v[178:181], v[106:109], v[22:25]
	v_mfma_f32_16x16x32_bf16 v[30:33], v[178:181], v[162:165], v[30:33]
	v_mfma_f32_16x16x32_bf16 v[62:65], v[186:189], v[106:109], v[62:65]
	v_mfma_f32_16x16x32_bf16 v[86:89], v[186:189], v[162:165], v[86:89]
	v_mfma_f32_16x16x32_bf16 v[118:121], v[194:197], v[106:109], v[118:121]
	v_mfma_f32_16x16x32_bf16 v[130:133], v[194:197], v[162:165], v[130:133]
	v_mfma_f32_16x16x32_bf16 v[2:5], v[174:177], v[110:113], v[2:5]
	v_mfma_f32_16x16x32_bf16 v[10:13], v[174:177], v[166:169], v[10:13]
	v_mfma_f32_16x16x32_bf16 v[22:25], v[182:185], v[110:113], v[22:25]
	v_mfma_f32_16x16x32_bf16 v[30:33], v[182:185], v[166:169], v[30:33]
	v_mfma_f32_16x16x32_bf16 v[62:65], v[190:193], v[110:113], v[62:65]
	v_mfma_f32_16x16x32_bf16 v[86:89], v[190:193], v[166:169], v[86:89]
	v_mfma_f32_16x16x32_bf16 v[118:121], v[198:201], v[110:113], v[118:121]
	v_mfma_f32_16x16x32_bf16 v[130:133], v[198:201], v[166:169], v[130:133]
	s_barrier
	v_lshl_add_u64 v[226:227], v[48:49], 0, s[22:23]
	s_mov_b32 m0, s42
	v_lshl_add_u64 v[90:91], v[226:227], 0, s[0:1]
	v_lshl_add_u64 v[228:229], v[34:35], 0, s[22:23]
	ds_read_b128 v[202:205], v236
	ds_read_b128 v[212:215], v236 offset:1024
	ds_read_b128 v[216:219], v236 offset:2048
	ds_read_b128 v[220:223], v236 offset:3072
	global_load_lds_dwordx4 v[90:91], off
	v_lshl_add_u64 v[90:91], v[228:229], 0, s[0:1]
	s_mov_b32 m0, s43
	s_nop 0
	global_load_lds_dwordx4 v[90:91], off
	s_barrier
	s_waitcnt lgkmcnt(0)
	s_waitcnt lgkmcnt(0)
	v_mfma_f32_16x16x32_bf16 v[6:9], v[170:173], v[202:205], v[6:9]
	v_mfma_f32_16x16x32_bf16 v[14:17], v[170:173], v[216:219], v[14:17]
	v_mfma_f32_16x16x32_bf16 v[18:21], v[178:181], v[202:205], v[18:21]
	v_mfma_f32_16x16x32_bf16 v[26:29], v[178:181], v[216:219], v[26:29]
	v_mfma_f32_16x16x32_bf16 v[58:61], v[186:189], v[202:205], v[58:61]
	v_mfma_f32_16x16x32_bf16 v[82:85], v[186:189], v[216:219], v[82:85]
	v_mfma_f32_16x16x32_bf16 v[114:117], v[194:197], v[202:205], v[114:117]
	v_mfma_f32_16x16x32_bf16 v[126:129], v[194:197], v[216:219], v[126:129]
	v_mfma_f32_16x16x32_bf16 v[6:9], v[174:177], v[212:215], v[6:9]
	v_mfma_f32_16x16x32_bf16 v[14:17], v[174:177], v[220:223], v[14:17]
	v_mfma_f32_16x16x32_bf16 v[18:21], v[182:185], v[212:215], v[18:21]
	v_mfma_f32_16x16x32_bf16 v[26:29], v[182:185], v[220:223], v[26:29]
	v_mfma_f32_16x16x32_bf16 v[58:61], v[190:193], v[212:215], v[58:61]
	v_mfma_f32_16x16x32_bf16 v[82:85], v[190:193], v[220:223], v[82:85]
	v_mfma_f32_16x16x32_bf16 v[114:117], v[198:201], v[212:215], v[114:117]
	v_mfma_f32_16x16x32_bf16 v[126:129], v[198:201], v[220:223], v[126:129]
	s_mov_b32 m0, s21
	v_lshl_add_u64 v[90:91], v[206:207], 0, s[0:1]
	s_barrier
	ds_read_b128 v[170:173], v209 offset:16384
	ds_read_b128 v[174:177], v209 offset:17408
	ds_read_b128 v[178:181], v210 offset:16384
	ds_read_b128 v[182:185], v210 offset:17408
	ds_read_b128 v[186:189], v211 offset:16384
	ds_read_b128 v[190:193], v211 offset:17408
	ds_read_b128 v[194:197], v235 offset:16384
	ds_read_b128 v[198:201], v235 offset:17408
	global_load_lds_dwordx4 v[90:91], off
	v_lshl_add_u64 v[90:91], v[224:225], 0, s[0:1]
	s_mov_b32 m0, s17
	s_nop 0
	global_load_lds_dwordx4 v[90:91], off
	s_barrier
	s_waitcnt lgkmcnt(0)
	s_waitcnt lgkmcnt(0)
	v_mfma_f32_16x16x32_bf16 v[122:125], v[170:173], v[106:109], v[122:125]
	v_mfma_f32_16x16x32_bf16 v[138:141], v[170:173], v[162:165], v[138:141]
	v_mfma_f32_16x16x32_bf16 v[50:53], v[178:181], v[106:109], v[50:53]
	v_mfma_f32_16x16x32_bf16 v[54:57], v[178:181], v[162:165], v[54:57]
	v_mfma_f32_16x16x32_bf16 v[78:81], v[186:189], v[106:109], v[78:81]
	v_mfma_f32_16x16x32_bf16 v[142:145], v[186:189], v[162:165], v[142:145]
	v_mfma_f32_16x16x32_bf16 v[102:105], v[194:197], v[106:109], v[102:105]
	v_mfma_f32_16x16x32_bf16 v[122:125], v[174:177], v[110:113], v[122:125]
	v_mfma_f32_16x16x32_bf16 v[138:141], v[174:177], v[166:169], v[138:141]
	v_mfma_f32_16x16x32_bf16 v[50:53], v[182:185], v[110:113], v[50:53]
	v_mfma_f32_16x16x32_bf16 v[54:57], v[182:185], v[166:169], v[54:57]
	v_mfma_f32_16x16x32_bf16 v[78:81], v[190:193], v[110:113], v[78:81]
	v_mfma_f32_16x16x32_bf16 v[142:145], v[190:193], v[166:169], v[142:145]
	v_mfma_f32_16x16x32_bf16 v[102:105], v[198:201], v[110:113], v[102:105]
	v_mfma_f32_16x16x32_bf16 v[106:109], v[194:197], v[162:165], v[146:149]
	v_mfma_f32_16x16x32_bf16 v[106:109], v[198:201], v[166:169], v[106:109]
	s_barrier
	s_mov_b32 m0, s44
	v_lshl_add_u64 v[90:91], v[226:227], 0, s[56:57]
	global_load_lds_dwordx4 v[90:91], off
	v_lshl_add_u64 v[90:91], v[228:229], 0, s[56:57]
	s_mov_b32 m0, s45
	s_nop 0
	global_load_lds_dwordx4 v[90:91], off
	s_waitcnt vmcnt(6)
	s_barrier
; #define STAGE(P, BASE, br, kt) do { const char* _gb = (const char*)((BASE) + ((long)(br) * K + (long)(kt) * BK)); \
;     __builtin_amdgcn_global_load_lds((const unsigned*)(_gb + (size_t)so0), (unsigned*)((char*)(P) + wv1k), 16, 0, 0); \
;     __builtin_amdgcn_global_load_lds((const unsigned*)(_gb + (size_t)so1), (unsigned*)((char*)(P) + wv1k + 8192), 16, 0, 0); } while (0)
; #define LDA(dst, b, h) _Pragma("unroll") for (int m = 0; m < 4; ++m) _Pragma("unroll") for (int k = 0; k < 2; ++k) \
;     dst[m][k] = *reinterpret_cast<const bf16x8*>((char*)SA(b, h) + lds_byte(wr * 64 + m * 16 + fr, k * 32 + fq * 8))
; #define LDB(dst, b, h) _Pragma("unroll") for (int n = 0; n < 2; ++n) _Pragma("unroll") for (int k = 0; k < 2; ++k) \
;     dst[n][k] = *reinterpret_cast<const bf16x8*>((char*)SB(b, h) + lds_byte(wc * 32 + n * 16 + fr, k * 32 + fq * 8))
; #define MMA(ai, bj, At_, Bt_) do { __builtin_amdgcn_s_setprio(1); \
;     _Pragma("unroll") for (int m = 0; m < 4; ++m) _Pragma("unroll") for (int n = 0; n < 2; ++n) _Pragma("unroll") for (int k = 0; k < 2; ++k) \
;       acc[ai][bj][m][n] = __builtin_amdgcn_mfma_f32_16x16x32_bf16(At_[m][k], Bt_[n][k], acc[ai][bj][m][n], 0, 0, 0); \
;     __builtin_amdgcn_s_setprio(0); } while (0)
; #define WAIT_V(n) asm volatile("s_waitcnt vmcnt(" #n ")" ::: "memory")
; #define WAIT_L(n) asm volatile("s_waitcnt lgkmcnt(" #n ")" ::: "memory")
; #define BAR __builtin_amdgcn_s_barrier()
; #define SCHED __builtin_amdgcn_sched_barrier(0)
; template <class Epi> ...
;     ...
;     WAIT_V(6); BAR; MMA(1, 1, At, B1); BAR;
;     LDB(B0, 1, 0); SCHED; LDA(At, 1, 0); STAGE(SA(0, 1), A, brow + HALF, t + 2);
;     WAIT_L(8); BAR; WAIT_L(0); MMA(0, 0, At, B0); BAR; SCHED;
;     LDB(B1, 1, 1); STAGE(SB(1, 0), Bt, bcol, t + 3);
;     BAR; WAIT_L(0); MMA(0, 1, At, B1); BAR;
;     LDA(At, 1, 1); STAGE(SA(1, 0), A, brow, t + 3);
;     BAR; WAIT_L(0); MMA(1, 0, At, B0); BAR; SCHED;
	v_mfma_f32_16x16x32_bf16 v[36:39], v[170:173], v[216:219], v[36:39]
	v_mfma_f32_16x16x32_bf16 v[40:43], v[178:181], v[202:205], v[40:43]
	v_mfma_f32_16x16x32_bf16 v[44:47], v[178:181], v[216:219], v[44:47]
	v_mfma_f32_16x16x32_bf16 v[74:77], v[186:189], v[202:205], v[74:77]
	v_mfma_f32_16x16x32_bf16 v[68:71], v[186:189], v[216:219], v[68:71]
	v_mfma_f32_16x16x32_bf16 v[96:99], v[194:197], v[202:205], v[98:101]
	v_mfma_f32_16x16x32_bf16 v[90:93], v[194:197], v[216:219], v[92:95]
	v_mfma_f32_16x16x32_bf16 v[110:113], v[170:173], v[202:205], v[134:137]
	v_mfma_f32_16x16x32_bf16 v[36:39], v[174:177], v[220:223], v[36:39]
	v_mfma_f32_16x16x32_bf16 v[40:43], v[182:185], v[212:215], v[40:43]
	v_mfma_f32_16x16x32_bf16 v[44:47], v[182:185], v[220:223], v[44:47]
	v_mfma_f32_16x16x32_bf16 v[74:77], v[190:193], v[212:215], v[74:77]
	v_mfma_f32_16x16x32_bf16 v[68:71], v[190:193], v[220:223], v[68:71]
	v_mfma_f32_16x16x32_bf16 v[96:99], v[198:201], v[212:215], v[96:99]
	v_mfma_f32_16x16x32_bf16 v[90:93], v[198:201], v[220:223], v[90:93]
	v_mfma_f32_16x16x32_bf16 v[110:113], v[174:177], v[212:215], v[110:113]
	s_barrier
	ds_read_b128 v[134:137], v237
	ds_read_b128 v[146:149], v237 offset:1024
	ds_read_b128 v[162:165], v237 offset:2048
	ds_read_b128 v[166:169], v237 offset:3072
	s_mov_b32 m0, s46
	v_lshl_add_u64 v[94:95], v[206:207], 0, s[56:57]
	ds_read_b128 v[170:173], v209 offset:32768
	ds_read_b128 v[174:177], v209 offset:33792
	ds_read_b128 v[178:181], v210 offset:32768
	ds_read_b128 v[182:185], v210 offset:33792
	ds_read_b128 v[186:189], v211 offset:32768
	ds_read_b128 v[190:193], v211 offset:33792
	ds_read_b128 v[194:197], v235 offset:32768
	ds_read_b128 v[198:201], v235 offset:33792
	global_load_lds_dwordx4 v[94:95], off
	v_lshl_add_u64 v[94:95], v[224:225], 0, s[56:57]
	s_mov_b32 m0, s47
	s_nop 0
	global_load_lds_dwordx4 v[94:95], off
	s_waitcnt lgkmcnt(8)
	s_barrier
	s_waitcnt lgkmcnt(0)
	s_waitcnt lgkmcnt(0)
	v_mfma_f32_16x16x32_bf16 v[2:5], v[170:173], v[134:137], v[2:5]
	v_mfma_f32_16x16x32_bf16 v[10:13], v[170:173], v[162:165], v[10:13]
	v_mfma_f32_16x16x32_bf16 v[22:25], v[178:181], v[134:137], v[22:25]
	v_mfma_f32_16x16x32_bf16 v[30:33], v[178:181], v[162:165], v[30:33]
	v_mfma_f32_16x16x32_bf16 v[62:65], v[186:189], v[134:137], v[62:65]
	v_mfma_f32_16x16x32_bf16 v[86:89], v[186:189], v[162:165], v[86:89]
	v_mfma_f32_16x16x32_bf16 v[118:121], v[194:197], v[134:137], v[118:121]
	v_mfma_f32_16x16x32_bf16 v[130:133], v[194:197], v[162:165], v[130:133]
	v_mfma_f32_16x16x32_bf16 v[2:5], v[174:177], v[146:149], v[2:5]
	v_mfma_f32_16x16x32_bf16 v[10:13], v[174:177], v[166:169], v[10:13]
	v_mfma_f32_16x16x32_bf16 v[22:25], v[182:185], v[146:149], v[22:25]
	v_mfma_f32_16x16x32_bf16 v[30:33], v[182:185], v[166:169], v[30:33]
	v_mfma_f32_16x16x32_bf16 v[62:65], v[190:193], v[146:149], v[62:65]
	v_mfma_f32_16x16x32_bf16 v[86:89], v[190:193], v[166:169], v[86:89]
	v_mfma_f32_16x16x32_bf16 v[118:121], v[198:201], v[146:149], v[118:121]
	v_mfma_f32_16x16x32_bf16 v[130:133], v[198:201], v[166:169], v[130:133]
	s_barrier
	s_mov_b32 m0, s30
	v_lshl_add_u64 v[94:95], v[226:227], 0, s[90:91]
	ds_read_b128 v[202:205], v238
	ds_read_b128 v[212:215], v238 offset:1024
	ds_read_b128 v[216:219], v238 offset:2048
	ds_read_b128 v[220:223], v238 offset:3072
	global_load_lds_dwordx4 v[94:95], off
	v_lshl_add_u64 v[94:95], v[228:229], 0, s[90:91]
	s_mov_b32 m0, s31
	s_nop 0
	global_load_lds_dwordx4 v[94:95], off
	s_barrier
	s_waitcnt lgkmcnt(0)
	s_waitcnt lgkmcnt(0)
	v_mfma_f32_16x16x32_bf16 v[6:9], v[170:173], v[202:205], v[6:9]
	v_mfma_f32_16x16x32_bf16 v[14:17], v[170:173], v[216:219], v[14:17]
	v_mfma_f32_16x16x32_bf16 v[18:21], v[178:181], v[202:205], v[18:21]
	v_mfma_f32_16x16x32_bf16 v[26:29], v[178:181], v[216:219], v[26:29]
	v_mfma_f32_16x16x32_bf16 v[58:61], v[186:189], v[202:205], v[58:61]
	v_mfma_f32_16x16x32_bf16 v[82:85], v[186:189], v[216:219], v[82:85]
	v_mfma_f32_16x16x32_bf16 v[114:117], v[194:197], v[202:205], v[114:117]
	v_mfma_f32_16x16x32_bf16 v[126:129], v[194:197], v[216:219], v[126:129]
	v_mfma_f32_16x16x32_bf16 v[6:9], v[174:177], v[212:215], v[6:9]
	v_mfma_f32_16x16x32_bf16 v[14:17], v[174:177], v[220:223], v[14:17]
	v_mfma_f32_16x16x32_bf16 v[18:21], v[182:185], v[212:215], v[18:21]
	v_mfma_f32_16x16x32_bf16 v[26:29], v[182:185], v[220:223], v[26:29]
	v_mfma_f32_16x16x32_bf16 v[58:61], v[190:193], v[212:215], v[58:61]
	v_mfma_f32_16x16x32_bf16 v[82:85], v[190:193], v[220:223], v[82:85]
	v_mfma_f32_16x16x32_bf16 v[114:117], v[198:201], v[212:215], v[114:117]
	v_mfma_f32_16x16x32_bf16 v[126:129], v[198:201], v[220:223], v[126:129]
	s_mov_b32 m0, s51
	v_lshl_add_u64 v[94:95], v[206:207], 0, s[90:91]
	s_barrier
	ds_read_b128 v[170:173], v209 offset:49152
	ds_read_b128 v[174:177], v209 offset:50176
	ds_read_b128 v[178:181], v210 offset:49152
	ds_read_b128 v[182:185], v210 offset:50176
	ds_read_b128 v[186:189], v211 offset:49152
	ds_read_b128 v[190:193], v211 offset:50176
	ds_read_b128 v[194:197], v235 offset:49152
	ds_read_b128 v[198:201], v235 offset:50176
	global_load_lds_dwordx4 v[94:95], off
	v_lshl_add_u64 v[94:95], v[224:225], 0, s[90:91]
	s_mov_b32 m0, s52
	s_nop 0
	global_load_lds_dwordx4 v[94:95], off
	s_barrier
; #define STAGE(P, BASE, br, kt) do { const char* _gb = (const char*)((BASE) + ((long)(br) * K + (long)(kt) * BK)); \
;     __builtin_amdgcn_global_load_lds((const unsigned*)(_gb + (size_t)so0), (unsigned*)((char*)(P) + wv1k), 16, 0, 0); \
;     __builtin_amdgcn_global_load_lds((const unsigned*)(_gb + (size_t)so1), (unsigned*)((char*)(P) + wv1k + 8192), 16, 0, 0); } while (0)
; #define LDA(dst, b, h) _Pragma("unroll") for (int m = 0; m < 4; ++m) _Pragma("unroll") for (int k = 0; k < 2; ++k) \
;     dst[m][k] = *reinterpret_cast<const bf16x8*>((char*)SA(b, h) + lds_byte(wr * 64 + m * 16 + fr, k * 32 + fq * 8))
; #define LDB(dst, b, h) _Pragma("unroll") for (int n = 0; n < 2; ++n) _Pragma("unroll") for (int k = 0; k < 2; ++k) \
;     dst[n][k] = *reinterpret_cast<const bf16x8*>((char*)SB(b, h) + lds_byte(wc * 32 + n * 16 + fr, k * 32 + fq * 8))
; #define MMA(ai, bj, At_, Bt_) do { __builtin_amdgcn_s_setprio(1); \
;     _Pragma("unroll") for (int m = 0; m < 4; ++m) _Pragma("unroll") for (int n = 0; n < 2; ++n) _Pragma("unroll") for (int k = 0; k < 2; ++k) \
;       acc[ai][bj][m][n] = __builtin_amdgcn_mfma_f32_16x16x32_bf16(At_[m][k], Bt_[n][k], acc[ai][bj][m][n], 0, 0, 0); \
;     __builtin_amdgcn_s_setprio(0); } while (0)
; #define WAIT_V(n) asm volatile("s_waitcnt vmcnt(" #n ")" ::: "memory")
; #define WAIT_L(n) asm volatile("s_waitcnt lgkmcnt(" #n ")" ::: "memory")
; #define BAR __builtin_amdgcn_s_barrier()
; #define SCHED __builtin_amdgcn_sched_barrier(0)
; template <class Epi> ...
;     ...
;     BAR; WAIT_L(0); MMA(1, 0, At, B0); BAR; SCHED;
;     STAGE(SB(1, 1), Bt, bcol + HALF, t + 3);
;     WAIT_V(6); BAR; MMA(1, 1, At, B1); BAR;
;   }
;   { LDB(B0, 0, 0); LDA(At, 0, 0); STAGE(SA(1, 1), A, brow + HALF, nt - 1);
;     BAR; WAIT_L(0); MMA(0, 0, At, B0); BAR;
;     LDB(B1, 0, 1); BAR; WAIT_L(0); MMA(0, 1, At, B1); BAR;
;     LDA(At, 0, 1); WAIT_V(4); BAR; WAIT_L(0); MMA(1, 0, At, B0); MMA(1, 1, At, B1); BAR; }
	s_waitcnt lgkmcnt(0)
	s_waitcnt lgkmcnt(0)
	v_mfma_f32_16x16x32_bf16 v[122:125], v[170:173], v[134:137], v[122:125]
	v_mfma_f32_16x16x32_bf16 v[138:141], v[170:173], v[162:165], v[138:141]
	v_mfma_f32_16x16x32_bf16 v[50:53], v[178:181], v[134:137], v[50:53]
	v_mfma_f32_16x16x32_bf16 v[54:57], v[178:181], v[162:165], v[54:57]
	v_mfma_f32_16x16x32_bf16 v[78:81], v[186:189], v[134:137], v[78:81]
	v_mfma_f32_16x16x32_bf16 v[142:145], v[186:189], v[162:165], v[142:145]
	v_mfma_f32_16x16x32_bf16 v[100:103], v[194:197], v[134:137], v[102:105]
	v_mfma_f32_16x16x32_bf16 v[106:109], v[194:197], v[162:165], v[106:109]
	v_mfma_f32_16x16x32_bf16 v[122:125], v[174:177], v[146:149], v[122:125]
	v_mfma_f32_16x16x32_bf16 v[138:141], v[174:177], v[166:169], v[138:141]
	v_mfma_f32_16x16x32_bf16 v[50:53], v[182:185], v[146:149], v[50:53]
	v_mfma_f32_16x16x32_bf16 v[54:57], v[182:185], v[166:169], v[54:57]
	v_mfma_f32_16x16x32_bf16 v[78:81], v[190:193], v[146:149], v[78:81]
	v_mfma_f32_16x16x32_bf16 v[142:145], v[190:193], v[166:169], v[142:145]
	v_mfma_f32_16x16x32_bf16 v[102:105], v[198:201], v[146:149], v[100:103]
	v_mfma_f32_16x16x32_bf16 v[146:149], v[198:201], v[166:169], v[106:109]
	s_barrier
	s_mov_b32 m0, s53
	v_lshl_add_u64 v[94:95], v[226:227], 0, s[60:61]
	global_load_lds_dwordx4 v[94:95], off
	v_lshl_add_u64 v[94:95], v[228:229], 0, s[60:61]
	s_mov_b32 m0, s54
	s_nop 0
	global_load_lds_dwordx4 v[94:95], off
	s_waitcnt vmcnt(6)
	s_barrier
	v_mfma_f32_16x16x32_bf16 v[106:109], v[170:173], v[202:205], v[110:113]
	v_mfma_f32_16x16x32_bf16 v[36:39], v[170:173], v[216:219], v[36:39]
	v_mfma_f32_16x16x32_bf16 v[40:43], v[178:181], v[202:205], v[40:43]
	v_mfma_f32_16x16x32_bf16 v[44:47], v[178:181], v[216:219], v[44:47]
	v_mfma_f32_16x16x32_bf16 v[74:77], v[186:189], v[202:205], v[74:77]
	v_mfma_f32_16x16x32_bf16 v[68:71], v[186:189], v[216:219], v[68:71]
	v_mfma_f32_16x16x32_bf16 v[94:97], v[194:197], v[202:205], v[96:99]
	v_mfma_f32_16x16x32_bf16 v[90:93], v[194:197], v[216:219], v[90:93]
	v_mfma_f32_16x16x32_bf16 v[134:137], v[174:177], v[212:215], v[106:109]
	v_mfma_f32_16x16x32_bf16 v[36:39], v[174:177], v[220:223], v[36:39]
	v_mfma_f32_16x16x32_bf16 v[40:43], v[182:185], v[212:215], v[40:43]
	v_mfma_f32_16x16x32_bf16 v[44:47], v[182:185], v[220:223], v[44:47]
	v_mfma_f32_16x16x32_bf16 v[74:77], v[190:193], v[212:215], v[74:77]
	v_mfma_f32_16x16x32_bf16 v[68:71], v[190:193], v[220:223], v[68:71]
	v_mfma_f32_16x16x32_bf16 v[98:101], v[198:201], v[212:215], v[94:97]
	v_mfma_f32_16x16x32_bf16 v[92:95], v[198:201], v[220:223], v[90:93]
	s_add_i32 s24, s24, 2
	s_add_u32 s22, s22, 0x100
	s_addc_u32 s23, s23, 0
	s_cmp_lt_u32 s24, 12
	s_barrier
	s_cbranch_scc1 .LBB0_115
	s_mov_b64 s[22:23], 0x780
	s_mov_b32 m0, s26
	v_lshl_add_u64 v[34:35], v[158:159], 0, s[22:23]
	ds_read_b128 v[106:109], v208
	ds_read_b128 v[110:113], v208 offset:1024
	ds_read_b128 v[162:165], v208 offset:2048
	ds_read_b128 v[166:169], v208 offset:3072
	ds_read_b128 v[170:173], v209
	ds_read_b128 v[174:177], v209 offset:1024
	ds_read_b128 v[178:181], v210
	ds_read_b128 v[182:185], v210 offset:1024
	ds_read_b128 v[186:189], v211
	ds_read_b128 v[190:193], v211 offset:1024
	ds_read_b128 v[194:197], v235
	ds_read_b128 v[198:201], v235 offset:1024
	global_load_lds_dwordx4 v[34:35], off
	v_lshl_add_u64 v[34:35], v[160:161], 0, s[22:23]
	s_mov_b32 m0, s25
	s_nop 0
	global_load_lds_dwordx4 v[34:35], off
	s_barrier
	s_waitcnt lgkmcnt(0)
	s_waitcnt lgkmcnt(0)
	v_mfma_f32_16x16x32_bf16 v[2:5], v[170:173], v[106:109], v[2:5]
	v_mfma_f32_16x16x32_bf16 v[10:13], v[170:173], v[162:165], v[10:13]
	v_mfma_f32_16x16x32_bf16 v[22:25], v[178:181], v[106:109], v[22:25]
	v_mfma_f32_16x16x32_bf16 v[30:33], v[178:181], v[162:165], v[30:33]
	v_mfma_f32_16x16x32_bf16 v[62:65], v[186:189], v[106:109], v[62:65]
	v_mfma_f32_16x16x32_bf16 v[86:89], v[186:189], v[162:165], v[86:89]
	v_mfma_f32_16x16x32_bf16 v[118:121], v[194:197], v[106:109], v[118:121]
	v_mfma_f32_16x16x32_bf16 v[2:5], v[174:177], v[110:113], v[2:5]
	v_mfma_f32_16x16x32_bf16 v[10:13], v[174:177], v[166:169], v[10:13]
	v_mfma_f32_16x16x32_bf16 v[22:25], v[182:185], v[110:113], v[22:25]
	v_mfma_f32_16x16x32_bf16 v[30:33], v[182:185], v[166:169], v[30:33]
	v_mfma_f32_16x16x32_bf16 v[62:65], v[190:193], v[110:113], v[62:65]
	v_mfma_f32_16x16x32_bf16 v[86:89], v[190:193], v[166:169], v[86:89]
	v_mfma_f32_16x16x32_bf16 v[158:161], v[198:201], v[110:113], v[118:121]
	v_mfma_f32_16x16x32_bf16 v[118:121], v[194:197], v[162:165], v[130:133]
	v_mfma_f32_16x16x32_bf16 v[130:133], v[198:201], v[166:169], v[118:121]
	s_barrier
	s_nop 4
	ds_read_b128 v[118:121], v236
	ds_read_b128 v[202:205], v236 offset:1024
	ds_read_b128 v[212:215], v236 offset:2048
	ds_read_b128 v[216:219], v236 offset:3072
	s_barrier
	s_waitcnt lgkmcnt(0)
	s_waitcnt lgkmcnt(0)
	v_mfma_f32_16x16x32_bf16 v[58:61], v[186:189], v[118:121], v[58:61]
	v_mfma_f32_16x16x32_bf16 v[6:9], v[170:173], v[118:121], v[6:9]
	v_mfma_f32_16x16x32_bf16 v[14:17], v[170:173], v[212:215], v[14:17]
	v_mfma_f32_16x16x32_bf16 v[170:173], v[190:193], v[202:205], v[58:61]
	v_mfma_f32_16x16x32_bf16 v[58:61], v[186:189], v[212:215], v[82:85]
	v_mfma_f32_16x16x32_bf16 v[6:9], v[174:177], v[202:205], v[6:9]
	v_mfma_f32_16x16x32_bf16 v[14:17], v[174:177], v[216:219], v[14:17]
	v_mfma_f32_16x16x32_bf16 v[18:21], v[178:181], v[118:121], v[18:21]
	v_mfma_f32_16x16x32_bf16 v[26:29], v[178:181], v[212:215], v[26:29]
	v_mfma_f32_16x16x32_bf16 v[174:177], v[190:193], v[216:219], v[58:61]
	v_mfma_f32_16x16x32_bf16 v[58:61], v[194:197], v[118:121], v[114:117]
	v_mfma_f32_16x16x32_bf16 v[18:21], v[182:185], v[202:205], v[18:21]
	v_mfma_f32_16x16x32_bf16 v[26:29], v[182:185], v[216:219], v[26:29]
	v_mfma_f32_16x16x32_bf16 v[178:181], v[198:201], v[202:205], v[58:61]
	v_mfma_f32_16x16x32_bf16 v[58:61], v[194:197], v[212:215], v[126:129]
	v_mfma_f32_16x16x32_bf16 v[182:185], v[198:201], v[216:219], v[58:61]
	s_barrier
; #define LDA(dst, b, h) _Pragma("unroll") for (int m = 0; m < 4; ++m) _Pragma("unroll") for (int k = 0; k < 2; ++k) \
;     dst[m][k] = *reinterpret_cast<const bf16x8*>((char*)SA(b, h) + lds_byte(wr * 64 + m * 16 + fr, k * 32 + fq * 8))
; #define LDB(dst, b, h) _Pragma("unroll") for (int n = 0; n < 2; ++n) _Pragma("unroll") for (int k = 0; k < 2; ++k) \
;     dst[n][k] = *reinterpret_cast<const bf16x8*>((char*)SB(b, h) + lds_byte(wc * 32 + n * 16 + fr, k * 32 + fq * 8))
; #define MMA(ai, bj, At_, Bt_) do { __builtin_amdgcn_s_setprio(1); \
;     _Pragma("unroll") for (int m = 0; m < 4; ++m) _Pragma("unroll") for (int n = 0; n < 2; ++n) _Pragma("unroll") for (int k = 0; k < 2; ++k) \
;       acc[ai][bj][m][n] = __builtin_amdgcn_mfma_f32_16x16x32_bf16(At_[m][k], Bt_[n][k], acc[ai][bj][m][n], 0, 0, 0); \
;     __builtin_amdgcn_s_setprio(0); } while (0)
; #define WAIT_V(n) asm volatile("s_waitcnt vmcnt(" #n ")" ::: "memory")
; #define WAIT_L(n) asm volatile("s_waitcnt lgkmcnt(" #n ")" ::: "memory")
; #define BAR __builtin_amdgcn_s_barrier()
; template <class Epi> ...
;     ...
;     LDA(At, 0, 1); WAIT_V(4); BAR; WAIT_L(0); MMA(1, 0, At, B0); MMA(1, 1, At, B1); BAR; }
;   { LDB(B0, 1, 0); LDA(At, 1, 0); WAIT_V(2); BAR; WAIT_L(0); MMA(0, 0, At, B0); BAR;
	s_nop 4
	ds_read_b128 v[58:61], v209 offset:16384
	ds_read_b128 v[82:85], v209 offset:17408
	ds_read_b128 v[114:117], v210 offset:16384
	ds_read_b128 v[126:129], v210 offset:17408
	ds_read_b128 v[186:189], v211 offset:16384
	ds_read_b128 v[190:193], v211 offset:17408
	ds_read_b128 v[194:197], v235 offset:16384
	ds_read_b128 v[198:201], v235 offset:17408
	s_waitcnt vmcnt(4)
	s_barrier
	s_waitcnt lgkmcnt(0)
	s_waitcnt lgkmcnt(0)
	v_mfma_f32_16x16x32_bf16 v[48:51], v[114:117], v[106:109], v[50:53]
	v_mfma_f32_16x16x32_bf16 v[224:227], v[126:129], v[110:113], v[48:51]
	v_mfma_f32_16x16x32_bf16 v[48:51], v[114:117], v[162:165], v[54:57]
	v_mfma_f32_16x16x32_bf16 v[228:231], v[126:129], v[166:169], v[48:51]
	v_mfma_f32_16x16x32_bf16 v[48:51], v[186:189], v[106:109], v[78:81]
	v_mfma_f32_16x16x32_bf16 v[240:243], v[190:193], v[110:113], v[48:51]
	v_mfma_f32_16x16x32_bf16 v[48:51], v[186:189], v[162:165], v[142:145]
	v_mfma_f32_16x16x32_bf16 v[122:125], v[58:61], v[106:109], v[122:125]
	v_mfma_f32_16x16x32_bf16 v[142:145], v[190:193], v[166:169], v[48:51]
	v_mfma_f32_16x16x32_bf16 v[48:51], v[194:197], v[106:109], v[102:105]
	v_mfma_f32_16x16x32_bf16 v[220:223], v[82:85], v[110:113], v[122:125]
	v_mfma_f32_16x16x32_bf16 v[122:125], v[58:61], v[162:165], v[138:141]
	v_mfma_f32_16x16x32_bf16 v[244:247], v[198:201], v[110:113], v[48:51]
	v_mfma_f32_16x16x32_bf16 v[48:51], v[194:197], v[162:165], v[146:149]
	v_mfma_f32_16x16x32_bf16 v[138:141], v[82:85], v[166:169], v[122:125]
	v_mfma_f32_16x16x32_bf16 v[146:149], v[198:201], v[166:169], v[48:51]
	v_mfma_f32_16x16x32_bf16 v[34:37], v[58:61], v[212:215], v[36:39]
	v_mfma_f32_16x16x32_bf16 v[162:165], v[82:85], v[216:219], v[34:37]
	v_mfma_f32_16x16x32_bf16 v[34:37], v[114:117], v[118:121], v[40:43]
	v_mfma_f32_16x16x32_bf16 v[48:51], v[58:61], v[118:121], v[134:137]
	v_mfma_f32_16x16x32_bf16 v[166:169], v[126:129], v[202:205], v[34:37]
	v_mfma_f32_16x16x32_bf16 v[34:37], v[114:117], v[212:215], v[44:47]
	v_mfma_f32_16x16x32_bf16 v[134:137], v[82:85], v[202:205], v[48:51]
	v_mfma_f32_16x16x32_bf16 v[46:49], v[126:129], v[216:219], v[34:37]
	v_mfma_f32_16x16x32_bf16 v[34:37], v[186:189], v[118:121], v[74:77]
	v_mfma_f32_16x16x32_bf16 v[248:251], v[190:193], v[202:205], v[34:37]
	v_mfma_f32_16x16x32_bf16 v[34:37], v[186:189], v[212:215], v[68:71]
	v_mfma_f32_16x16x32_bf16 v[186:189], v[190:193], v[216:219], v[34:37]
	v_mfma_f32_16x16x32_bf16 v[34:37], v[194:197], v[118:121], v[98:101]
	v_mfma_f32_16x16x32_bf16 v[190:193], v[198:201], v[202:205], v[34:37]
	v_mfma_f32_16x16x32_bf16 v[34:37], v[194:197], v[212:215], v[92:95]
	v_mfma_f32_16x16x32_bf16 v[194:197], v[198:201], v[216:219], v[34:37]
	s_barrier
	ds_read_b128 v[42:45], v237
	ds_read_b128 v[66:69], v237 offset:1024
	ds_read_b128 v[70:73], v237 offset:2048
	ds_read_b128 v[198:201], v237 offset:3072
	s_nop 0
	ds_read_b128 v[34:37], v209 offset:32768
	ds_read_b128 v[38:41], v209 offset:33792
	ds_read_b128 v[50:53], v210 offset:32768
	ds_read_b128 v[54:57], v210 offset:33792
	ds_read_b128 v[74:77], v211 offset:32768
	ds_read_b128 v[78:81], v211 offset:33792
	ds_read_b128 v[202:205], v235 offset:32768
	ds_read_b128 v[212:215], v235 offset:33792
	s_waitcnt vmcnt(2)
	s_barrier
	s_waitcnt lgkmcnt(0)
	s_waitcnt lgkmcnt(0)
	v_mfma_f32_16x16x32_bf16 v[2:5], v[34:37], v[42:45], v[2:5]
	v_mfma_f32_16x16x32_bf16 v[114:117], v[38:41], v[66:69], v[2:5]
	v_mfma_f32_16x16x32_bf16 v[2:5], v[34:37], v[70:73], v[10:13]
	v_mfma_f32_16x16x32_bf16 v[118:121], v[38:41], v[198:201], v[2:5]
	v_mfma_f32_16x16x32_bf16 v[2:5], v[50:53], v[42:45], v[22:25]
	v_mfma_f32_16x16x32_bf16 v[98:101], v[54:57], v[66:69], v[2:5]
	v_mfma_f32_16x16x32_bf16 v[2:5], v[50:53], v[70:73], v[30:33]
	v_mfma_f32_16x16x32_bf16 v[102:105], v[54:57], v[198:201], v[2:5]
	v_mfma_f32_16x16x32_bf16 v[2:5], v[74:77], v[42:45], v[62:65]
	v_mfma_f32_16x16x32_bf16 v[82:85], v[78:81], v[66:69], v[2:5]
	v_mfma_f32_16x16x32_bf16 v[2:5], v[74:77], v[70:73], v[86:89]
	v_mfma_f32_16x16x32_bf16 v[86:89], v[78:81], v[198:201], v[2:5]
	v_mfma_f32_16x16x32_bf16 v[2:5], v[202:205], v[42:45], v[158:161]
	v_mfma_f32_16x16x32_bf16 v[58:61], v[212:215], v[66:69], v[2:5]
	v_mfma_f32_16x16x32_bf16 v[2:5], v[202:205], v[70:73], v[130:133]
	v_mfma_f32_16x16x32_bf16 v[62:65], v[212:215], v[198:201], v[2:5]
	s_barrier
; #define LDA(dst, b, h) _Pragma("unroll") for (int m = 0; m < 4; ++m) _Pragma("unroll") for (int k = 0; k < 2; ++k) \
;     dst[m][k] = *reinterpret_cast<const bf16x8*>((char*)SA(b, h) + lds_byte(wr * 64 + m * 16 + fr, k * 32 + fq * 8))
; #define LDB(dst, b, h) _Pragma("unroll") for (int n = 0; n < 2; ++n) _Pragma("unroll") for (int k = 0; k < 2; ++k) \
;     dst[n][k] = *reinterpret_cast<const bf16x8*>((char*)SB(b, h) + lds_byte(wc * 32 + n * 16 + fr, k * 32 + fq * 8))
; #define MMA(ai, bj, At_, Bt_) do { __builtin_amdgcn_s_setprio(1); \
;     _Pragma("unroll") for (int m = 0; m < 4; ++m) _Pragma("unroll") for (int n = 0; n < 2; ++n) _Pragma("unroll") for (int k = 0; k < 2; ++k) \
;       acc[ai][bj][m][n] = __builtin_amdgcn_mfma_f32_16x16x32_bf16(At_[m][k], Bt_[n][k], acc[ai][bj][m][n], 0, 0, 0); \
;     __builtin_amdgcn_s_setprio(0); } while (0)
; #define WAIT_V(n) asm volatile("s_waitcnt vmcnt(" #n ")" ::: "memory")
; #define WAIT_L(n) asm volatile("s_waitcnt lgkmcnt(" #n ")" ::: "memory")
; #define BAR __builtin_amdgcn_s_barrier()
; template <class Epi> ...
;     ...
;   { LDB(B0, 1, 0); LDA(At, 1, 0); WAIT_V(2); BAR; WAIT_L(0); MMA(0, 0, At, B0); BAR;
;     LDB(B1, 1, 1); WAIT_V(0); BAR; WAIT_L(0); MMA(0, 1, At, B1); BAR;
;     LDA(At, 1, 1); BAR; WAIT_L(0); MMA(1, 0, At, B0); MMA(1, 1, At, B1); BAR; }
;   if (wr == 0) BAR;
	ds_read_b128 v[10:13], v238
	ds_read_b128 v[130:133], v238 offset:1024
	ds_read_b128 v[158:161], v238 offset:2048
	ds_read_b128 v[216:219], v238 offset:3072
	s_waitcnt vmcnt(0)
	s_barrier
	s_waitcnt lgkmcnt(0)
	s_waitcnt lgkmcnt(0)
	v_mfma_f32_16x16x32_bf16 v[2:5], v[34:37], v[10:13], v[6:9]
	v_mfma_f32_16x16x32_bf16 v[122:125], v[38:41], v[130:133], v[2:5]
	v_mfma_f32_16x16x32_bf16 v[2:5], v[34:37], v[158:161], v[14:17]
	v_mfma_f32_16x16x32_bf16 v[126:129], v[38:41], v[216:219], v[2:5]
	v_mfma_f32_16x16x32_bf16 v[2:5], v[50:53], v[10:13], v[18:21]
	v_mfma_f32_16x16x32_bf16 v[106:109], v[54:57], v[130:133], v[2:5]
	v_mfma_f32_16x16x32_bf16 v[2:5], v[50:53], v[158:161], v[26:29]
	v_mfma_f32_16x16x32_bf16 v[110:113], v[54:57], v[216:219], v[2:5]
	v_mfma_f32_16x16x32_bf16 v[2:5], v[74:77], v[10:13], v[170:173]
	v_mfma_f32_16x16x32_bf16 v[90:93], v[78:81], v[130:133], v[2:5]
	v_mfma_f32_16x16x32_bf16 v[2:5], v[74:77], v[158:161], v[174:177]
	v_mfma_f32_16x16x32_bf16 v[94:97], v[78:81], v[216:219], v[2:5]
	v_mfma_f32_16x16x32_bf16 v[2:5], v[202:205], v[10:13], v[178:181]
	v_mfma_f32_16x16x32_bf16 v[74:77], v[212:215], v[130:133], v[2:5]
	v_mfma_f32_16x16x32_bf16 v[2:5], v[202:205], v[158:161], v[182:185]
	v_mfma_f32_16x16x32_bf16 v[78:81], v[212:215], v[216:219], v[2:5]
	s_barrier
	ds_read_b128 v[14:17], v209 offset:49152
	ds_read_b128 v[26:29], v209 offset:50176
	ds_read_b128 v[30:33], v210 offset:49152
	ds_read_b128 v[170:173], v210 offset:50176
	ds_read_b128 v[174:177], v211 offset:49152
	ds_read_b128 v[178:181], v211 offset:50176
	ds_read_b128 v[182:185], v235 offset:49152
	ds_read_b128 v[202:205], v235 offset:50176
	s_barrier
	s_waitcnt lgkmcnt(0)
	s_waitcnt lgkmcnt(0)
	v_mfma_f32_16x16x32_bf16 v[2:5], v[14:17], v[42:45], v[220:223]
	v_mfma_f32_16x16x32_bf16 v[50:53], v[26:29], v[66:69], v[2:5]
	v_mfma_f32_16x16x32_bf16 v[2:5], v[14:17], v[70:73], v[138:141]
	v_mfma_f32_16x16x32_bf16 v[54:57], v[26:29], v[198:201], v[2:5]
	v_mfma_f32_16x16x32_bf16 v[2:5], v[30:33], v[42:45], v[224:227]
	v_mfma_f32_16x16x32_bf16 v[34:37], v[170:173], v[66:69], v[2:5]
	v_mfma_f32_16x16x32_bf16 v[2:5], v[30:33], v[70:73], v[228:231]
	v_mfma_f32_16x16x32_bf16 v[38:41], v[170:173], v[198:201], v[2:5]
	v_mfma_f32_16x16x32_bf16 v[2:5], v[174:177], v[42:45], v[240:243]
	v_mfma_f32_16x16x32_bf16 v[18:21], v[178:181], v[66:69], v[2:5]
	v_mfma_f32_16x16x32_bf16 v[2:5], v[174:177], v[70:73], v[142:145]
	v_mfma_f32_16x16x32_bf16 v[22:25], v[178:181], v[198:201], v[2:5]
	v_mfma_f32_16x16x32_bf16 v[2:5], v[182:185], v[42:45], v[244:247]
	v_mfma_f32_16x16x32_bf16 v[6:9], v[182:185], v[70:73], v[146:149]
	v_mfma_f32_16x16x32_bf16 v[2:5], v[202:205], v[66:69], v[2:5]
	v_mfma_f32_16x16x32_bf16 v[6:9], v[202:205], v[198:201], v[6:9]
	v_mfma_f32_16x16x32_bf16 v[42:45], v[14:17], v[10:13], v[134:137]
	v_mfma_f32_16x16x32_bf16 v[14:17], v[14:17], v[158:161], v[162:165]
	v_mfma_f32_16x16x32_bf16 v[70:73], v[26:29], v[216:219], v[14:17]
	v_mfma_f32_16x16x32_bf16 v[14:17], v[30:33], v[10:13], v[166:169]
	v_mfma_f32_16x16x32_bf16 v[66:69], v[26:29], v[130:133], v[42:45]
	v_mfma_f32_16x16x32_bf16 v[42:45], v[170:173], v[130:133], v[14:17]
	v_mfma_f32_16x16x32_bf16 v[14:17], v[30:33], v[158:161], v[46:49]
	v_mfma_f32_16x16x32_bf16 v[46:49], v[170:173], v[216:219], v[14:17]
	v_mfma_f32_16x16x32_bf16 v[14:17], v[174:177], v[10:13], v[248:251]
	v_mfma_f32_16x16x32_bf16 v[26:29], v[178:181], v[130:133], v[14:17]
	v_mfma_f32_16x16x32_bf16 v[14:17], v[174:177], v[158:161], v[186:189]
	v_mfma_f32_16x16x32_bf16 v[30:33], v[178:181], v[216:219], v[14:17]
	v_mfma_f32_16x16x32_bf16 v[10:13], v[182:185], v[10:13], v[190:193]
	v_mfma_f32_16x16x32_bf16 v[14:17], v[182:185], v[158:161], v[194:197]
	v_mfma_f32_16x16x32_bf16 v[10:13], v[202:205], v[130:133], v[10:13]
	v_mfma_f32_16x16x32_bf16 v[14:17], v[202:205], v[216:219], v[14:17]
	s_barrier
	s_and_saveexec_b64 s[22:23], s[6:7]
	s_cbranch_execz .LBB0_111
	s_barrier
	s_branch .LBB0_111

; #define STAGE(P, BASE, br, kt) do { const char* _gb = (const char*)((BASE) + ((long)(br) * K + (long)(kt) * BK)); \
;     __builtin_amdgcn_global_load_lds((const unsigned*)(_gb + (size_t)so0), (unsigned*)((char*)(P) + wv1k), 16, 0, 0); \
;     __builtin_amdgcn_global_load_lds((const unsigned*)(_gb + (size_t)so1), (unsigned*)((char*)(P) + wv1k + 8192), 16, 0, 0); } while (0)
; #define LDA(dst, b, h) _Pragma("unroll") for (int m = 0; m < 4; ++m) _Pragma("unroll") for (int k = 0; k < 2; ++k) \
;     dst[m][k] = *reinterpret_cast<const bf16x8*>((char*)SA(b, h) + lds_byte(wr * 64 + m * 16 + fr, k * 32 + fq * 8))
; #define LDB(dst, b, h) _Pragma("unroll") for (int n = 0; n < 2; ++n) _Pragma("unroll") for (int k = 0; k < 2; ++k) \
;     dst[n][k] = *reinterpret_cast<const bf16x8*>((char*)SB(b, h) + lds_byte(wc * 32 + n * 16 + fr, k * 32 + fq * 8))
; #define MMA(ai, bj, At_, Bt_) do { __builtin_amdgcn_s_setprio(1); \
;     _Pragma("unroll") for (int m = 0; m < 4; ++m) _Pragma("unroll") for (int n = 0; n < 2; ++n) _Pragma("unroll") for (int k = 0; k < 2; ++k) \
;       acc[ai][bj][m][n] = __builtin_amdgcn_mfma_f32_16x16x32_bf16(At_[m][k], Bt_[n][k], acc[ai][bj][m][n], 0, 0, 0); \
;     __builtin_amdgcn_s_setprio(0); } while (0)
; #define WAIT_V(n) asm volatile("s_waitcnt vmcnt(" #n ")" ::: "memory")
; #define WAIT_L(n) asm volatile("s_waitcnt lgkmcnt(" #n ")" ::: "memory")
; #define BAR __builtin_amdgcn_s_barrier()
; #define SCHED __builtin_amdgcn_sched_barrier(0)
; template <class Epi> ...
;     ...
;   for (int t = 0; t < nt - 2; t += 2) {
;     LDB(B0, 0, 0); SCHED; LDA(At, 0, 0); STAGE(SA(1, 1), A, brow + HALF, t + 1);
;     WAIT_L(8); BAR; WAIT_L(0); MMA(0, 0, At, B0); BAR; SCHED;
;     LDB(B1, 0, 1); STAGE(SB(0, 0), Bt, bcol, t + 2);
;     BAR; WAIT_L(0); MMA(0, 1, At, B1); BAR;
;     LDA(At, 0, 1); STAGE(SA(0, 0), A, brow, t + 2);
;     BAR; WAIT_L(0); MMA(1, 0, At, B0); BAR; SCHED;
;     STAGE(SB(0, 1), Bt, bcol + HALF, t + 2);
;     WAIT_V(6); BAR; MMA(1, 1, At, B1); BAR;
; DEVINL bool run_phase(int ph, int rep) {
;     ...
;         gemm_tile_acc(acc, which == 0, cx, which ? p.nao : p.y, p.wt[l][which ? 4 : 3], which ? 512 : DM, pm * BM, pn * BM, e, false, nullptr, nullptr, 0, -1, 0);
.LBB0_133:
	ds_read_b128 v[162:165], v154
	ds_read_b128 v[166:169], v154 offset:1024
	ds_read_b128 v[170:173], v154 offset:2048
	ds_read_b128 v[174:177], v154 offset:3072
	v_lshl_add_u64 v[226:227], v[146:147], 0, s[24:25]
	s_add_i32 s30, s21, 0xc000
	v_lshl_add_u64 v[210:211], v[226:227], 0, s[34:35]
	s_mov_b32 m0, s30
	v_lshl_add_u64 v[228:229], v[144:145], 0, s[24:25]
	s_add_i32 s27, s21, 0xe000
	ds_read_b128 v[178:181], v155
	ds_read_b128 v[182:185], v155 offset:1024
	ds_read_b128 v[186:189], v156
	ds_read_b128 v[190:193], v156 offset:1024
	ds_read_b128 v[194:197], v157
	ds_read_b128 v[198:201], v157 offset:1024
	ds_read_b128 v[202:205], v158
	ds_read_b128 v[206:209], v158 offset:1024
	global_load_lds_dwordx4 v[210:211], off
	v_lshl_add_u64 v[210:211], v[228:229], 0, s[34:35]
	s_mov_b32 m0, s27
	s_nop 0
	global_load_lds_dwordx4 v[210:211], off
	s_waitcnt lgkmcnt(8)
	s_barrier
	s_waitcnt lgkmcnt(0)
	s_waitcnt lgkmcnt(0)
	v_mfma_f32_16x16x32_bf16 v[104:107], v[178:181], v[162:165], v[104:107]
	v_mfma_f32_16x16x32_bf16 v[100:103], v[178:181], v[170:173], v[100:103]
	v_mfma_f32_16x16x32_bf16 v[112:115], v[186:189], v[162:165], v[112:115]
	v_mfma_f32_16x16x32_bf16 v[108:111], v[186:189], v[170:173], v[108:111]
	v_mfma_f32_16x16x32_bf16 v[120:123], v[194:197], v[162:165], v[120:123]
	v_mfma_f32_16x16x32_bf16 v[116:119], v[194:197], v[170:173], v[116:119]
	v_mfma_f32_16x16x32_bf16 v[128:131], v[202:205], v[162:165], v[128:131]
	v_mfma_f32_16x16x32_bf16 v[124:127], v[202:205], v[170:173], v[124:127]
	v_mfma_f32_16x16x32_bf16 v[104:107], v[182:185], v[166:169], v[104:107]
	v_mfma_f32_16x16x32_bf16 v[100:103], v[182:185], v[174:177], v[100:103]
	v_mfma_f32_16x16x32_bf16 v[112:115], v[190:193], v[166:169], v[112:115]
	v_mfma_f32_16x16x32_bf16 v[108:111], v[190:193], v[174:177], v[108:111]
	v_mfma_f32_16x16x32_bf16 v[120:123], v[198:201], v[166:169], v[120:123]
	v_mfma_f32_16x16x32_bf16 v[116:119], v[198:201], v[174:177], v[116:119]
	v_mfma_f32_16x16x32_bf16 v[128:131], v[206:209], v[166:169], v[128:131]
	v_mfma_f32_16x16x32_bf16 v[124:127], v[206:209], v[174:177], v[124:127]
	s_barrier
	v_lshl_add_u64 v[230:231], v[142:143], 0, s[24:25]
	s_mov_b32 m0, s55
	v_lshl_add_u64 v[232:233], v[230:231], 0, s[0:1]
	ds_read_b128 v[210:213], v159
	ds_read_b128 v[214:217], v159 offset:1024
	ds_read_b128 v[218:221], v159 offset:2048
	ds_read_b128 v[222:225], v159 offset:3072
	global_load_lds_dwordx4 v[232:233], off
	v_lshl_add_u64 v[232:233], v[140:141], 0, s[24:25]
	v_lshl_add_u64 v[236:237], v[232:233], 0, s[0:1]
	s_mov_b32 m0, s56
	s_add_i32 s26, s26, 2
	global_load_lds_dwordx4 v[236:237], off
	s_barrier
	s_waitcnt lgkmcnt(0)
	s_waitcnt lgkmcnt(0)
	v_mfma_f32_16x16x32_bf16 v[72:75], v[178:181], v[210:213], v[72:75]
	v_mfma_f32_16x16x32_bf16 v[68:71], v[178:181], v[218:221], v[68:71]
	v_mfma_f32_16x16x32_bf16 v[80:83], v[186:189], v[210:213], v[80:83]
	v_mfma_f32_16x16x32_bf16 v[76:79], v[186:189], v[218:221], v[76:79]
	v_mfma_f32_16x16x32_bf16 v[88:91], v[194:197], v[210:213], v[88:91]
	v_mfma_f32_16x16x32_bf16 v[84:87], v[194:197], v[218:221], v[84:87]
	v_mfma_f32_16x16x32_bf16 v[96:99], v[202:205], v[210:213], v[96:99]
	v_mfma_f32_16x16x32_bf16 v[92:95], v[202:205], v[218:221], v[92:95]
	v_mfma_f32_16x16x32_bf16 v[72:75], v[182:185], v[214:217], v[72:75]
	v_mfma_f32_16x16x32_bf16 v[68:71], v[182:185], v[222:225], v[68:71]
	v_mfma_f32_16x16x32_bf16 v[80:83], v[190:193], v[214:217], v[80:83]
	v_mfma_f32_16x16x32_bf16 v[76:79], v[190:193], v[222:225], v[76:79]
	v_mfma_f32_16x16x32_bf16 v[88:91], v[198:201], v[214:217], v[88:91]
	v_mfma_f32_16x16x32_bf16 v[84:87], v[198:201], v[222:225], v[84:87]
	v_mfma_f32_16x16x32_bf16 v[96:99], v[206:209], v[214:217], v[96:99]
	v_mfma_f32_16x16x32_bf16 v[92:95], v[206:209], v[222:225], v[92:95]
	v_lshl_add_u64 v[236:237], v[138:139], 0, s[24:25]
	s_mov_b32 m0, s21
	v_lshl_add_u64 v[238:239], v[236:237], 0, s[0:1]
	s_barrier
	ds_read_b128 v[178:181], v155 offset:16384
	ds_read_b128 v[182:185], v155 offset:17408
	ds_read_b128 v[186:189], v156 offset:16384
	ds_read_b128 v[190:193], v156 offset:17408
	ds_read_b128 v[194:197], v157 offset:16384
	ds_read_b128 v[198:201], v157 offset:17408
	ds_read_b128 v[202:205], v158 offset:16384
	ds_read_b128 v[206:209], v158 offset:17408
	global_load_lds_dwordx4 v[238:239], off
	v_lshl_add_u64 v[238:239], v[136:137], 0, s[24:25]
	v_lshl_add_u64 v[240:241], v[238:239], 0, s[0:1]
	s_mov_b32 m0, s9
	s_nop 0
	global_load_lds_dwordx4 v[240:241], off
	s_barrier
	s_waitcnt lgkmcnt(0)
	s_waitcnt lgkmcnt(0)
	v_mfma_f32_16x16x32_bf16 v[40:43], v[178:181], v[162:165], v[40:43]
	v_mfma_f32_16x16x32_bf16 v[36:39], v[178:181], v[170:173], v[36:39]
	v_mfma_f32_16x16x32_bf16 v[48:51], v[186:189], v[162:165], v[48:51]
	v_mfma_f32_16x16x32_bf16 v[44:47], v[186:189], v[170:173], v[44:47]
	v_mfma_f32_16x16x32_bf16 v[56:59], v[194:197], v[162:165], v[56:59]
	v_mfma_f32_16x16x32_bf16 v[52:55], v[194:197], v[170:173], v[52:55]
	v_mfma_f32_16x16x32_bf16 v[64:67], v[202:205], v[162:165], v[64:67]
	v_mfma_f32_16x16x32_bf16 v[60:63], v[202:205], v[170:173], v[60:63]
	v_mfma_f32_16x16x32_bf16 v[40:43], v[182:185], v[166:169], v[40:43]
	v_mfma_f32_16x16x32_bf16 v[36:39], v[182:185], v[174:177], v[36:39]
	v_mfma_f32_16x16x32_bf16 v[48:51], v[190:193], v[166:169], v[48:51]
	v_mfma_f32_16x16x32_bf16 v[44:47], v[190:193], v[174:177], v[44:47]
	v_mfma_f32_16x16x32_bf16 v[56:59], v[198:201], v[166:169], v[56:59]
	v_mfma_f32_16x16x32_bf16 v[52:55], v[198:201], v[174:177], v[52:55]
	v_mfma_f32_16x16x32_bf16 v[64:67], v[206:209], v[166:169], v[64:67]
	v_mfma_f32_16x16x32_bf16 v[60:63], v[206:209], v[174:177], v[60:63]
	s_barrier
; #define STAGE(P, BASE, br, kt) do { const char* _gb = (const char*)((BASE) + ((long)(br) * K + (long)(kt) * BK)); \
;     __builtin_amdgcn_global_load_lds((const unsigned*)(_gb + (size_t)so0), (unsigned*)((char*)(P) + wv1k), 16, 0, 0); \
;     __builtin_amdgcn_global_load_lds((const unsigned*)(_gb + (size_t)so1), (unsigned*)((char*)(P) + wv1k + 8192), 16, 0, 0); } while (0)
; #define LDA(dst, b, h) _Pragma("unroll") for (int m = 0; m < 4; ++m) _Pragma("unroll") for (int k = 0; k < 2; ++k) \
;     dst[m][k] = *reinterpret_cast<const bf16x8*>((char*)SA(b, h) + lds_byte(wr * 64 + m * 16 + fr, k * 32 + fq * 8))
; #define LDB(dst, b, h) _Pragma("unroll") for (int n = 0; n < 2; ++n) _Pragma("unroll") for (int k = 0; k < 2; ++k) \
;     dst[n][k] = *reinterpret_cast<const bf16x8*>((char*)SB(b, h) + lds_byte(wc * 32 + n * 16 + fr, k * 32 + fq * 8))
; #define MMA(ai, bj, At_, Bt_) do { __builtin_amdgcn_s_setprio(1); \
;     _Pragma("unroll") for (int m = 0; m < 4; ++m) _Pragma("unroll") for (int n = 0; n < 2; ++n) _Pragma("unroll") for (int k = 0; k < 2; ++k) \
;       acc[ai][bj][m][n] = __builtin_amdgcn_mfma_f32_16x16x32_bf16(At_[m][k], Bt_[n][k], acc[ai][bj][m][n], 0, 0, 0); \
;     __builtin_amdgcn_s_setprio(0); } while (0)
; #define WAIT_V(n) asm volatile("s_waitcnt vmcnt(" #n ")" ::: "memory")
; #define WAIT_L(n) asm volatile("s_waitcnt lgkmcnt(" #n ")" ::: "memory")
; #define BAR __builtin_amdgcn_s_barrier()
; #define SCHED __builtin_amdgcn_sched_barrier(0)
; template <class Epi> ...
;     ...
;     WAIT_V(6); BAR; MMA(1, 1, At, B1); BAR;
;     LDB(B0, 1, 0); SCHED; LDA(At, 1, 0); STAGE(SA(0, 1), A, brow + HALF, t + 2);
;     WAIT_L(8); BAR; WAIT_L(0); MMA(0, 0, At, B0); BAR; SCHED;
;     LDB(B1, 1, 1); STAGE(SB(1, 0), Bt, bcol, t + 3);
;     BAR; WAIT_L(0); MMA(0, 1, At, B1); BAR;
;     LDA(At, 1, 1); STAGE(SA(1, 0), A, brow, t + 3);
;     BAR; WAIT_L(0); MMA(1, 0, At, B0); BAR; SCHED;
	v_lshl_add_u64 v[240:241], v[134:135], 0, s[24:25]
	s_mov_b32 m0, s57
	v_lshl_add_u64 v[162:163], v[240:241], 0, s[0:1]
	v_lshl_add_u64 v[242:243], v[132:133], 0, s[24:25]
	global_load_lds_dwordx4 v[162:163], off
	v_lshl_add_u64 v[162:163], v[242:243], 0, s[0:1]
	s_mov_b32 m0, s58
	s_nop 0
	global_load_lds_dwordx4 v[162:163], off
	s_waitcnt vmcnt(6)
	s_barrier
	v_mfma_f32_16x16x32_bf16 v[8:11], v[178:181], v[210:213], v[8:11]
	v_mfma_f32_16x16x32_bf16 v[4:7], v[178:181], v[218:221], v[4:7]
	v_mfma_f32_16x16x32_bf16 v[16:19], v[186:189], v[210:213], v[16:19]
	v_mfma_f32_16x16x32_bf16 v[12:15], v[186:189], v[218:221], v[12:15]
	v_mfma_f32_16x16x32_bf16 v[24:27], v[194:197], v[210:213], v[24:27]
	v_mfma_f32_16x16x32_bf16 v[20:23], v[194:197], v[218:221], v[20:23]
	v_mfma_f32_16x16x32_bf16 v[32:35], v[202:205], v[210:213], v[32:35]
	v_mfma_f32_16x16x32_bf16 v[28:31], v[202:205], v[218:221], v[28:31]
	v_mfma_f32_16x16x32_bf16 v[8:11], v[182:185], v[214:217], v[8:11]
	v_mfma_f32_16x16x32_bf16 v[4:7], v[182:185], v[222:225], v[4:7]
	v_mfma_f32_16x16x32_bf16 v[16:19], v[190:193], v[214:217], v[16:19]
	v_mfma_f32_16x16x32_bf16 v[12:15], v[190:193], v[222:225], v[12:15]
	v_mfma_f32_16x16x32_bf16 v[24:27], v[198:201], v[214:217], v[24:27]
	v_mfma_f32_16x16x32_bf16 v[20:23], v[198:201], v[222:225], v[20:23]
	v_mfma_f32_16x16x32_bf16 v[32:35], v[206:209], v[214:217], v[32:35]
	v_mfma_f32_16x16x32_bf16 v[28:31], v[206:209], v[222:225], v[28:31]
	s_barrier
	ds_read_b128 v[162:165], v160
	ds_read_b128 v[166:169], v160 offset:1024
	ds_read_b128 v[170:173], v160 offset:2048
	ds_read_b128 v[174:177], v160 offset:3072
	s_mov_b32 m0, s59
	v_lshl_add_u64 v[210:211], v[226:227], 0, s[0:1]
	ds_read_b128 v[178:181], v155 offset:32768
	ds_read_b128 v[182:185], v155 offset:33792
	ds_read_b128 v[186:189], v156 offset:32768
	ds_read_b128 v[190:193], v156 offset:33792
	ds_read_b128 v[194:197], v157 offset:32768
	ds_read_b128 v[198:201], v157 offset:33792
	ds_read_b128 v[202:205], v158 offset:32768
	ds_read_b128 v[206:209], v158 offset:33792
	global_load_lds_dwordx4 v[210:211], off
	v_lshl_add_u64 v[210:211], v[228:229], 0, s[0:1]
	s_mov_b32 m0, s60
	s_nop 0
	global_load_lds_dwordx4 v[210:211], off
	s_waitcnt lgkmcnt(8)
	s_barrier
	s_waitcnt lgkmcnt(0)
	s_waitcnt lgkmcnt(0)
	v_mfma_f32_16x16x32_bf16 v[104:107], v[178:181], v[162:165], v[104:107]
	v_mfma_f32_16x16x32_bf16 v[100:103], v[178:181], v[170:173], v[100:103]
	v_mfma_f32_16x16x32_bf16 v[112:115], v[186:189], v[162:165], v[112:115]
	v_mfma_f32_16x16x32_bf16 v[108:111], v[186:189], v[170:173], v[108:111]
	v_mfma_f32_16x16x32_bf16 v[120:123], v[194:197], v[162:165], v[120:123]
	v_mfma_f32_16x16x32_bf16 v[116:119], v[194:197], v[170:173], v[116:119]
	v_mfma_f32_16x16x32_bf16 v[128:131], v[202:205], v[162:165], v[128:131]
	v_mfma_f32_16x16x32_bf16 v[124:127], v[202:205], v[170:173], v[124:127]
	v_mfma_f32_16x16x32_bf16 v[104:107], v[182:185], v[166:169], v[104:107]
	v_mfma_f32_16x16x32_bf16 v[100:103], v[182:185], v[174:177], v[100:103]
	v_mfma_f32_16x16x32_bf16 v[112:115], v[190:193], v[166:169], v[112:115]
	v_mfma_f32_16x16x32_bf16 v[108:111], v[190:193], v[174:177], v[108:111]
	v_mfma_f32_16x16x32_bf16 v[120:123], v[198:201], v[166:169], v[120:123]
	v_mfma_f32_16x16x32_bf16 v[116:119], v[198:201], v[174:177], v[116:119]
	v_mfma_f32_16x16x32_bf16 v[128:131], v[206:209], v[166:169], v[128:131]
	v_mfma_f32_16x16x32_bf16 v[124:127], v[206:209], v[174:177], v[124:127]
	s_barrier
	s_mov_b32 m0, s29
	v_lshl_add_u64 v[226:227], v[230:231], 0, s[90:91]
	ds_read_b128 v[210:213], v161
	ds_read_b128 v[214:217], v161 offset:1024
	ds_read_b128 v[218:221], v161 offset:2048
	ds_read_b128 v[222:225], v161 offset:3072
	global_load_lds_dwordx4 v[226:227], off
	v_lshl_add_u64 v[226:227], v[232:233], 0, s[90:91]
	s_mov_b32 m0, s40
	s_nop 0
	global_load_lds_dwordx4 v[226:227], off
	s_barrier
	s_waitcnt lgkmcnt(0)
	s_waitcnt lgkmcnt(0)
	v_mfma_f32_16x16x32_bf16 v[72:75], v[178:181], v[210:213], v[72:75]
	v_mfma_f32_16x16x32_bf16 v[68:71], v[178:181], v[218:221], v[68:71]
	v_mfma_f32_16x16x32_bf16 v[80:83], v[186:189], v[210:213], v[80:83]
	v_mfma_f32_16x16x32_bf16 v[76:79], v[186:189], v[218:221], v[76:79]
	v_mfma_f32_16x16x32_bf16 v[88:91], v[194:197], v[210:213], v[88:91]
	v_mfma_f32_16x16x32_bf16 v[84:87], v[194:197], v[218:221], v[84:87]
	v_mfma_f32_16x16x32_bf16 v[96:99], v[202:205], v[210:213], v[96:99]
	v_mfma_f32_16x16x32_bf16 v[92:95], v[202:205], v[218:221], v[92:95]
	v_mfma_f32_16x16x32_bf16 v[72:75], v[182:185], v[214:217], v[72:75]
	v_mfma_f32_16x16x32_bf16 v[68:71], v[182:185], v[222:225], v[68:71]
	v_mfma_f32_16x16x32_bf16 v[80:83], v[190:193], v[214:217], v[80:83]
	v_mfma_f32_16x16x32_bf16 v[76:79], v[190:193], v[222:225], v[76:79]
	v_mfma_f32_16x16x32_bf16 v[88:91], v[198:201], v[214:217], v[88:91]
	v_mfma_f32_16x16x32_bf16 v[84:87], v[198:201], v[222:225], v[84:87]
	v_mfma_f32_16x16x32_bf16 v[96:99], v[206:209], v[214:217], v[96:99]
	v_mfma_f32_16x16x32_bf16 v[92:95], v[206:209], v[222:225], v[92:95]
	s_mov_b32 m0, s41
	v_lshl_add_u64 v[226:227], v[236:237], 0, s[90:91]
	s_barrier
	ds_read_b128 v[178:181], v155 offset:49152
	ds_read_b128 v[182:185], v155 offset:50176
	ds_read_b128 v[186:189], v156 offset:49152
	ds_read_b128 v[190:193], v156 offset:50176
	ds_read_b128 v[194:197], v157 offset:49152
	ds_read_b128 v[198:201], v157 offset:50176
	ds_read_b128 v[202:205], v158 offset:49152
	ds_read_b128 v[206:209], v158 offset:50176
	global_load_lds_dwordx4 v[226:227], off
	v_lshl_add_u64 v[226:227], v[238:239], 0, s[90:91]
	s_mov_b32 m0, s42
	s_nop 0
	global_load_lds_dwordx4 v[226:227], off
	s_barrier
; #define STAGE(P, BASE, br, kt) do { const char* _gb = (const char*)((BASE) + ((long)(br) * K + (long)(kt) * BK)); \
;     __builtin_amdgcn_global_load_lds((const unsigned*)(_gb + (size_t)so0), (unsigned*)((char*)(P) + wv1k), 16, 0, 0); \
;     __builtin_amdgcn_global_load_lds((const unsigned*)(_gb + (size_t)so1), (unsigned*)((char*)(P) + wv1k + 8192), 16, 0, 0); } while (0)
; #define LDA(dst, b, h) _Pragma("unroll") for (int m = 0; m < 4; ++m) _Pragma("unroll") for (int k = 0; k < 2; ++k) \
;     dst[m][k] = *reinterpret_cast<const bf16x8*>((char*)SA(b, h) + lds_byte(wr * 64 + m * 16 + fr, k * 32 + fq * 8))
; #define LDB(dst, b, h) _Pragma("unroll") for (int n = 0; n < 2; ++n) _Pragma("unroll") for (int k = 0; k < 2; ++k) \
;     dst[n][k] = *reinterpret_cast<const bf16x8*>((char*)SB(b, h) + lds_byte(wc * 32 + n * 16 + fr, k * 32 + fq * 8))
; #define MMA(ai, bj, At_, Bt_) do { __builtin_amdgcn_s_setprio(1); \
;     _Pragma("unroll") for (int m = 0; m < 4; ++m) _Pragma("unroll") for (int n = 0; n < 2; ++n) _Pragma("unroll") for (int k = 0; k < 2; ++k) \
;       acc[ai][bj][m][n] = __builtin_amdgcn_mfma_f32_16x16x32_bf16(At_[m][k], Bt_[n][k], acc[ai][bj][m][n], 0, 0, 0); \
;     __builtin_amdgcn_s_setprio(0); } while (0)
; #define WAIT_V(n) asm volatile("s_waitcnt vmcnt(" #n ")" ::: "memory")
; #define WAIT_L(n) asm volatile("s_waitcnt lgkmcnt(" #n ")" ::: "memory")
; #define BAR __builtin_amdgcn_s_barrier()
; #define SCHED __builtin_amdgcn_sched_barrier(0)
; template <class Epi> ...
;     ...
;     BAR; WAIT_L(0); MMA(1, 0, At, B0); BAR; SCHED;
;     STAGE(SB(1, 1), Bt, bcol + HALF, t + 3);
;     WAIT_V(6); BAR; MMA(1, 1, At, B1); BAR;
;   }
;   { LDB(B0, 0, 0); LDA(At, 0, 0); STAGE(SA(1, 1), A, brow + HALF, nt - 1);
;     BAR; WAIT_L(0); MMA(0, 0, At, B0); BAR;
;     LDB(B1, 0, 1); BAR; WAIT_L(0); MMA(0, 1, At, B1); BAR;
;     LDA(At, 0, 1); WAIT_V(4); BAR; WAIT_L(0); MMA(1, 0, At, B0); MMA(1, 1, At, B1); BAR; }
	s_waitcnt lgkmcnt(0)
	s_waitcnt lgkmcnt(0)
	v_mfma_f32_16x16x32_bf16 v[40:43], v[178:181], v[162:165], v[40:43]
	v_mfma_f32_16x16x32_bf16 v[36:39], v[178:181], v[170:173], v[36:39]
	v_mfma_f32_16x16x32_bf16 v[48:51], v[186:189], v[162:165], v[48:51]
	v_mfma_f32_16x16x32_bf16 v[44:47], v[186:189], v[170:173], v[44:47]
	v_mfma_f32_16x16x32_bf16 v[56:59], v[194:197], v[162:165], v[56:59]
	v_mfma_f32_16x16x32_bf16 v[52:55], v[194:197], v[170:173], v[52:55]
	v_mfma_f32_16x16x32_bf16 v[64:67], v[202:205], v[162:165], v[64:67]
	v_mfma_f32_16x16x32_bf16 v[60:63], v[202:205], v[170:173], v[60:63]
	v_mfma_f32_16x16x32_bf16 v[40:43], v[182:185], v[166:169], v[40:43]
	v_mfma_f32_16x16x32_bf16 v[36:39], v[182:185], v[174:177], v[36:39]
	v_mfma_f32_16x16x32_bf16 v[48:51], v[190:193], v[166:169], v[48:51]
	v_mfma_f32_16x16x32_bf16 v[44:47], v[190:193], v[174:177], v[44:47]
	v_mfma_f32_16x16x32_bf16 v[56:59], v[198:201], v[166:169], v[56:59]
	v_mfma_f32_16x16x32_bf16 v[52:55], v[198:201], v[174:177], v[52:55]
	v_mfma_f32_16x16x32_bf16 v[64:67], v[206:209], v[166:169], v[64:67]
	v_mfma_f32_16x16x32_bf16 v[60:63], v[206:209], v[174:177], v[60:63]
	s_barrier
	s_mov_b32 m0, s43
	v_lshl_add_u64 v[162:163], v[240:241], 0, s[90:91]
	global_load_lds_dwordx4 v[162:163], off
	v_lshl_add_u64 v[162:163], v[242:243], 0, s[90:91]
	s_mov_b32 m0, s44
	s_nop 0
	global_load_lds_dwordx4 v[162:163], off
	s_waitcnt vmcnt(6)
	s_barrier
	v_mfma_f32_16x16x32_bf16 v[8:11], v[178:181], v[210:213], v[8:11]
	v_mfma_f32_16x16x32_bf16 v[4:7], v[178:181], v[218:221], v[4:7]
	v_mfma_f32_16x16x32_bf16 v[16:19], v[186:189], v[210:213], v[16:19]
	v_mfma_f32_16x16x32_bf16 v[12:15], v[186:189], v[218:221], v[12:15]
	v_mfma_f32_16x16x32_bf16 v[24:27], v[194:197], v[210:213], v[24:27]
	v_mfma_f32_16x16x32_bf16 v[20:23], v[194:197], v[218:221], v[20:23]
	v_mfma_f32_16x16x32_bf16 v[32:35], v[202:205], v[210:213], v[32:35]
	v_mfma_f32_16x16x32_bf16 v[28:31], v[202:205], v[218:221], v[28:31]
	v_mfma_f32_16x16x32_bf16 v[8:11], v[182:185], v[214:217], v[8:11]
	v_mfma_f32_16x16x32_bf16 v[4:7], v[182:185], v[222:225], v[4:7]
	v_mfma_f32_16x16x32_bf16 v[16:19], v[190:193], v[214:217], v[16:19]
	v_mfma_f32_16x16x32_bf16 v[12:15], v[190:193], v[222:225], v[12:15]
	v_mfma_f32_16x16x32_bf16 v[24:27], v[198:201], v[214:217], v[24:27]
	v_mfma_f32_16x16x32_bf16 v[20:23], v[198:201], v[222:225], v[20:23]
	v_mfma_f32_16x16x32_bf16 v[32:35], v[206:209], v[214:217], v[32:35]
	v_mfma_f32_16x16x32_bf16 v[28:31], v[206:209], v[222:225], v[28:31]
	s_add_u32 s24, s24, 0x100
	s_addc_u32 s25, s25, 0
	s_cmp_lt_u32 s26, s45
	s_barrier
	s_cbranch_scc1 .LBB0_133
	s_add_i32 s96, s28, -1
	s_lshl_b64 s[24:25], s[96:97], 7
	s_add_u32 s22, s22, s24
	s_addc_u32 s23, s23, s25
	s_mov_b32 m0, s30
	v_lshl_add_u64 v[194:195], s[22:23], 0, v[0:1]
	ds_read_b128 v[132:135], v154
	ds_read_b128 v[136:139], v154 offset:1024
	ds_read_b128 v[140:143], v154 offset:2048
	ds_read_b128 v[144:147], v154 offset:3072
	ds_read_b128 v[162:165], v155
	ds_read_b128 v[166:169], v155 offset:1024
	ds_read_b128 v[170:173], v156
	ds_read_b128 v[174:177], v156 offset:1024
	ds_read_b128 v[178:181], v157
	ds_read_b128 v[182:185], v157 offset:1024
	ds_read_b128 v[186:189], v158
	ds_read_b128 v[190:193], v158 offset:1024
	global_load_lds_dwordx4 v[194:195], off
	v_lshl_add_u64 v[2:3], s[22:23], 0, v[2:3]
	s_mov_b32 m0, s27
	s_nop 0
	global_load_lds_dwordx4 v[2:3], off
	s_barrier
	s_waitcnt lgkmcnt(0)
	s_waitcnt lgkmcnt(0)
	v_mfma_f32_16x16x32_bf16 v[104:107], v[162:165], v[132:135], v[104:107]
	v_mfma_f32_16x16x32_bf16 v[100:103], v[162:165], v[140:143], v[100:103]
	v_mfma_f32_16x16x32_bf16 v[112:115], v[170:173], v[132:135], v[112:115]
	v_mfma_f32_16x16x32_bf16 v[108:111], v[170:173], v[140:143], v[108:111]
	v_mfma_f32_16x16x32_bf16 v[120:123], v[178:181], v[132:135], v[120:123]
	v_mfma_f32_16x16x32_bf16 v[116:119], v[178:181], v[140:143], v[116:119]
	v_mfma_f32_16x16x32_bf16 v[128:131], v[186:189], v[132:135], v[128:131]
	v_mfma_f32_16x16x32_bf16 v[124:127], v[186:189], v[140:143], v[124:127]
	v_mfma_f32_16x16x32_bf16 v[104:107], v[166:169], v[136:139], v[104:107]
	v_mfma_f32_16x16x32_bf16 v[100:103], v[166:169], v[144:147], v[100:103]
	v_mfma_f32_16x16x32_bf16 v[112:115], v[174:177], v[136:139], v[112:115]
	v_mfma_f32_16x16x32_bf16 v[108:111], v[174:177], v[144:147], v[108:111]
	v_mfma_f32_16x16x32_bf16 v[120:123], v[182:185], v[136:139], v[120:123]
	v_mfma_f32_16x16x32_bf16 v[116:119], v[182:185], v[144:147], v[116:119]
	v_mfma_f32_16x16x32_bf16 v[128:131], v[190:193], v[136:139], v[128:131]
	v_mfma_f32_16x16x32_bf16 v[124:127], v[190:193], v[144:147], v[124:127]
	s_barrier
	ds_read_b128 v[194:197], v159
	ds_read_b128 v[198:201], v159 offset:1024
	ds_read_b128 v[202:205], v159 offset:2048
	ds_read_b128 v[206:209], v159 offset:3072
	s_barrier
	s_waitcnt lgkmcnt(0)
	s_waitcnt lgkmcnt(0)
	v_mfma_f32_16x16x32_bf16 v[72:75], v[162:165], v[194:197], v[72:75]
	v_mfma_f32_16x16x32_bf16 v[68:71], v[162:165], v[202:205], v[68:71]
	v_mfma_f32_16x16x32_bf16 v[80:83], v[170:173], v[194:197], v[80:83]
	v_mfma_f32_16x16x32_bf16 v[76:79], v[170:173], v[202:205], v[76:79]
	v_mfma_f32_16x16x32_bf16 v[88:91], v[178:181], v[194:197], v[88:91]
	v_mfma_f32_16x16x32_bf16 v[84:87], v[178:181], v[202:205], v[84:87]
	v_mfma_f32_16x16x32_bf16 v[96:99], v[186:189], v[194:197], v[96:99]
	v_mfma_f32_16x16x32_bf16 v[92:95], v[186:189], v[202:205], v[92:95]
	v_mfma_f32_16x16x32_bf16 v[72:75], v[166:169], v[198:201], v[72:75]
	v_mfma_f32_16x16x32_bf16 v[68:71], v[166:169], v[206:209], v[68:71]
	v_mfma_f32_16x16x32_bf16 v[80:83], v[174:177], v[198:201], v[80:83]
	v_mfma_f32_16x16x32_bf16 v[76:79], v[174:177], v[206:209], v[76:79]
	v_mfma_f32_16x16x32_bf16 v[88:91], v[182:185], v[198:201], v[88:91]
	v_mfma_f32_16x16x32_bf16 v[84:87], v[182:185], v[206:209], v[84:87]
	v_mfma_f32_16x16x32_bf16 v[96:99], v[190:193], v[198:201], v[96:99]
	v_mfma_f32_16x16x32_bf16 v[92:95], v[190:193], v[206:209], v[92:95]
	s_barrier
; #define LDA(dst, b, h) _Pragma("unroll") for (int m = 0; m < 4; ++m) _Pragma("unroll") for (int k = 0; k < 2; ++k) \
;     dst[m][k] = *reinterpret_cast<const bf16x8*>((char*)SA(b, h) + lds_byte(wr * 64 + m * 16 + fr, k * 32 + fq * 8))
; #define LDB(dst, b, h) _Pragma("unroll") for (int n = 0; n < 2; ++n) _Pragma("unroll") for (int k = 0; k < 2; ++k) \
;     dst[n][k] = *reinterpret_cast<const bf16x8*>((char*)SB(b, h) + lds_byte(wc * 32 + n * 16 + fr, k * 32 + fq * 8))
; #define MMA(ai, bj, At_, Bt_) do { __builtin_amdgcn_s_setprio(1); \
;     _Pragma("unroll") for (int m = 0; m < 4; ++m) _Pragma("unroll") for (int n = 0; n < 2; ++n) _Pragma("unroll") for (int k = 0; k < 2; ++k) \
;       acc[ai][bj][m][n] = __builtin_amdgcn_mfma_f32_16x16x32_bf16(At_[m][k], Bt_[n][k], acc[ai][bj][m][n], 0, 0, 0); \
;     __builtin_amdgcn_s_setprio(0); } while (0)
; #define WAIT_V(n) asm volatile("s_waitcnt vmcnt(" #n ")" ::: "memory")
; #define WAIT_L(n) asm volatile("s_waitcnt lgkmcnt(" #n ")" ::: "memory")
; #define BAR __builtin_amdgcn_s_barrier()
; template <class Epi> ...
;     ...
;     LDA(At, 0, 1); WAIT_V(4); BAR; WAIT_L(0); MMA(1, 0, At, B0); MMA(1, 1, At, B1); BAR; }
;   { LDB(B0, 1, 0); LDA(At, 1, 0); WAIT_V(2); BAR; WAIT_L(0); MMA(0, 0, At, B0); BAR;
	ds_read_b128 v[162:165], v155 offset:16384
	ds_read_b128 v[166:169], v155 offset:17408
	ds_read_b128 v[170:173], v156 offset:16384
	ds_read_b128 v[174:177], v156 offset:17408
	ds_read_b128 v[178:181], v157 offset:16384
	ds_read_b128 v[182:185], v157 offset:17408
	ds_read_b128 v[186:189], v158 offset:16384
	ds_read_b128 v[190:193], v158 offset:17408
	s_waitcnt vmcnt(4)
	s_barrier
	s_waitcnt lgkmcnt(0)
	s_waitcnt lgkmcnt(0)
	v_mfma_f32_16x16x32_bf16 v[40:43], v[162:165], v[132:135], v[40:43]
	v_mfma_f32_16x16x32_bf16 v[36:39], v[162:165], v[140:143], v[36:39]
	v_mfma_f32_16x16x32_bf16 v[48:51], v[170:173], v[132:135], v[48:51]
	v_mfma_f32_16x16x32_bf16 v[44:47], v[170:173], v[140:143], v[44:47]
	v_mfma_f32_16x16x32_bf16 v[56:59], v[178:181], v[132:135], v[56:59]
	v_mfma_f32_16x16x32_bf16 v[52:55], v[178:181], v[140:143], v[52:55]
	v_mfma_f32_16x16x32_bf16 v[64:67], v[186:189], v[132:135], v[64:67]
	v_mfma_f32_16x16x32_bf16 v[60:63], v[186:189], v[140:143], v[60:63]
	v_mfma_f32_16x16x32_bf16 v[40:43], v[166:169], v[136:139], v[40:43]
	v_mfma_f32_16x16x32_bf16 v[36:39], v[166:169], v[144:147], v[36:39]
	v_mfma_f32_16x16x32_bf16 v[48:51], v[174:177], v[136:139], v[48:51]
	v_mfma_f32_16x16x32_bf16 v[44:47], v[174:177], v[144:147], v[44:47]
	v_mfma_f32_16x16x32_bf16 v[56:59], v[182:185], v[136:139], v[56:59]
	v_mfma_f32_16x16x32_bf16 v[52:55], v[182:185], v[144:147], v[52:55]
	v_mfma_f32_16x16x32_bf16 v[64:67], v[190:193], v[136:139], v[64:67]
	v_mfma_f32_16x16x32_bf16 v[60:63], v[190:193], v[144:147], v[60:63]
	v_mfma_f32_16x16x32_bf16 v[8:11], v[162:165], v[194:197], v[8:11]
	v_mfma_f32_16x16x32_bf16 v[2:5], v[162:165], v[202:205], v[4:7]
	v_mfma_f32_16x16x32_bf16 v[16:19], v[170:173], v[194:197], v[16:19]
	v_mfma_f32_16x16x32_bf16 v[12:15], v[170:173], v[202:205], v[12:15]
	v_mfma_f32_16x16x32_bf16 v[24:27], v[178:181], v[194:197], v[24:27]
	v_mfma_f32_16x16x32_bf16 v[20:23], v[178:181], v[202:205], v[20:23]
	v_mfma_f32_16x16x32_bf16 v[32:35], v[186:189], v[194:197], v[32:35]
	v_mfma_f32_16x16x32_bf16 v[28:31], v[186:189], v[202:205], v[28:31]
	v_mfma_f32_16x16x32_bf16 v[8:11], v[166:169], v[198:201], v[8:11]
	v_mfma_f32_16x16x32_bf16 v[2:5], v[166:169], v[206:209], v[2:5]
	v_mfma_f32_16x16x32_bf16 v[16:19], v[174:177], v[198:201], v[16:19]
	v_mfma_f32_16x16x32_bf16 v[12:15], v[174:177], v[206:209], v[12:15]
	v_mfma_f32_16x16x32_bf16 v[24:27], v[182:185], v[198:201], v[24:27]
	v_mfma_f32_16x16x32_bf16 v[20:23], v[182:185], v[206:209], v[20:23]
	v_mfma_f32_16x16x32_bf16 v[32:35], v[190:193], v[198:201], v[32:35]
	v_mfma_f32_16x16x32_bf16 v[28:31], v[190:193], v[206:209], v[28:31]
	s_barrier
	ds_read_b128 v[132:135], v160
	ds_read_b128 v[136:139], v160 offset:1024
	ds_read_b128 v[140:143], v160 offset:2048
	ds_read_b128 v[144:147], v160 offset:3072
	ds_read_b128 v[162:165], v155 offset:32768
	ds_read_b128 v[166:169], v155 offset:33792
	ds_read_b128 v[170:173], v156 offset:32768
	ds_read_b128 v[174:177], v156 offset:33792
	ds_read_b128 v[178:181], v157 offset:32768
	ds_read_b128 v[182:185], v157 offset:33792
	ds_read_b128 v[186:189], v158 offset:32768
	ds_read_b128 v[190:193], v158 offset:33792
	s_waitcnt vmcnt(2)
	s_barrier
	s_waitcnt lgkmcnt(0)
	s_waitcnt lgkmcnt(0)
	v_mfma_f32_16x16x32_bf16 v[104:107], v[162:165], v[132:135], v[104:107]
	v_mfma_f32_16x16x32_bf16 v[100:103], v[162:165], v[140:143], v[100:103]
	v_mfma_f32_16x16x32_bf16 v[112:115], v[170:173], v[132:135], v[112:115]
	v_mfma_f32_16x16x32_bf16 v[108:111], v[170:173], v[140:143], v[108:111]
	v_mfma_f32_16x16x32_bf16 v[120:123], v[178:181], v[132:135], v[120:123]
	v_mfma_f32_16x16x32_bf16 v[116:119], v[178:181], v[140:143], v[116:119]
	v_mfma_f32_16x16x32_bf16 v[128:131], v[186:189], v[132:135], v[128:131]
	v_mfma_f32_16x16x32_bf16 v[124:127], v[186:189], v[140:143], v[124:127]
	v_mfma_f32_16x16x32_bf16 v[104:107], v[166:169], v[136:139], v[104:107]
	v_mfma_f32_16x16x32_bf16 v[100:103], v[166:169], v[144:147], v[100:103]
	v_mfma_f32_16x16x32_bf16 v[112:115], v[174:177], v[136:139], v[112:115]
	v_mfma_f32_16x16x32_bf16 v[108:111], v[174:177], v[144:147], v[108:111]
	v_mfma_f32_16x16x32_bf16 v[120:123], v[182:185], v[136:139], v[120:123]
	v_mfma_f32_16x16x32_bf16 v[116:119], v[182:185], v[144:147], v[116:119]
	v_mfma_f32_16x16x32_bf16 v[128:131], v[190:193], v[136:139], v[128:131]
	v_mfma_f32_16x16x32_bf16 v[124:127], v[190:193], v[144:147], v[124:127]
	s_barrier
; #define LDA(dst, b, h) _Pragma("unroll") for (int m = 0; m < 4; ++m) _Pragma("unroll") for (int k = 0; k < 2; ++k) \
;     dst[m][k] = *reinterpret_cast<const bf16x8*>((char*)SA(b, h) + lds_byte(wr * 64 + m * 16 + fr, k * 32 + fq * 8))
; #define LDB(dst, b, h) _Pragma("unroll") for (int n = 0; n < 2; ++n) _Pragma("unroll") for (int k = 0; k < 2; ++k) \
;     dst[n][k] = *reinterpret_cast<const bf16x8*>((char*)SB(b, h) + lds_byte(wc * 32 + n * 16 + fr, k * 32 + fq * 8))
; #define MMA(ai, bj, At_, Bt_) do { __builtin_amdgcn_s_setprio(1); \
;     _Pragma("unroll") for (int m = 0; m < 4; ++m) _Pragma("unroll") for (int n = 0; n < 2; ++n) _Pragma("unroll") for (int k = 0; k < 2; ++k) \
;       acc[ai][bj][m][n] = __builtin_amdgcn_mfma_f32_16x16x32_bf16(At_[m][k], Bt_[n][k], acc[ai][bj][m][n], 0, 0, 0); \
;     __builtin_amdgcn_s_setprio(0); } while (0)
; #define WAIT_V(n) asm volatile("s_waitcnt vmcnt(" #n ")" ::: "memory")
; #define WAIT_L(n) asm volatile("s_waitcnt lgkmcnt(" #n ")" ::: "memory")
; #define BAR __builtin_amdgcn_s_barrier()
; template <class Epi> ...
;     ...
;   { LDB(B0, 1, 0); LDA(At, 1, 0); WAIT_V(2); BAR; WAIT_L(0); MMA(0, 0, At, B0); BAR;
;     LDB(B1, 1, 1); WAIT_V(0); BAR; WAIT_L(0); MMA(0, 1, At, B1); BAR;
;     LDA(At, 1, 1); BAR; WAIT_L(0); MMA(1, 0, At, B0); MMA(1, 1, At, B1); BAR; }
;   if (wr == 0) BAR;
	ds_read_b128 v[194:197], v161
	ds_read_b128 v[198:201], v161 offset:1024
	ds_read_b128 v[202:205], v161 offset:2048
	ds_read_b128 v[206:209], v161 offset:3072
	s_waitcnt vmcnt(0)
	s_barrier
	s_waitcnt lgkmcnt(0)
	s_waitcnt lgkmcnt(0)
	v_mfma_f32_16x16x32_bf16 v[72:75], v[162:165], v[194:197], v[72:75]
	v_mfma_f32_16x16x32_bf16 v[68:71], v[162:165], v[202:205], v[68:71]
	v_mfma_f32_16x16x32_bf16 v[80:83], v[170:173], v[194:197], v[80:83]
	v_mfma_f32_16x16x32_bf16 v[76:79], v[170:173], v[202:205], v[76:79]
	v_mfma_f32_16x16x32_bf16 v[88:91], v[178:181], v[194:197], v[88:91]
	v_mfma_f32_16x16x32_bf16 v[84:87], v[178:181], v[202:205], v[84:87]
	v_mfma_f32_16x16x32_bf16 v[96:99], v[186:189], v[194:197], v[96:99]
	v_mfma_f32_16x16x32_bf16 v[92:95], v[186:189], v[202:205], v[92:95]
	v_mfma_f32_16x16x32_bf16 v[72:75], v[166:169], v[198:201], v[72:75]
	v_mfma_f32_16x16x32_bf16 v[68:71], v[166:169], v[206:209], v[68:71]
	v_mfma_f32_16x16x32_bf16 v[80:83], v[174:177], v[198:201], v[80:83]
	v_mfma_f32_16x16x32_bf16 v[76:79], v[174:177], v[206:209], v[76:79]
	v_mfma_f32_16x16x32_bf16 v[88:91], v[182:185], v[198:201], v[88:91]
	v_mfma_f32_16x16x32_bf16 v[84:87], v[182:185], v[206:209], v[84:87]
	v_mfma_f32_16x16x32_bf16 v[96:99], v[190:193], v[198:201], v[96:99]
	v_mfma_f32_16x16x32_bf16 v[92:95], v[190:193], v[206:209], v[92:95]
	s_barrier
	ds_read_b128 v[162:165], v155 offset:49152
	ds_read_b128 v[166:169], v155 offset:50176
	ds_read_b128 v[170:173], v156 offset:49152
	ds_read_b128 v[174:177], v156 offset:50176
	ds_read_b128 v[178:181], v157 offset:49152
	ds_read_b128 v[182:185], v157 offset:50176
	ds_read_b128 v[186:189], v158 offset:49152
	ds_read_b128 v[190:193], v158 offset:50176
	s_barrier
	s_waitcnt lgkmcnt(0)
	s_waitcnt lgkmcnt(0)
	v_mfma_f32_16x16x32_bf16 v[40:43], v[162:165], v[132:135], v[40:43]
	v_mfma_f32_16x16x32_bf16 v[36:39], v[162:165], v[140:143], v[36:39]
	v_mfma_f32_16x16x32_bf16 v[48:51], v[170:173], v[132:135], v[48:51]
	v_mfma_f32_16x16x32_bf16 v[44:47], v[170:173], v[140:143], v[44:47]
	v_mfma_f32_16x16x32_bf16 v[56:59], v[178:181], v[132:135], v[56:59]
	v_mfma_f32_16x16x32_bf16 v[52:55], v[178:181], v[140:143], v[52:55]
	v_mfma_f32_16x16x32_bf16 v[64:67], v[186:189], v[132:135], v[64:67]
	v_mfma_f32_16x16x32_bf16 v[60:63], v[186:189], v[140:143], v[60:63]
	v_mfma_f32_16x16x32_bf16 v[40:43], v[166:169], v[136:139], v[40:43]
	v_mfma_f32_16x16x32_bf16 v[36:39], v[166:169], v[144:147], v[36:39]
	v_mfma_f32_16x16x32_bf16 v[48:51], v[174:177], v[136:139], v[48:51]
	v_mfma_f32_16x16x32_bf16 v[44:47], v[174:177], v[144:147], v[44:47]
	v_mfma_f32_16x16x32_bf16 v[56:59], v[182:185], v[136:139], v[56:59]
	v_mfma_f32_16x16x32_bf16 v[52:55], v[182:185], v[144:147], v[52:55]
	v_mfma_f32_16x16x32_bf16 v[64:67], v[190:193], v[136:139], v[64:67]
	v_mfma_f32_16x16x32_bf16 v[60:63], v[190:193], v[144:147], v[60:63]
	v_mfma_f32_16x16x32_bf16 v[6:9], v[162:165], v[194:197], v[8:11]
	v_mfma_f32_16x16x32_bf16 v[2:5], v[162:165], v[202:205], v[2:5]
	v_mfma_f32_16x16x32_bf16 v[16:19], v[170:173], v[194:197], v[16:19]
	v_mfma_f32_16x16x32_bf16 v[12:15], v[170:173], v[202:205], v[12:15]
	v_mfma_f32_16x16x32_bf16 v[24:27], v[178:181], v[194:197], v[24:27]
	v_mfma_f32_16x16x32_bf16 v[20:23], v[178:181], v[202:205], v[20:23]
	v_mfma_f32_16x16x32_bf16 v[32:35], v[186:189], v[194:197], v[32:35]
	v_mfma_f32_16x16x32_bf16 v[28:31], v[186:189], v[202:205], v[28:31]
	v_mfma_f32_16x16x32_bf16 v[8:11], v[166:169], v[198:201], v[6:9]
	v_mfma_f32_16x16x32_bf16 v[4:7], v[166:169], v[206:209], v[2:5]
	v_mfma_f32_16x16x32_bf16 v[16:19], v[174:177], v[198:201], v[16:19]
	v_mfma_f32_16x16x32_bf16 v[12:15], v[174:177], v[206:209], v[12:15]
	v_mfma_f32_16x16x32_bf16 v[24:27], v[182:185], v[198:201], v[24:27]
	v_mfma_f32_16x16x32_bf16 v[20:23], v[182:185], v[206:209], v[20:23]
	v_mfma_f32_16x16x32_bf16 v[32:35], v[190:193], v[198:201], v[32:35]
	v_mfma_f32_16x16x32_bf16 v[28:31], v[190:193], v[206:209], v[28:31]
	s_barrier
	s_and_saveexec_b64 s[22:23], s[6:7]
	s_cbranch_execz .LBB0_136
	s_barrier

; #define STAGE(P, BASE, br, kt) do { const char* _gb = (const char*)((BASE) + ((long)(br) * K + (long)(kt) * BK)); \
;     __builtin_amdgcn_global_load_lds((const unsigned*)(_gb + (size_t)so0), (unsigned*)((char*)(P) + wv1k), 16, 0, 0); \
;     __builtin_amdgcn_global_load_lds((const unsigned*)(_gb + (size_t)so1), (unsigned*)((char*)(P) + wv1k + 8192), 16, 0, 0); } while (0)
; #define LDA(dst, b, h) _Pragma("unroll") for (int m = 0; m < 4; ++m) _Pragma("unroll") for (int k = 0; k < 2; ++k) \
;     dst[m][k] = *reinterpret_cast<const bf16x8*>((char*)SA(b, h) + lds_byte(wr * 64 + m * 16 + fr, k * 32 + fq * 8))
; #define LDB(dst, b, h) _Pragma("unroll") for (int n = 0; n < 2; ++n) _Pragma("unroll") for (int k = 0; k < 2; ++k) \
;     dst[n][k] = *reinterpret_cast<const bf16x8*>((char*)SB(b, h) + lds_byte(wc * 32 + n * 16 + fr, k * 32 + fq * 8))
; #define MMA(ai, bj, At_, Bt_) do { __builtin_amdgcn_s_setprio(1); \
;     _Pragma("unroll") for (int m = 0; m < 4; ++m) _Pragma("unroll") for (int n = 0; n < 2; ++n) _Pragma("unroll") for (int k = 0; k < 2; ++k) \
;       acc[ai][bj][m][n] = __builtin_amdgcn_mfma_f32_16x16x32_bf16(At_[m][k], Bt_[n][k], acc[ai][bj][m][n], 0, 0, 0); \
;     __builtin_amdgcn_s_setprio(0); } while (0)
; #define WAIT_V(n) asm volatile("s_waitcnt vmcnt(" #n ")" ::: "memory")
; #define WAIT_L(n) asm volatile("s_waitcnt lgkmcnt(" #n ")" ::: "memory")
; #define BAR __builtin_amdgcn_s_barrier()
; #define SCHED __builtin_amdgcn_sched_barrier(0)
; template <class Epi> ...
;     ...
;   for (int t = 0; t < nt - 2; t += 2) {
;     LDB(B0, 0, 0); SCHED; LDA(At, 0, 0); STAGE(SA(1, 1), A, brow + HALF, t + 1);
;     WAIT_L(8); BAR; WAIT_L(0); MMA(0, 0, At, B0); BAR; SCHED;
;     LDB(B1, 0, 1); STAGE(SB(0, 0), Bt, bcol, t + 2);
;     BAR; WAIT_L(0); MMA(0, 1, At, B1); BAR;
;     LDA(At, 0, 1); STAGE(SA(0, 0), A, brow, t + 2);
;     BAR; WAIT_L(0); MMA(1, 0, At, B0); BAR; SCHED;
;     STAGE(SB(0, 1), Bt, bcol + HALF, t + 2);
;     WAIT_V(6); BAR; MMA(1, 1, At, B1); BAR;
.LBB0_449:
	ds_read_b128 v[156:159], v175
	ds_read_b128 v[160:163], v175 offset:1024
	ds_read_b128 v[164:167], v175 offset:2048
	ds_read_b128 v[168:171], v175 offset:3072
	v_lshl_add_u64 v[172:173], v[148:149], 0, s[8:9]
	s_add_i32 s40, s20, 0xc000
	v_lshl_add_u64 v[216:217], v[172:173], 0, s[42:43]
	s_mov_b32 m0, s40
	v_lshl_add_u64 v[232:233], v[146:147], 0, s[8:9]
	s_add_i32 s11, s20, 0xe000
	ds_read_b128 v[184:187], v176
	ds_read_b128 v[188:191], v176 offset:1024
	ds_read_b128 v[192:195], v177
	ds_read_b128 v[196:199], v177 offset:1024
	ds_read_b128 v[200:203], v178
	ds_read_b128 v[204:207], v178 offset:1024
	ds_read_b128 v[208:211], v179
	ds_read_b128 v[212:215], v179 offset:1024
	global_load_lds_dwordx4 v[216:217], off
	v_lshl_add_u64 v[216:217], v[232:233], 0, s[42:43]
	s_mov_b32 m0, s11
	s_nop 0
	global_load_lds_dwordx4 v[216:217], off
	s_waitcnt lgkmcnt(8)
	s_barrier
	s_waitcnt lgkmcnt(0)
	s_waitcnt lgkmcnt(0)
	v_mfma_f32_16x16x32_bf16 v[126:129], v[184:187], v[156:159], v[126:129]
	v_mfma_f32_16x16x32_bf16 v[122:125], v[184:187], v[164:167], v[122:125]
	v_mfma_f32_16x16x32_bf16 v[118:121], v[192:195], v[156:159], v[118:121]
	v_mfma_f32_16x16x32_bf16 v[114:117], v[192:195], v[164:167], v[114:117]
	v_mfma_f32_16x16x32_bf16 v[110:113], v[200:203], v[156:159], v[110:113]
	v_mfma_f32_16x16x32_bf16 v[106:109], v[200:203], v[164:167], v[106:109]
	v_mfma_f32_16x16x32_bf16 v[102:105], v[208:211], v[156:159], v[102:105]
	v_mfma_f32_16x16x32_bf16 v[98:101], v[208:211], v[164:167], v[98:101]
	v_mfma_f32_16x16x32_bf16 v[126:129], v[188:191], v[160:163], v[126:129]
	v_mfma_f32_16x16x32_bf16 v[122:125], v[188:191], v[168:171], v[122:125]
	v_mfma_f32_16x16x32_bf16 v[118:121], v[196:199], v[160:163], v[118:121]
	v_mfma_f32_16x16x32_bf16 v[114:117], v[196:199], v[168:171], v[114:117]
	v_mfma_f32_16x16x32_bf16 v[110:113], v[204:207], v[160:163], v[110:113]
	v_mfma_f32_16x16x32_bf16 v[106:109], v[204:207], v[168:171], v[106:109]
	v_mfma_f32_16x16x32_bf16 v[102:105], v[212:215], v[160:163], v[102:105]
	v_mfma_f32_16x16x32_bf16 v[98:101], v[212:215], v[168:171], v[98:101]
	s_barrier
	v_lshl_add_u64 v[236:237], v[154:155], 0, s[8:9]
	s_mov_b32 m0, s21
	v_lshl_add_u64 v[238:239], v[236:237], 0, s[0:1]
	ds_read_b128 v[216:219], v180
	ds_read_b128 v[220:223], v180 offset:1024
	ds_read_b128 v[224:227], v180 offset:2048
	ds_read_b128 v[228:231], v180 offset:3072
	global_load_lds_dwordx4 v[238:239], off
	v_lshl_add_u64 v[238:239], v[152:153], 0, s[8:9]
	v_lshl_add_u64 v[240:241], v[238:239], 0, s[0:1]
	s_mov_b32 m0, s23
	s_nop 0
	global_load_lds_dwordx4 v[240:241], off
	s_barrier
	s_waitcnt lgkmcnt(0)
	s_waitcnt lgkmcnt(0)
	v_mfma_f32_16x16x32_bf16 v[94:97], v[184:187], v[216:219], v[94:97]
	v_mfma_f32_16x16x32_bf16 v[90:93], v[184:187], v[224:227], v[90:93]
	v_mfma_f32_16x16x32_bf16 v[86:89], v[192:195], v[216:219], v[86:89]
	v_mfma_f32_16x16x32_bf16 v[82:85], v[192:195], v[224:227], v[82:85]
	v_mfma_f32_16x16x32_bf16 v[78:81], v[200:203], v[216:219], v[78:81]
	v_mfma_f32_16x16x32_bf16 v[74:77], v[200:203], v[224:227], v[74:77]
	v_mfma_f32_16x16x32_bf16 v[70:73], v[208:211], v[216:219], v[70:73]
	v_mfma_f32_16x16x32_bf16 v[66:69], v[208:211], v[224:227], v[66:69]
	v_mfma_f32_16x16x32_bf16 v[94:97], v[188:191], v[220:223], v[94:97]
	v_mfma_f32_16x16x32_bf16 v[90:93], v[188:191], v[228:231], v[90:93]
	v_mfma_f32_16x16x32_bf16 v[86:89], v[196:199], v[220:223], v[86:89]
	v_mfma_f32_16x16x32_bf16 v[82:85], v[196:199], v[228:231], v[82:85]
	v_mfma_f32_16x16x32_bf16 v[78:81], v[204:207], v[220:223], v[78:81]
	v_mfma_f32_16x16x32_bf16 v[74:77], v[204:207], v[228:231], v[74:77]
	v_mfma_f32_16x16x32_bf16 v[70:73], v[212:215], v[220:223], v[70:73]
	v_mfma_f32_16x16x32_bf16 v[66:69], v[212:215], v[228:231], v[66:69]
	s_mov_b32 m0, s20
	v_lshl_add_u64 v[240:241], v[172:173], 0, s[0:1]
	s_barrier
	ds_read_b128 v[184:187], v176 offset:16384
	ds_read_b128 v[188:191], v176 offset:17408
	ds_read_b128 v[192:195], v177 offset:16384
	ds_read_b128 v[196:199], v177 offset:17408
	ds_read_b128 v[200:203], v178 offset:16384
	ds_read_b128 v[204:207], v178 offset:17408
	ds_read_b128 v[208:211], v179 offset:16384
	ds_read_b128 v[212:215], v179 offset:17408
	global_load_lds_dwordx4 v[240:241], off
	v_lshl_add_u64 v[240:241], v[232:233], 0, s[0:1]
	s_mov_b32 m0, s13
	s_nop 0
	global_load_lds_dwordx4 v[240:241], off
	s_barrier
	s_waitcnt lgkmcnt(0)
	s_waitcnt lgkmcnt(0)
	v_mfma_f32_16x16x32_bf16 v[62:65], v[184:187], v[156:159], v[62:65]
	v_mfma_f32_16x16x32_bf16 v[58:61], v[184:187], v[164:167], v[58:61]
	v_mfma_f32_16x16x32_bf16 v[54:57], v[192:195], v[156:159], v[54:57]
	v_mfma_f32_16x16x32_bf16 v[50:53], v[192:195], v[164:167], v[50:53]
	v_mfma_f32_16x16x32_bf16 v[46:49], v[200:203], v[156:159], v[46:49]
	v_mfma_f32_16x16x32_bf16 v[42:45], v[200:203], v[164:167], v[42:45]
	v_mfma_f32_16x16x32_bf16 v[38:41], v[208:211], v[156:159], v[38:41]
	v_mfma_f32_16x16x32_bf16 v[34:37], v[208:211], v[164:167], v[34:37]
	v_mfma_f32_16x16x32_bf16 v[62:65], v[188:191], v[160:163], v[62:65]
	v_mfma_f32_16x16x32_bf16 v[58:61], v[188:191], v[168:171], v[58:61]
	v_mfma_f32_16x16x32_bf16 v[54:57], v[196:199], v[160:163], v[54:57]
	v_mfma_f32_16x16x32_bf16 v[50:53], v[196:199], v[168:171], v[50:53]
	v_mfma_f32_16x16x32_bf16 v[46:49], v[204:207], v[160:163], v[46:49]
	v_mfma_f32_16x16x32_bf16 v[42:45], v[204:207], v[168:171], v[42:45]
	v_mfma_f32_16x16x32_bf16 v[38:41], v[212:215], v[160:163], v[38:41]
	v_mfma_f32_16x16x32_bf16 v[34:37], v[212:215], v[168:171], v[34:37]
	s_barrier
; #define STAGE(P, BASE, br, kt) do { const char* _gb = (const char*)((BASE) + ((long)(br) * K + (long)(kt) * BK)); \
;     __builtin_amdgcn_global_load_lds((const unsigned*)(_gb + (size_t)so0), (unsigned*)((char*)(P) + wv1k), 16, 0, 0); \
;     __builtin_amdgcn_global_load_lds((const unsigned*)(_gb + (size_t)so1), (unsigned*)((char*)(P) + wv1k + 8192), 16, 0, 0); } while (0)
; #define LDA(dst, b, h) _Pragma("unroll") for (int m = 0; m < 4; ++m) _Pragma("unroll") for (int k = 0; k < 2; ++k) \
;     dst[m][k] = *reinterpret_cast<const bf16x8*>((char*)SA(b, h) + lds_byte(wr * 64 + m * 16 + fr, k * 32 + fq * 8))
; #define LDB(dst, b, h) _Pragma("unroll") for (int n = 0; n < 2; ++n) _Pragma("unroll") for (int k = 0; k < 2; ++k) \
;     dst[n][k] = *reinterpret_cast<const bf16x8*>((char*)SB(b, h) + lds_byte(wc * 32 + n * 16 + fr, k * 32 + fq * 8))
; #define MMA(ai, bj, At_, Bt_) do { __builtin_amdgcn_s_setprio(1); \
;     _Pragma("unroll") for (int m = 0; m < 4; ++m) _Pragma("unroll") for (int n = 0; n < 2; ++n) _Pragma("unroll") for (int k = 0; k < 2; ++k) \
;       acc[ai][bj][m][n] = __builtin_amdgcn_mfma_f32_16x16x32_bf16(At_[m][k], Bt_[n][k], acc[ai][bj][m][n], 0, 0, 0); \
;     __builtin_amdgcn_s_setprio(0); } while (0)
; #define WAIT_V(n) asm volatile("s_waitcnt vmcnt(" #n ")" ::: "memory")
; #define WAIT_L(n) asm volatile("s_waitcnt lgkmcnt(" #n ")" ::: "memory")
; #define BAR __builtin_amdgcn_s_barrier()
; #define SCHED __builtin_amdgcn_sched_barrier(0)
; template <class Epi> ...
;     ...
;     WAIT_V(6); BAR; MMA(1, 1, At, B1); BAR;
;     LDB(B0, 1, 0); SCHED; LDA(At, 1, 0); STAGE(SA(0, 1), A, brow + HALF, t + 2);
;     WAIT_L(8); BAR; WAIT_L(0); MMA(0, 0, At, B0); BAR; SCHED;
;     LDB(B1, 1, 1); STAGE(SB(1, 0), Bt, bcol, t + 3);
;     BAR; WAIT_L(0); MMA(0, 1, At, B1); BAR;
;     LDA(At, 1, 1); STAGE(SA(1, 0), A, brow, t + 3);
;     BAR; WAIT_L(0); MMA(1, 0, At, B0); BAR; SCHED;
	s_mov_b32 m0, s24
	v_lshl_add_u64 v[156:157], v[236:237], 0, s[44:45]
	global_load_lds_dwordx4 v[156:157], off
	v_lshl_add_u64 v[156:157], v[238:239], 0, s[44:45]
	s_mov_b32 m0, s25
	s_nop 0
	global_load_lds_dwordx4 v[156:157], off
	s_waitcnt vmcnt(6)
	s_barrier
	v_mfma_f32_16x16x32_bf16 v[30:33], v[184:187], v[216:219], v[30:33]
	v_mfma_f32_16x16x32_bf16 v[26:29], v[184:187], v[224:227], v[26:29]
	v_mfma_f32_16x16x32_bf16 v[22:25], v[192:195], v[216:219], v[22:25]
	v_mfma_f32_16x16x32_bf16 v[18:21], v[192:195], v[224:227], v[18:21]
	v_mfma_f32_16x16x32_bf16 v[14:17], v[200:203], v[216:219], v[14:17]
	v_mfma_f32_16x16x32_bf16 v[10:13], v[200:203], v[224:227], v[10:13]
	v_mfma_f32_16x16x32_bf16 v[6:9], v[208:211], v[216:219], v[6:9]
	v_mfma_f32_16x16x32_bf16 v[2:5], v[208:211], v[224:227], v[2:5]
	v_mfma_f32_16x16x32_bf16 v[30:33], v[188:191], v[220:223], v[30:33]
	v_mfma_f32_16x16x32_bf16 v[26:29], v[188:191], v[228:231], v[26:29]
	v_mfma_f32_16x16x32_bf16 v[22:25], v[196:199], v[220:223], v[22:25]
	v_mfma_f32_16x16x32_bf16 v[18:21], v[196:199], v[228:231], v[18:21]
	v_mfma_f32_16x16x32_bf16 v[14:17], v[204:207], v[220:223], v[14:17]
	v_mfma_f32_16x16x32_bf16 v[10:13], v[204:207], v[228:231], v[10:13]
	v_mfma_f32_16x16x32_bf16 v[6:9], v[212:215], v[220:223], v[6:9]
	v_mfma_f32_16x16x32_bf16 v[2:5], v[212:215], v[228:231], v[2:5]
	s_barrier
	ds_read_b128 v[156:159], v181
	ds_read_b128 v[160:163], v181 offset:1024
	ds_read_b128 v[164:167], v181 offset:2048
	ds_read_b128 v[168:171], v181 offset:3072
	s_mov_b32 m0, s26
	v_lshl_add_u64 v[216:217], v[172:173], 0, s[44:45]
	ds_read_b128 v[184:187], v176 offset:32768
	ds_read_b128 v[188:191], v176 offset:33792
	ds_read_b128 v[192:195], v177 offset:32768
	ds_read_b128 v[196:199], v177 offset:33792
	ds_read_b128 v[200:203], v178 offset:32768
	ds_read_b128 v[204:207], v178 offset:33792
	ds_read_b128 v[208:211], v179 offset:32768
	ds_read_b128 v[212:215], v179 offset:33792
	global_load_lds_dwordx4 v[216:217], off
	v_lshl_add_u64 v[216:217], v[232:233], 0, s[44:45]
	s_mov_b32 m0, s27
	s_nop 0
	global_load_lds_dwordx4 v[216:217], off
	s_waitcnt lgkmcnt(8)
	s_barrier
	s_waitcnt lgkmcnt(0)
	s_waitcnt lgkmcnt(0)
	v_mfma_f32_16x16x32_bf16 v[126:129], v[184:187], v[156:159], v[126:129]
	v_mfma_f32_16x16x32_bf16 v[122:125], v[184:187], v[164:167], v[122:125]
	v_mfma_f32_16x16x32_bf16 v[118:121], v[192:195], v[156:159], v[118:121]
	v_mfma_f32_16x16x32_bf16 v[114:117], v[192:195], v[164:167], v[114:117]
	v_mfma_f32_16x16x32_bf16 v[110:113], v[200:203], v[156:159], v[110:113]
	v_mfma_f32_16x16x32_bf16 v[106:109], v[200:203], v[164:167], v[106:109]
	v_mfma_f32_16x16x32_bf16 v[102:105], v[208:211], v[156:159], v[102:105]
	v_mfma_f32_16x16x32_bf16 v[98:101], v[208:211], v[164:167], v[98:101]
	v_mfma_f32_16x16x32_bf16 v[126:129], v[188:191], v[160:163], v[126:129]
	v_mfma_f32_16x16x32_bf16 v[122:125], v[188:191], v[168:171], v[122:125]
	v_mfma_f32_16x16x32_bf16 v[118:121], v[196:199], v[160:163], v[118:121]
	v_mfma_f32_16x16x32_bf16 v[114:117], v[196:199], v[168:171], v[114:117]
	v_mfma_f32_16x16x32_bf16 v[110:113], v[204:207], v[160:163], v[110:113]
	v_mfma_f32_16x16x32_bf16 v[106:109], v[204:207], v[168:171], v[106:109]
	v_mfma_f32_16x16x32_bf16 v[102:105], v[212:215], v[160:163], v[102:105]
	v_mfma_f32_16x16x32_bf16 v[98:101], v[212:215], v[168:171], v[98:101]
	s_barrier
	s_mov_b32 m0, s14
	v_lshl_add_u64 v[240:241], v[236:237], 0, s[90:91]
	ds_read_b128 v[216:219], v182
	ds_read_b128 v[220:223], v182 offset:1024
	ds_read_b128 v[224:227], v182 offset:2048
	ds_read_b128 v[228:231], v182 offset:3072
	global_load_lds_dwordx4 v[240:241], off
	v_lshl_add_u64 v[240:241], v[238:239], 0, s[90:91]
	s_mov_b32 m0, s15
	s_nop 0
	global_load_lds_dwordx4 v[240:241], off
	s_barrier
	s_waitcnt lgkmcnt(0)
	s_waitcnt lgkmcnt(0)
	v_mfma_f32_16x16x32_bf16 v[94:97], v[184:187], v[216:219], v[94:97]
	v_mfma_f32_16x16x32_bf16 v[90:93], v[184:187], v[224:227], v[90:93]
	v_mfma_f32_16x16x32_bf16 v[86:89], v[192:195], v[216:219], v[86:89]
	v_mfma_f32_16x16x32_bf16 v[82:85], v[192:195], v[224:227], v[82:85]
	v_mfma_f32_16x16x32_bf16 v[78:81], v[200:203], v[216:219], v[78:81]
	v_mfma_f32_16x16x32_bf16 v[74:77], v[200:203], v[224:227], v[74:77]
	v_mfma_f32_16x16x32_bf16 v[70:73], v[208:211], v[216:219], v[70:73]
	v_mfma_f32_16x16x32_bf16 v[66:69], v[208:211], v[224:227], v[66:69]
	v_mfma_f32_16x16x32_bf16 v[94:97], v[188:191], v[220:223], v[94:97]
	v_mfma_f32_16x16x32_bf16 v[90:93], v[188:191], v[228:231], v[90:93]
	v_mfma_f32_16x16x32_bf16 v[86:89], v[196:199], v[220:223], v[86:89]
	v_mfma_f32_16x16x32_bf16 v[82:85], v[196:199], v[228:231], v[82:85]
	v_mfma_f32_16x16x32_bf16 v[78:81], v[204:207], v[220:223], v[78:81]
	v_mfma_f32_16x16x32_bf16 v[74:77], v[204:207], v[228:231], v[74:77]
	v_mfma_f32_16x16x32_bf16 v[70:73], v[212:215], v[220:223], v[70:73]
	v_mfma_f32_16x16x32_bf16 v[66:69], v[212:215], v[228:231], v[66:69]
	s_mov_b32 m0, s28
	v_lshl_add_u64 v[172:173], v[172:173], 0, s[90:91]
	s_barrier
	ds_read_b128 v[184:187], v176 offset:49152
	ds_read_b128 v[188:191], v176 offset:50176
	ds_read_b128 v[192:195], v177 offset:49152
	ds_read_b128 v[196:199], v177 offset:50176
	ds_read_b128 v[200:203], v178 offset:49152
	ds_read_b128 v[204:207], v178 offset:50176
	ds_read_b128 v[208:211], v179 offset:49152
	ds_read_b128 v[212:215], v179 offset:50176
	global_load_lds_dwordx4 v[172:173], off
	v_lshl_add_u64 v[172:173], v[232:233], 0, s[90:91]
	s_mov_b32 m0, s29
	s_nop 0
	global_load_lds_dwordx4 v[172:173], off
	s_barrier
; #define STAGE(P, BASE, br, kt) do { const char* _gb = (const char*)((BASE) + ((long)(br) * K + (long)(kt) * BK)); \
;     __builtin_amdgcn_global_load_lds((const unsigned*)(_gb + (size_t)so0), (unsigned*)((char*)(P) + wv1k), 16, 0, 0); \
;     __builtin_amdgcn_global_load_lds((const unsigned*)(_gb + (size_t)so1), (unsigned*)((char*)(P) + wv1k + 8192), 16, 0, 0); } while (0)
; #define LDA(dst, b, h) _Pragma("unroll") for (int m = 0; m < 4; ++m) _Pragma("unroll") for (int k = 0; k < 2; ++k) \
;     dst[m][k] = *reinterpret_cast<const bf16x8*>((char*)SA(b, h) + lds_byte(wr * 64 + m * 16 + fr, k * 32 + fq * 8))
; #define LDB(dst, b, h) _Pragma("unroll") for (int n = 0; n < 2; ++n) _Pragma("unroll") for (int k = 0; k < 2; ++k) \
;     dst[n][k] = *reinterpret_cast<const bf16x8*>((char*)SB(b, h) + lds_byte(wc * 32 + n * 16 + fr, k * 32 + fq * 8))
; #define MMA(ai, bj, At_, Bt_) do { __builtin_amdgcn_s_setprio(1); \
;     _Pragma("unroll") for (int m = 0; m < 4; ++m) _Pragma("unroll") for (int n = 0; n < 2; ++n) _Pragma("unroll") for (int k = 0; k < 2; ++k) \
;       acc[ai][bj][m][n] = __builtin_amdgcn_mfma_f32_16x16x32_bf16(At_[m][k], Bt_[n][k], acc[ai][bj][m][n], 0, 0, 0); \
;     __builtin_amdgcn_s_setprio(0); } while (0)
; #define WAIT_V(n) asm volatile("s_waitcnt vmcnt(" #n ")" ::: "memory")
; #define WAIT_L(n) asm volatile("s_waitcnt lgkmcnt(" #n ")" ::: "memory")
; #define BAR __builtin_amdgcn_s_barrier()
; #define SCHED __builtin_amdgcn_sched_barrier(0)
; template <class Epi> ...
;     ...
;     BAR; WAIT_L(0); MMA(1, 0, At, B0); BAR; SCHED;
;     STAGE(SB(1, 1), Bt, bcol + HALF, t + 3);
;     WAIT_V(6); BAR; MMA(1, 1, At, B1); BAR;
;   }
;   { LDB(B0, 0, 0); LDA(At, 0, 0); STAGE(SA(1, 1), A, brow + HALF, nt - 1);
;     BAR; WAIT_L(0); MMA(0, 0, At, B0); BAR;
;     LDB(B1, 0, 1); BAR; WAIT_L(0); MMA(0, 1, At, B1); BAR;
;     LDA(At, 0, 1); WAIT_V(4); BAR; WAIT_L(0); MMA(1, 0, At, B0); MMA(1, 1, At, B1); BAR; }
	s_waitcnt lgkmcnt(0)
	s_waitcnt lgkmcnt(0)
	v_mfma_f32_16x16x32_bf16 v[62:65], v[184:187], v[156:159], v[62:65]
	v_mfma_f32_16x16x32_bf16 v[58:61], v[184:187], v[164:167], v[58:61]
	v_mfma_f32_16x16x32_bf16 v[54:57], v[192:195], v[156:159], v[54:57]
	v_mfma_f32_16x16x32_bf16 v[50:53], v[192:195], v[164:167], v[50:53]
	v_mfma_f32_16x16x32_bf16 v[46:49], v[200:203], v[156:159], v[46:49]
	v_mfma_f32_16x16x32_bf16 v[42:45], v[200:203], v[164:167], v[42:45]
	v_mfma_f32_16x16x32_bf16 v[38:41], v[208:211], v[156:159], v[38:41]
	v_mfma_f32_16x16x32_bf16 v[34:37], v[208:211], v[164:167], v[34:37]
	v_mfma_f32_16x16x32_bf16 v[62:65], v[188:191], v[160:163], v[62:65]
	v_mfma_f32_16x16x32_bf16 v[58:61], v[188:191], v[168:171], v[58:61]
	v_mfma_f32_16x16x32_bf16 v[54:57], v[196:199], v[160:163], v[54:57]
	v_mfma_f32_16x16x32_bf16 v[50:53], v[196:199], v[168:171], v[50:53]
	v_mfma_f32_16x16x32_bf16 v[46:49], v[204:207], v[160:163], v[46:49]
	v_mfma_f32_16x16x32_bf16 v[42:45], v[204:207], v[168:171], v[42:45]
	v_mfma_f32_16x16x32_bf16 v[38:41], v[212:215], v[160:163], v[38:41]
	v_mfma_f32_16x16x32_bf16 v[34:37], v[212:215], v[168:171], v[34:37]
	s_barrier
	s_mov_b32 m0, s38
	v_lshl_add_u64 v[156:157], v[236:237], 0, s[46:47]
	global_load_lds_dwordx4 v[156:157], off
	v_lshl_add_u64 v[156:157], v[238:239], 0, s[46:47]
	s_mov_b32 m0, s39
	s_nop 0
	global_load_lds_dwordx4 v[156:157], off
	s_waitcnt vmcnt(6)
	s_barrier
	v_mfma_f32_16x16x32_bf16 v[30:33], v[184:187], v[216:219], v[30:33]
	v_mfma_f32_16x16x32_bf16 v[26:29], v[184:187], v[224:227], v[26:29]
	v_mfma_f32_16x16x32_bf16 v[22:25], v[192:195], v[216:219], v[22:25]
	v_mfma_f32_16x16x32_bf16 v[18:21], v[192:195], v[224:227], v[18:21]
	v_mfma_f32_16x16x32_bf16 v[14:17], v[200:203], v[216:219], v[14:17]
	v_mfma_f32_16x16x32_bf16 v[10:13], v[200:203], v[224:227], v[10:13]
	v_mfma_f32_16x16x32_bf16 v[6:9], v[208:211], v[216:219], v[6:9]
	v_mfma_f32_16x16x32_bf16 v[2:5], v[208:211], v[224:227], v[2:5]
	v_mfma_f32_16x16x32_bf16 v[30:33], v[188:191], v[220:223], v[30:33]
	v_mfma_f32_16x16x32_bf16 v[26:29], v[188:191], v[228:231], v[26:29]
	v_mfma_f32_16x16x32_bf16 v[22:25], v[196:199], v[220:223], v[22:25]
	v_mfma_f32_16x16x32_bf16 v[18:21], v[196:199], v[228:231], v[18:21]
	v_mfma_f32_16x16x32_bf16 v[14:17], v[204:207], v[220:223], v[14:17]
	v_mfma_f32_16x16x32_bf16 v[10:13], v[204:207], v[228:231], v[10:13]
	v_mfma_f32_16x16x32_bf16 v[6:9], v[212:215], v[220:223], v[6:9]
	v_mfma_f32_16x16x32_bf16 v[2:5], v[212:215], v[228:231], v[2:5]
	s_add_i32 s10, s10, 2
	s_add_u32 s8, s8, 0x100
	s_addc_u32 s9, s9, 0
	s_cmp_lt_u32 s10, 12
	s_barrier
	s_cbranch_scc1 .LBB0_449
	s_mov_b64 s[8:9], 0x780
	s_mov_b32 m0, s40
	v_lshl_add_u64 v[142:143], v[142:143], 0, s[8:9]
	ds_read_b128 v[146:149], v175
	ds_read_b128 v[152:155], v175 offset:1024
	ds_read_b128 v[156:159], v175 offset:2048
	ds_read_b128 v[160:163], v175 offset:3072
	ds_read_b128 v[164:167], v176
	ds_read_b128 v[168:171], v176 offset:1024
	ds_read_b128 v[184:187], v177
	ds_read_b128 v[188:191], v177 offset:1024
	ds_read_b128 v[192:195], v178
	ds_read_b128 v[196:199], v178 offset:1024
	ds_read_b128 v[200:203], v179
	ds_read_b128 v[204:207], v179 offset:1024
	global_load_lds_dwordx4 v[142:143], off
	v_lshl_add_u64 v[142:143], v[144:145], 0, s[8:9]
	s_mov_b32 m0, s11
	s_nop 0
	global_load_lds_dwordx4 v[142:143], off
	s_barrier
	s_waitcnt lgkmcnt(0)
	s_waitcnt lgkmcnt(0)
	v_mfma_f32_16x16x32_bf16 v[126:129], v[164:167], v[146:149], v[126:129]
	v_mfma_f32_16x16x32_bf16 v[122:125], v[164:167], v[156:159], v[122:125]
	v_mfma_f32_16x16x32_bf16 v[110:113], v[192:195], v[146:149], v[110:113]
	v_mfma_f32_16x16x32_bf16 v[106:109], v[192:195], v[156:159], v[106:109]
	v_mfma_f32_16x16x32_bf16 v[126:129], v[168:171], v[152:155], v[126:129]
	v_mfma_f32_16x16x32_bf16 v[122:125], v[168:171], v[160:163], v[122:125]
	v_mfma_f32_16x16x32_bf16 v[118:121], v[184:187], v[146:149], v[118:121]
	v_mfma_f32_16x16x32_bf16 v[114:117], v[184:187], v[156:159], v[114:117]
	v_mfma_f32_16x16x32_bf16 v[110:113], v[196:199], v[152:155], v[110:113]
	v_mfma_f32_16x16x32_bf16 v[106:109], v[196:199], v[160:163], v[106:109]
	v_mfma_f32_16x16x32_bf16 v[102:105], v[200:203], v[146:149], v[102:105]
	v_mfma_f32_16x16x32_bf16 v[98:101], v[200:203], v[156:159], v[98:101]
	v_mfma_f32_16x16x32_bf16 v[142:145], v[188:191], v[152:155], v[118:121]
	v_mfma_f32_16x16x32_bf16 v[208:211], v[188:191], v[160:163], v[114:117]
	v_mfma_f32_16x16x32_bf16 v[212:215], v[204:207], v[152:155], v[102:105]
	v_mfma_f32_16x16x32_bf16 v[216:219], v[204:207], v[160:163], v[98:101]
	s_barrier
	s_nop 1
	ds_read_b128 v[98:101], v180
	ds_read_b128 v[102:105], v180 offset:1024
	ds_read_b128 v[114:117], v180 offset:2048
	ds_read_b128 v[118:121], v180 offset:3072
	s_barrier
	s_waitcnt lgkmcnt(0)
	s_waitcnt lgkmcnt(0)
	v_mfma_f32_16x16x32_bf16 v[94:97], v[164:167], v[98:101], v[94:97]
	v_mfma_f32_16x16x32_bf16 v[90:93], v[164:167], v[114:117], v[90:93]
	v_mfma_f32_16x16x32_bf16 v[78:81], v[192:195], v[98:101], v[78:81]
	v_mfma_f32_16x16x32_bf16 v[74:77], v[192:195], v[114:117], v[74:77]
	v_mfma_f32_16x16x32_bf16 v[94:97], v[168:171], v[102:105], v[94:97]
	v_mfma_f32_16x16x32_bf16 v[90:93], v[168:171], v[118:121], v[90:93]
	v_mfma_f32_16x16x32_bf16 v[86:89], v[184:187], v[98:101], v[86:89]
	v_mfma_f32_16x16x32_bf16 v[82:85], v[184:187], v[114:117], v[82:85]
	v_mfma_f32_16x16x32_bf16 v[78:81], v[196:199], v[102:105], v[78:81]
	v_mfma_f32_16x16x32_bf16 v[74:77], v[196:199], v[118:121], v[74:77]
	v_mfma_f32_16x16x32_bf16 v[70:73], v[200:203], v[98:101], v[70:73]
	v_mfma_f32_16x16x32_bf16 v[66:69], v[200:203], v[114:117], v[66:69]
	v_mfma_f32_16x16x32_bf16 v[164:167], v[188:191], v[102:105], v[86:89]
	v_mfma_f32_16x16x32_bf16 v[168:171], v[188:191], v[118:121], v[82:85]
	v_mfma_f32_16x16x32_bf16 v[184:187], v[204:207], v[102:105], v[70:73]
	v_mfma_f32_16x16x32_bf16 v[188:191], v[204:207], v[118:121], v[66:69]
	s_barrier
; #define LDA(dst, b, h) _Pragma("unroll") for (int m = 0; m < 4; ++m) _Pragma("unroll") for (int k = 0; k < 2; ++k) \
;     dst[m][k] = *reinterpret_cast<const bf16x8*>((char*)SA(b, h) + lds_byte(wr * 64 + m * 16 + fr, k * 32 + fq * 8))
; #define LDB(dst, b, h) _Pragma("unroll") for (int n = 0; n < 2; ++n) _Pragma("unroll") for (int k = 0; k < 2; ++k) \
;     dst[n][k] = *reinterpret_cast<const bf16x8*>((char*)SB(b, h) + lds_byte(wc * 32 + n * 16 + fr, k * 32 + fq * 8))
; #define MMA(ai, bj, At_, Bt_) do { __builtin_amdgcn_s_setprio(1); \
;     _Pragma("unroll") for (int m = 0; m < 4; ++m) _Pragma("unroll") for (int n = 0; n < 2; ++n) _Pragma("unroll") for (int k = 0; k < 2; ++k) \
;       acc[ai][bj][m][n] = __builtin_amdgcn_mfma_f32_16x16x32_bf16(At_[m][k], Bt_[n][k], acc[ai][bj][m][n], 0, 0, 0); \
;     __builtin_amdgcn_s_setprio(0); } while (0)
; #define WAIT_V(n) asm volatile("s_waitcnt vmcnt(" #n ")" ::: "memory")
; #define WAIT_L(n) asm volatile("s_waitcnt lgkmcnt(" #n ")" ::: "memory")
; #define BAR __builtin_amdgcn_s_barrier()
; template <class Epi> ...
;     ...
;     LDA(At, 0, 1); WAIT_V(4); BAR; WAIT_L(0); MMA(1, 0, At, B0); MMA(1, 1, At, B1); BAR; }
;   { LDB(B0, 1, 0); LDA(At, 1, 0); WAIT_V(2); BAR; WAIT_L(0); MMA(0, 0, At, B0); BAR;
;     LDB(B1, 1, 1); WAIT_V(0); BAR; WAIT_L(0); MMA(0, 1, At, B1); BAR;
;     LDA(At, 1, 1); BAR; WAIT_L(0); MMA(1, 0, At, B0); MMA(1, 1, At, B1); BAR; }
	s_nop 1
	ds_read_b128 v[66:69], v176 offset:16384
	ds_read_b128 v[70:73], v176 offset:17408
	ds_read_b128 v[82:85], v177 offset:16384
	ds_read_b128 v[86:89], v177 offset:17408
	ds_read_b128 v[192:195], v178 offset:16384
	ds_read_b128 v[196:199], v178 offset:17408
	ds_read_b128 v[200:203], v179 offset:16384
	ds_read_b128 v[204:207], v179 offset:17408
	s_waitcnt vmcnt(4)
	s_barrier
	s_waitcnt lgkmcnt(0)
	s_waitcnt lgkmcnt(0)
	v_mfma_f32_16x16x32_bf16 v[62:65], v[66:69], v[146:149], v[62:65]
	v_mfma_f32_16x16x32_bf16 v[58:61], v[66:69], v[156:159], v[58:61]
	v_mfma_f32_16x16x32_bf16 v[46:49], v[192:195], v[146:149], v[46:49]
	v_mfma_f32_16x16x32_bf16 v[42:45], v[192:195], v[156:159], v[42:45]
	v_mfma_f32_16x16x32_bf16 v[62:65], v[70:73], v[152:155], v[62:65]
	v_mfma_f32_16x16x32_bf16 v[58:61], v[70:73], v[160:163], v[58:61]
	v_mfma_f32_16x16x32_bf16 v[54:57], v[82:85], v[146:149], v[54:57]
	v_mfma_f32_16x16x32_bf16 v[50:53], v[82:85], v[156:159], v[50:53]
	v_mfma_f32_16x16x32_bf16 v[46:49], v[196:199], v[152:155], v[46:49]
	v_mfma_f32_16x16x32_bf16 v[42:45], v[196:199], v[160:163], v[42:45]
	v_mfma_f32_16x16x32_bf16 v[38:41], v[200:203], v[146:149], v[38:41]
	v_mfma_f32_16x16x32_bf16 v[34:37], v[200:203], v[156:159], v[34:37]
	v_mfma_f32_16x16x32_bf16 v[220:223], v[86:89], v[152:155], v[54:57]
	v_mfma_f32_16x16x32_bf16 v[224:227], v[86:89], v[160:163], v[50:53]
	v_mfma_f32_16x16x32_bf16 v[146:149], v[204:207], v[152:155], v[38:41]
	v_mfma_f32_16x16x32_bf16 v[152:155], v[204:207], v[160:163], v[34:37]
	v_mfma_f32_16x16x32_bf16 v[30:33], v[66:69], v[98:101], v[30:33]
	v_mfma_f32_16x16x32_bf16 v[26:29], v[66:69], v[114:117], v[26:29]
	v_mfma_f32_16x16x32_bf16 v[14:17], v[192:195], v[98:101], v[14:17]
	v_mfma_f32_16x16x32_bf16 v[10:13], v[192:195], v[114:117], v[10:13]
	v_mfma_f32_16x16x32_bf16 v[30:33], v[70:73], v[102:105], v[30:33]
	v_mfma_f32_16x16x32_bf16 v[26:29], v[70:73], v[118:121], v[26:29]
	v_mfma_f32_16x16x32_bf16 v[22:25], v[82:85], v[98:101], v[22:25]
	v_mfma_f32_16x16x32_bf16 v[18:21], v[82:85], v[114:117], v[18:21]
	v_mfma_f32_16x16x32_bf16 v[14:17], v[196:199], v[102:105], v[14:17]
	v_mfma_f32_16x16x32_bf16 v[10:13], v[196:199], v[118:121], v[10:13]
	v_mfma_f32_16x16x32_bf16 v[6:9], v[200:203], v[98:101], v[6:9]
	v_mfma_f32_16x16x32_bf16 v[2:5], v[200:203], v[114:117], v[2:5]
	v_mfma_f32_16x16x32_bf16 v[156:159], v[86:89], v[102:105], v[22:25]
	v_mfma_f32_16x16x32_bf16 v[160:163], v[86:89], v[118:121], v[18:21]
	v_mfma_f32_16x16x32_bf16 v[192:195], v[204:207], v[102:105], v[6:9]
	v_mfma_f32_16x16x32_bf16 v[196:199], v[204:207], v[118:121], v[2:5]
	s_barrier
	s_nop 1
	ds_read_b128 v[2:5], v181
	ds_read_b128 v[6:9], v181 offset:1024
	ds_read_b128 v[200:203], v181 offset:2048
	ds_read_b128 v[204:207], v181 offset:3072
	ds_read_b128 v[18:21], v176 offset:32768
	ds_read_b128 v[22:25], v176 offset:33792
	ds_read_b128 v[34:37], v177 offset:32768
	ds_read_b128 v[38:41], v177 offset:33792
	ds_read_b128 v[50:53], v178 offset:32768
	ds_read_b128 v[54:57], v178 offset:33792
	ds_read_b128 v[228:231], v179 offset:32768
	ds_read_b128 v[236:239], v179 offset:33792
	s_waitcnt vmcnt(2)
	s_barrier
	s_waitcnt lgkmcnt(0)
	s_waitcnt lgkmcnt(0)
	v_mfma_f32_16x16x32_bf16 v[66:69], v[18:21], v[2:5], v[126:129]
	v_mfma_f32_16x16x32_bf16 v[118:121], v[22:25], v[6:9], v[66:69]
	v_mfma_f32_16x16x32_bf16 v[66:69], v[18:21], v[200:203], v[122:125]
	v_mfma_f32_16x16x32_bf16 v[114:117], v[22:25], v[204:207], v[66:69]
	v_mfma_f32_16x16x32_bf16 v[66:69], v[34:37], v[2:5], v[142:145]
	v_mfma_f32_16x16x32_bf16 v[102:105], v[38:41], v[6:9], v[66:69]
	v_mfma_f32_16x16x32_bf16 v[66:69], v[34:37], v[200:203], v[208:211]
	v_mfma_f32_16x16x32_bf16 v[98:101], v[38:41], v[204:207], v[66:69]
	v_mfma_f32_16x16x32_bf16 v[66:69], v[50:53], v[2:5], v[110:113]
	v_mfma_f32_16x16x32_bf16 v[86:89], v[54:57], v[6:9], v[66:69]
	v_mfma_f32_16x16x32_bf16 v[66:69], v[50:53], v[200:203], v[106:109]
	v_mfma_f32_16x16x32_bf16 v[82:85], v[54:57], v[204:207], v[66:69]
	v_mfma_f32_16x16x32_bf16 v[66:69], v[228:231], v[2:5], v[212:215]
	v_mfma_f32_16x16x32_bf16 v[70:73], v[236:239], v[6:9], v[66:69]
	v_mfma_f32_16x16x32_bf16 v[66:69], v[228:231], v[200:203], v[216:219]
	v_mfma_f32_16x16x32_bf16 v[66:69], v[236:239], v[204:207], v[66:69]
	s_barrier
; #define LDA(dst, b, h) _Pragma("unroll") for (int m = 0; m < 4; ++m) _Pragma("unroll") for (int k = 0; k < 2; ++k) \
;     dst[m][k] = *reinterpret_cast<const bf16x8*>((char*)SA(b, h) + lds_byte(wr * 64 + m * 16 + fr, k * 32 + fq * 8))
; #define LDB(dst, b, h) _Pragma("unroll") for (int n = 0; n < 2; ++n) _Pragma("unroll") for (int k = 0; k < 2; ++k) \
;     dst[n][k] = *reinterpret_cast<const bf16x8*>((char*)SB(b, h) + lds_byte(wc * 32 + n * 16 + fr, k * 32 + fq * 8))
; #define MMA(ai, bj, At_, Bt_) do { __builtin_amdgcn_s_setprio(1); \
;     _Pragma("unroll") for (int m = 0; m < 4; ++m) _Pragma("unroll") for (int n = 0; n < 2; ++n) _Pragma("unroll") for (int k = 0; k < 2; ++k) \
;       acc[ai][bj][m][n] = __builtin_amdgcn_mfma_f32_16x16x32_bf16(At_[m][k], Bt_[n][k], acc[ai][bj][m][n], 0, 0, 0); \
;     __builtin_amdgcn_s_setprio(0); } while (0)
; #define WAIT_V(n) asm volatile("s_waitcnt vmcnt(" #n ")" ::: "memory")
; #define WAIT_L(n) asm volatile("s_waitcnt lgkmcnt(" #n ")" ::: "memory")
; #define BAR __builtin_amdgcn_s_barrier()
; template <class Epi> ...
;     ...
;   { LDB(B0, 1, 0); LDA(At, 1, 0); WAIT_V(2); BAR; WAIT_L(0); MMA(0, 0, At, B0); BAR;
;     LDB(B1, 1, 1); WAIT_V(0); BAR; WAIT_L(0); MMA(0, 1, At, B1); BAR;
;     LDA(At, 1, 1); BAR; WAIT_L(0); MMA(1, 0, At, B0); MMA(1, 1, At, B1); BAR; }
;   if (wr == 0) BAR;
	ds_read_b128 v[142:145], v182
	ds_read_b128 v[208:211], v182 offset:1024
	ds_read_b128 v[212:215], v182 offset:2048
	ds_read_b128 v[216:219], v182 offset:3072
	s_waitcnt vmcnt(0)
	s_barrier
	s_waitcnt lgkmcnt(0)
	s_waitcnt lgkmcnt(0)
	v_mfma_f32_16x16x32_bf16 v[94:97], v[18:21], v[142:145], v[94:97]
	v_mfma_f32_16x16x32_bf16 v[18:21], v[18:21], v[212:215], v[90:93]
	v_mfma_f32_16x16x32_bf16 v[122:125], v[22:25], v[216:219], v[18:21]
	v_mfma_f32_16x16x32_bf16 v[18:21], v[34:37], v[142:145], v[164:167]
	v_mfma_f32_16x16x32_bf16 v[110:113], v[38:41], v[208:211], v[18:21]
	v_mfma_f32_16x16x32_bf16 v[18:21], v[34:37], v[212:215], v[168:171]
	v_mfma_f32_16x16x32_bf16 v[106:109], v[38:41], v[216:219], v[18:21]
	v_mfma_f32_16x16x32_bf16 v[18:21], v[50:53], v[142:145], v[78:81]
	v_mfma_f32_16x16x32_bf16 v[126:129], v[22:25], v[208:211], v[94:97]
	v_mfma_f32_16x16x32_bf16 v[94:97], v[54:57], v[208:211], v[18:21]
	v_mfma_f32_16x16x32_bf16 v[18:21], v[50:53], v[212:215], v[74:77]
	v_mfma_f32_16x16x32_bf16 v[90:93], v[54:57], v[216:219], v[18:21]
	v_mfma_f32_16x16x32_bf16 v[18:21], v[228:231], v[142:145], v[184:187]
	v_mfma_f32_16x16x32_bf16 v[78:81], v[236:239], v[208:211], v[18:21]
	v_mfma_f32_16x16x32_bf16 v[18:21], v[228:231], v[212:215], v[188:191]
	v_mfma_f32_16x16x32_bf16 v[74:77], v[236:239], v[216:219], v[18:21]
	s_barrier
	ds_read_b128 v[164:167], v176 offset:49152
	ds_read_b128 v[168:171], v176 offset:50176
	ds_read_b128 v[184:187], v177 offset:49152
	ds_read_b128 v[188:191], v177 offset:50176
	ds_read_b128 v[228:231], v178 offset:49152
	ds_read_b128 v[236:239], v178 offset:50176
	ds_read_b128 v[240:243], v179 offset:49152
	ds_read_b128 v[244:247], v179 offset:50176
	s_barrier
	s_waitcnt lgkmcnt(0)
	s_waitcnt lgkmcnt(0)
	v_mfma_f32_16x16x32_bf16 v[18:21], v[164:167], v[2:5], v[62:65]
	v_mfma_f32_16x16x32_bf16 v[54:57], v[168:171], v[6:9], v[18:21]
	v_mfma_f32_16x16x32_bf16 v[18:21], v[164:167], v[200:203], v[58:61]
	v_mfma_f32_16x16x32_bf16 v[50:53], v[168:171], v[204:207], v[18:21]
	v_mfma_f32_16x16x32_bf16 v[18:21], v[184:187], v[2:5], v[220:223]
	v_mfma_f32_16x16x32_bf16 v[38:41], v[188:191], v[6:9], v[18:21]
	v_mfma_f32_16x16x32_bf16 v[18:21], v[184:187], v[200:203], v[224:227]
	v_mfma_f32_16x16x32_bf16 v[34:37], v[188:191], v[204:207], v[18:21]
	v_mfma_f32_16x16x32_bf16 v[18:21], v[228:231], v[2:5], v[46:49]
	v_mfma_f32_16x16x32_bf16 v[2:5], v[240:243], v[2:5], v[146:149]
	v_mfma_f32_16x16x32_bf16 v[22:25], v[236:239], v[6:9], v[18:21]
	v_mfma_f32_16x16x32_bf16 v[18:21], v[228:231], v[200:203], v[42:45]
	v_mfma_f32_16x16x32_bf16 v[6:9], v[244:247], v[6:9], v[2:5]
	v_mfma_f32_16x16x32_bf16 v[2:5], v[240:243], v[200:203], v[152:155]
	v_mfma_f32_16x16x32_bf16 v[18:21], v[236:239], v[204:207], v[18:21]
	v_mfma_f32_16x16x32_bf16 v[2:5], v[244:247], v[204:207], v[2:5]
	v_mfma_f32_16x16x32_bf16 v[26:29], v[164:167], v[212:215], v[26:29]
	v_mfma_f32_16x16x32_bf16 v[58:61], v[168:171], v[216:219], v[26:29]
	v_mfma_f32_16x16x32_bf16 v[26:29], v[184:187], v[142:145], v[156:159]
	v_mfma_f32_16x16x32_bf16 v[46:49], v[188:191], v[208:211], v[26:29]
	v_mfma_f32_16x16x32_bf16 v[26:29], v[184:187], v[212:215], v[160:163]
	v_mfma_f32_16x16x32_bf16 v[10:13], v[228:231], v[212:215], v[10:13]
	v_mfma_f32_16x16x32_bf16 v[30:33], v[164:167], v[142:145], v[30:33]
	v_mfma_f32_16x16x32_bf16 v[42:45], v[188:191], v[216:219], v[26:29]
	v_mfma_f32_16x16x32_bf16 v[14:17], v[228:231], v[142:145], v[14:17]
	v_mfma_f32_16x16x32_bf16 v[26:29], v[236:239], v[216:219], v[10:13]
	v_mfma_f32_16x16x32_bf16 v[10:13], v[240:243], v[142:145], v[192:195]
	v_mfma_f32_16x16x32_bf16 v[62:65], v[168:171], v[208:211], v[30:33]
	v_mfma_f32_16x16x32_bf16 v[30:33], v[236:239], v[208:211], v[14:17]
	v_mfma_f32_16x16x32_bf16 v[14:17], v[244:247], v[208:211], v[10:13]
	v_mfma_f32_16x16x32_bf16 v[10:13], v[240:243], v[212:215], v[196:199]
	v_mfma_f32_16x16x32_bf16 v[10:13], v[244:247], v[216:219], v[10:13]
	s_barrier
	s_and_saveexec_b64 s[8:9], s[6:7]
	s_cbranch_execz .LBB0_452
	s_barrier

; #define GSYNC() xcd_barrier(p.bar)
; #define GSYNC() grid.sync()
; __global__ void __launch_bounds__(512, 2) mega_kernel(Params p) {
;     ...
;   for (int ph = p.ph_lo; ph < p.ph_hi; ++ph) {
;     const bool worked = run_phase(ph, 0);
;     if (worked && ph + 1 < p.ph_hi) GSYNC();
;   }
.LBB0_1591:
	s_setprio 0
	s_add_i32 s64, s64, 1
	s_cmp_ge_i32 s64, s65
	s_cselect_b64 s[4:5], -1, 0
	s_cmp_lt_i32 s64, s65
	s_cselect_b64 s[6:7], -1, 0
	s_and_b64 s[6:7], s[12:13], s[6:7]
	v_readlane_b32 s8, v255, 36
	s_andn2_b64 vcc, exec, s[6:7]
	v_readlane_b32 s9, v255, 37
	s_cbranch_vccz .LBB0_1592
	s_getpc_b64 s[98:99]
